# one static priority raise for the trailing wave half over each tile's K loop, per-segment s_setprio toggles removed (all four plain GEMM loops, on top of v40)
# speedup vs baseline: 1.0145x; 1.0145x over previous
; #define PG8_STAGE(bufoff, gbase, voff) do { _Pragma("unroll") for (int _i = 0; _i < 2; ++_i) \
;         __builtin_amdgcn_global_load_lds((const unsigned*)((const char*)(gbase) + (voff)[_i]), (PG8_LAS unsigned*)(lds + (bufoff) + ldsw + _i * 8192), 16, 0, 0); } while (0)
; #define PG8_LDA(dst, b, h) do { _Pragma("unroll") for (int m = 0; m < 4; ++m) _Pragma("unroll") for (int k = 0; k < 2; ++k) dst[m][k] = *(const PG8_LAS bf16x8*)(lds + PG8_SA(b, h) + aoff + m * 2048 + k * 1024); } while (0)
; #define PG8_LDB(dst, b, h) do { _Pragma("unroll") for (int n = 0; n < 2; ++n) _Pragma("unroll") for (int k = 0; k < 2; ++k) dst[n][k] = *(const PG8_LAS bf16x8*)(lds + PG8_SB(b, h) + boff + n * 2048 + k * 1024); } while (0)
; #define PG8_MMA(ai, bj, At, Bt) do { __builtin_amdgcn_s_setprio(1); _Pragma("unroll") for (int m = 0; m < 4; ++m) _Pragma("unroll") for (int n = 0; n < 2; ++n) _Pragma("unroll") for (int k = 0; k < 2; ++k) \
;         acc[ai][bj][m][n] = __builtin_amdgcn_mfma_f32_16x16x32_bf16(Bt[n][k], At[m][k], acc[ai][bj][m][n], 0, 0, 0); __builtin_amdgcn_s_setprio(0); } while (0)
; #define PG8_WAIT_V(n) asm volatile("s_waitcnt vmcnt(" #n ")" ::: "memory")
; #define PG8_WAIT_L(n) asm volatile("s_waitcnt lgkmcnt(" #n ")" ::: "memory")
; #define PG8_BAR __builtin_amdgcn_s_barrier()
; #define PG8_SCHED __builtin_amdgcn_sched_barrier(0)
; template <class Epi, class Sched, bool ALIGN_EPI = false, bool SP2 = false>
; __device__ __forceinline__ void gemm_phase(PG8_LAS unsigned char* lds, const Gemm g, const Sched& S, const Epi& E) {
;     ...
;             PG8_LDB(B0, 0, 0); PG8_LDB(B1, 0, 1); PG8_SCHED; PG8_LDA(At, 0, 0); PG8_STAGE(PG8_SA(1, 1), a1 + hstep, voffA);
;             PG8_WAIT_V(8); PG8_WAIT_L(0); PG8_BAR; PG8_MMA(0, 0, At, B0); PG8_MMA(0, 1, At, B1); PG8_BAR; PG8_SCHED;
;             PG8_LDA(At, 0, 1); PG8_STAGE(PG8_SB(0, 0), b2, voffB); PG8_STAGE(PG8_SB(0, 1), b2 + hstep, voffB); PG8_STAGE(PG8_SA(0, 0), a2, voffA);
;             PG8_WAIT_V(8); PG8_WAIT_L(0); PG8_BAR; PG8_MMA(1, 0, At, B0); PG8_MMA(1, 1, At, B1); PG8_BAR; PG8_SCHED;
.LBB0_130:
	s_ashr_i32 s41, s40, 31
	s_lshl_b64 s[42:43], s[40:41], 20
	s_add_u32 s42, s35, s42
	s_addc_u32 s43, s54, s43
	s_and_b64 s[44:45], s[6:7], exec
	s_cselect_b32 s33, s43, s49
	s_cselect_b32 s41, s42, s48
	s_ashr_i32 s39, s38, 31
	s_lshl_b64 s[44:45], s[38:39], 20
	s_add_u32 s44, s55, s44
	s_addc_u32 s45, s56, s45
	s_and_b64 s[52:53], s[6:7], exec
	s_cselect_b32 s39, s45, s51
	s_cselect_b32 s47, s44, s50
	s_add_u32 s48, s48, 0x80080
	s_addc_u32 s49, s49, 0
	s_add_u32 s71, s50, 0x100
	v_mov_b32_e32 v28, 0
	s_addc_u32 s72, s51, 0
	s_mov_b32 s73, -2
	s_cmp_lg_u64 s[14:15], 0
	s_cbranch_scc1 .Lsp0_lead
	s_setprio 1
.Lsp0_lead:
	ds_read_b128 v[148:151], v156
	ds_read_b128 v[162:165], v157
	ds_read_b128 v[166:169], v156 offset:2048
	ds_read_b128 v[170:173], v157 offset:2048
	ds_read_b128 v[174:177], v156 offset:16384
	ds_read_b128 v[178:181], v157 offset:16384
	ds_read_b128 v[182:185], v156 offset:18432
	ds_read_b128 v[186:189], v157 offset:18432
	s_add_u32 s36, s48, 0xfff80080
	s_addc_u32 s37, s49, -1
	s_cmp_eq_u32 s73, 28
	s_cselect_b32 s53, s33, s37
	s_cselect_b32 s52, s41, s36
	s_cselect_b32 s51, s39, s72
	s_cselect_b32 s50, s47, s71
	v_lshl_add_u64 v[152:153], s[48:49], 0, v[138:139]
	s_add_i32 m0, s60, 0xc000
	ds_read_b128 v[190:193], v158
	ds_read_b128 v[194:197], v242
	ds_read_b128 v[198:201], v158 offset:2048
	ds_read_b128 v[202:205], v242 offset:2048
	ds_read_b128 v[206:209], v158 offset:4096
	ds_read_b128 v[210:213], v242 offset:4096
	ds_read_b128 v[214:217], v158 offset:6144
	ds_read_b128 v[218:221], v242 offset:6144
	global_load_lds_dwordx4 v[152:153], off
	v_lshl_add_u64 v[152:153], s[48:49], 0, v[140:141]
	s_add_i32 m0, s60, 0xe000
	s_nop 0
	global_load_lds_dwordx4 v[152:153], off
	s_waitcnt vmcnt(8)
	s_waitcnt lgkmcnt(0)
	s_barrier
	s_waitcnt lgkmcnt(0)
	v_mfma_f32_16x16x32_bf16 v[76:79], v[148:151], v[190:193], 0
	v_mfma_f32_16x16x32_bf16 v[72:75], v[166:169], v[190:193], 0
	v_mfma_f32_16x16x32_bf16 v[68:71], v[148:151], v[198:201], 0
	v_mfma_f32_16x16x32_bf16 v[64:67], v[166:169], v[198:201], 0
	v_mfma_f32_16x16x32_bf16 v[60:63], v[148:151], v[206:209], 0
	v_mfma_f32_16x16x32_bf16 v[52:55], v[166:169], v[206:209], 0
	v_mfma_f32_16x16x32_bf16 v[44:47], v[148:151], v[214:217], 0
	v_mfma_f32_16x16x32_bf16 v[40:43], v[166:169], v[214:217], 0
	v_mfma_f32_16x16x32_bf16 v[76:79], v[162:165], v[194:197], v[76:79]
	v_mfma_f32_16x16x32_bf16 v[72:75], v[170:173], v[194:197], v[72:75]
	v_mfma_f32_16x16x32_bf16 v[68:71], v[162:165], v[202:205], v[68:71]
	v_mfma_f32_16x16x32_bf16 v[64:67], v[170:173], v[202:205], v[64:67]
	v_mfma_f32_16x16x32_bf16 v[60:63], v[162:165], v[210:213], v[60:63]
	v_mfma_f32_16x16x32_bf16 v[52:55], v[170:173], v[210:213], v[52:55]
	v_mfma_f32_16x16x32_bf16 v[44:47], v[162:165], v[218:221], v[44:47]
	v_mfma_f32_16x16x32_bf16 v[40:43], v[170:173], v[218:221], v[40:43]
	v_mfma_f32_16x16x32_bf16 v[124:127], v[174:177], v[190:193], 0
	v_mfma_f32_16x16x32_bf16 v[120:123], v[182:185], v[190:193], 0
	v_mfma_f32_16x16x32_bf16 v[116:119], v[174:177], v[198:201], 0
	v_mfma_f32_16x16x32_bf16 v[112:115], v[182:185], v[198:201], 0
	v_mfma_f32_16x16x32_bf16 v[108:111], v[174:177], v[206:209], 0
	v_mfma_f32_16x16x32_bf16 v[104:107], v[182:185], v[206:209], 0
	v_mfma_f32_16x16x32_bf16 v[100:103], v[174:177], v[214:217], 0
	v_mfma_f32_16x16x32_bf16 v[96:99], v[182:185], v[214:217], 0
	v_mfma_f32_16x16x32_bf16 v[124:127], v[178:181], v[194:197], v[124:127]
	v_mfma_f32_16x16x32_bf16 v[120:123], v[186:189], v[194:197], v[120:123]
	v_mfma_f32_16x16x32_bf16 v[116:119], v[178:181], v[202:205], v[116:119]
	v_mfma_f32_16x16x32_bf16 v[112:115], v[186:189], v[202:205], v[112:115]
	v_mfma_f32_16x16x32_bf16 v[108:111], v[178:181], v[210:213], v[108:111]
	v_mfma_f32_16x16x32_bf16 v[104:107], v[186:189], v[210:213], v[104:107]
	v_mfma_f32_16x16x32_bf16 v[100:103], v[178:181], v[218:221], v[100:103]
	v_mfma_f32_16x16x32_bf16 v[96:99], v[186:189], v[218:221], v[96:99]
	s_barrier
	s_add_i32 s36, s68, s57
	v_lshl_add_u64 v[152:153], s[50:51], 0, v[132:133]
	s_mov_b32 m0, s36
	ds_read_b128 v[190:193], v158 offset:16384
	ds_read_b128 v[194:197], v242 offset:16384
	ds_read_b128 v[198:201], v158 offset:18432
	ds_read_b128 v[202:205], v242 offset:18432
	ds_read_b128 v[206:209], v158 offset:20480
	ds_read_b128 v[210:213], v242 offset:20480
	ds_read_b128 v[214:217], v158 offset:22528
	ds_read_b128 v[218:221], v242 offset:22528
	global_load_lds_dwordx4 v[152:153], off
	s_add_i32 m0, s36, 0x2000
	s_add_u32 s74, s50, 0x80000
	v_lshl_add_u64 v[222:223], s[50:51], 0, v[128:129]
	s_addc_u32 s75, s51, 0
	s_add_i32 s36, s69, s57
	global_load_lds_dwordx4 v[222:223], off
	v_lshl_add_u64 v[224:225], s[74:75], 0, v[132:133]
	s_mov_b32 m0, s36
	v_lshl_add_u64 v[226:227], s[52:53], 0, v[130:131]
	global_load_lds_dwordx4 v[224:225], off
	v_lshl_add_u64 v[224:225], s[74:75], 0, v[128:129]
	s_add_i32 m0, s36, 0x2000
	s_nop 0
	global_load_lds_dwordx4 v[224:225], off
	v_lshl_add_u64 v[224:225], s[52:53], 0, v[134:135]
	s_mov_b32 m0, s60
	s_nop 0
	global_load_lds_dwordx4 v[224:225], off
	s_mov_b32 m0, s61
	s_nop 0
	global_load_lds_dwordx4 v[226:227], off
	s_waitcnt vmcnt(8)
	s_waitcnt lgkmcnt(0)
	s_barrier
; #define PG8_STAGE(bufoff, gbase, voff) do { _Pragma("unroll") for (int _i = 0; _i < 2; ++_i) \
;         __builtin_amdgcn_global_load_lds((const unsigned*)((const char*)(gbase) + (voff)[_i]), (PG8_LAS unsigned*)(lds + (bufoff) + ldsw + _i * 8192), 16, 0, 0); } while (0)
; #define PG8_LDA(dst, b, h) do { _Pragma("unroll") for (int m = 0; m < 4; ++m) _Pragma("unroll") for (int k = 0; k < 2; ++k) dst[m][k] = *(const PG8_LAS bf16x8*)(lds + PG8_SA(b, h) + aoff + m * 2048 + k * 1024); } while (0)
; #define PG8_LDB(dst, b, h) do { _Pragma("unroll") for (int n = 0; n < 2; ++n) _Pragma("unroll") for (int k = 0; k < 2; ++k) dst[n][k] = *(const PG8_LAS bf16x8*)(lds + PG8_SB(b, h) + boff + n * 2048 + k * 1024); } while (0)
; #define PG8_MMA(ai, bj, At, Bt) do { __builtin_amdgcn_s_setprio(1); _Pragma("unroll") for (int m = 0; m < 4; ++m) _Pragma("unroll") for (int n = 0; n < 2; ++n) _Pragma("unroll") for (int k = 0; k < 2; ++k) \
;         acc[ai][bj][m][n] = __builtin_amdgcn_mfma_f32_16x16x32_bf16(Bt[n][k], At[m][k], acc[ai][bj][m][n], 0, 0, 0); __builtin_amdgcn_s_setprio(0); } while (0)
; #define PG8_WAIT_V(n) asm volatile("s_waitcnt vmcnt(" #n ")" ::: "memory")
; #define PG8_WAIT_L(n) asm volatile("s_waitcnt lgkmcnt(" #n ")" ::: "memory")
; #define PG8_BAR __builtin_amdgcn_s_barrier()
; #define PG8_SCHED __builtin_amdgcn_sched_barrier(0)
; template <class Epi, class Sched, bool ALIGN_EPI = false, bool SP2 = false>
; __device__ __forceinline__ void gemm_phase(PG8_LAS unsigned char* lds, const Gemm g, const Sched& S, const Epi& E) {
;     ...
;             PG8_WAIT_V(8); PG8_WAIT_L(0); PG8_BAR; PG8_MMA(1, 0, At, B0); PG8_MMA(1, 1, At, B1); PG8_BAR; PG8_SCHED;
;             PG8_LDB(B0, 1, 0); PG8_LDB(B1, 1, 1); PG8_SCHED; PG8_LDA(At, 1, 0); PG8_STAGE(PG8_SA(0, 1), a2 + hstep, voffA);
;             PG8_WAIT_V(8); PG8_WAIT_L(0); PG8_BAR; PG8_MMA(0, 0, At, B0); PG8_MMA(0, 1, At, B1); PG8_BAR; PG8_SCHED;
	s_waitcnt lgkmcnt(0)
	v_mfma_f32_16x16x32_bf16 v[32:35], v[148:151], v[190:193], 0
	v_mfma_f32_16x16x32_bf16 v[24:27], v[166:169], v[190:193], 0
	v_mfma_f32_16x16x32_bf16 v[20:23], v[148:151], v[198:201], 0
	v_mfma_f32_16x16x32_bf16 v[16:19], v[166:169], v[198:201], 0
	v_mfma_f32_16x16x32_bf16 v[12:15], v[148:151], v[206:209], 0
	v_mfma_f32_16x16x32_bf16 v[8:11], v[166:169], v[206:209], 0
	v_mfma_f32_16x16x32_bf16 v[4:7], v[148:151], v[214:217], 0
	v_mfma_f32_16x16x32_bf16 v[0:3], v[166:169], v[214:217], 0
	v_mfma_f32_16x16x32_bf16 v[32:35], v[162:165], v[194:197], v[32:35]
	v_mfma_f32_16x16x32_bf16 v[24:27], v[170:173], v[194:197], v[24:27]
	v_mfma_f32_16x16x32_bf16 v[20:23], v[162:165], v[202:205], v[20:23]
	v_mfma_f32_16x16x32_bf16 v[16:19], v[170:173], v[202:205], v[16:19]
	v_mfma_f32_16x16x32_bf16 v[12:15], v[162:165], v[210:213], v[12:15]
	v_mfma_f32_16x16x32_bf16 v[8:11], v[170:173], v[210:213], v[8:11]
	v_mfma_f32_16x16x32_bf16 v[4:7], v[162:165], v[218:221], v[4:7]
	v_mfma_f32_16x16x32_bf16 v[0:3], v[170:173], v[218:221], v[0:3]
	v_mfma_f32_16x16x32_bf16 v[92:95], v[174:177], v[190:193], 0
	v_mfma_f32_16x16x32_bf16 v[88:91], v[182:185], v[190:193], 0
	v_mfma_f32_16x16x32_bf16 v[84:87], v[174:177], v[198:201], 0
	v_mfma_f32_16x16x32_bf16 v[80:83], v[182:185], v[198:201], 0
	v_mfma_f32_16x16x32_bf16 v[56:59], v[174:177], v[206:209], 0
	v_mfma_f32_16x16x32_bf16 v[48:51], v[182:185], v[206:209], 0
	v_mfma_f32_16x16x32_bf16 v[36:39], v[174:177], v[214:217], 0
	v_mfma_f32_16x16x32_bf16 v[28:31], v[182:185], v[214:217], 0
	v_mfma_f32_16x16x32_bf16 v[92:95], v[178:181], v[194:197], v[92:95]
	v_mfma_f32_16x16x32_bf16 v[88:91], v[186:189], v[194:197], v[88:91]
	v_mfma_f32_16x16x32_bf16 v[84:87], v[178:181], v[202:205], v[84:87]
	v_mfma_f32_16x16x32_bf16 v[80:83], v[186:189], v[202:205], v[80:83]
	v_mfma_f32_16x16x32_bf16 v[56:59], v[178:181], v[210:213], v[56:59]
	v_mfma_f32_16x16x32_bf16 v[48:51], v[186:189], v[210:213], v[48:51]
	v_mfma_f32_16x16x32_bf16 v[36:39], v[178:181], v[218:221], v[36:39]
	v_mfma_f32_16x16x32_bf16 v[28:31], v[186:189], v[218:221], v[28:31]
	s_barrier
	s_add_i32 s36, 0, 0x18000
	v_add_u32_e32 v161, s36, v154
	s_add_i32 s37, 0, 0x1c000
	ds_read_b128 v[148:151], v156 offset:32768
	ds_read_b128 v[162:165], v157 offset:32768
	ds_read_b128 v[166:169], v156 offset:34816
	ds_read_b128 v[170:173], v157 offset:34816
	v_add_u32_e32 v161, s37, v154
	ds_read_b128 v[174:177], v156 offset:49152
	ds_read_b128 v[178:181], v157 offset:49152
	ds_read_b128 v[182:185], v156 offset:51200
	ds_read_b128 v[186:189], v157 offset:51200
	s_add_u32 s52, s52, 0x80000
	s_addc_u32 s53, s53, 0
	s_mov_b32 m0, s62
	v_lshl_add_u64 v[228:229], s[52:53], 0, v[134:135]
	ds_read_b128 v[190:193], v158 offset:32768
	ds_read_b128 v[194:197], v242 offset:32768
	ds_read_b128 v[198:201], v158 offset:34816
	ds_read_b128 v[202:205], v242 offset:34816
	ds_read_b128 v[206:209], v158 offset:36864
	ds_read_b128 v[210:213], v242 offset:36864
	ds_read_b128 v[214:217], v158 offset:38912
	ds_read_b128 v[218:221], v242 offset:38912
	global_load_lds_dwordx4 v[228:229], off
	v_lshl_add_u64 v[228:229], s[52:53], 0, v[130:131]
	s_mov_b32 m0, s63
	s_nop 0
	global_load_lds_dwordx4 v[228:229], off
	s_waitcnt vmcnt(8)
	s_waitcnt lgkmcnt(0)
	s_barrier
	s_waitcnt lgkmcnt(0)
	v_mfma_f32_16x16x32_bf16 v[76:79], v[148:151], v[190:193], v[76:79]
	v_mfma_f32_16x16x32_bf16 v[72:75], v[166:169], v[190:193], v[72:75]
	v_mfma_f32_16x16x32_bf16 v[68:71], v[148:151], v[198:201], v[68:71]
	v_mfma_f32_16x16x32_bf16 v[64:67], v[166:169], v[198:201], v[64:67]
	v_mfma_f32_16x16x32_bf16 v[60:63], v[148:151], v[206:209], v[60:63]
	v_mfma_f32_16x16x32_bf16 v[52:55], v[166:169], v[206:209], v[52:55]
	v_mfma_f32_16x16x32_bf16 v[44:47], v[148:151], v[214:217], v[44:47]
	v_mfma_f32_16x16x32_bf16 v[40:43], v[166:169], v[214:217], v[40:43]
	v_mfma_f32_16x16x32_bf16 v[76:79], v[162:165], v[194:197], v[76:79]
	v_mfma_f32_16x16x32_bf16 v[72:75], v[170:173], v[194:197], v[72:75]
	v_mfma_f32_16x16x32_bf16 v[68:71], v[162:165], v[202:205], v[68:71]
	v_mfma_f32_16x16x32_bf16 v[64:67], v[170:173], v[202:205], v[64:67]
	v_mfma_f32_16x16x32_bf16 v[60:63], v[162:165], v[210:213], v[60:63]
	v_mfma_f32_16x16x32_bf16 v[52:55], v[170:173], v[210:213], v[52:55]
	v_mfma_f32_16x16x32_bf16 v[44:47], v[162:165], v[218:221], v[44:47]
	v_mfma_f32_16x16x32_bf16 v[40:43], v[170:173], v[218:221], v[40:43]
	v_mfma_f32_16x16x32_bf16 v[124:127], v[174:177], v[190:193], v[124:127]
	v_mfma_f32_16x16x32_bf16 v[120:123], v[182:185], v[190:193], v[120:123]
	v_mfma_f32_16x16x32_bf16 v[116:119], v[174:177], v[198:201], v[116:119]
	v_mfma_f32_16x16x32_bf16 v[112:115], v[182:185], v[198:201], v[112:115]
	v_mfma_f32_16x16x32_bf16 v[108:111], v[174:177], v[206:209], v[108:111]
	v_mfma_f32_16x16x32_bf16 v[104:107], v[182:185], v[206:209], v[104:107]
	v_mfma_f32_16x16x32_bf16 v[100:103], v[174:177], v[214:217], v[100:103]
	v_mfma_f32_16x16x32_bf16 v[96:99], v[182:185], v[214:217], v[96:99]
	v_mfma_f32_16x16x32_bf16 v[124:127], v[178:181], v[194:197], v[124:127]
	v_mfma_f32_16x16x32_bf16 v[120:123], v[186:189], v[194:197], v[120:123]
	v_mfma_f32_16x16x32_bf16 v[116:119], v[178:181], v[202:205], v[116:119]
	v_mfma_f32_16x16x32_bf16 v[112:115], v[186:189], v[202:205], v[112:115]
	v_mfma_f32_16x16x32_bf16 v[108:111], v[178:181], v[210:213], v[108:111]
	v_mfma_f32_16x16x32_bf16 v[104:107], v[186:189], v[210:213], v[104:107]
	v_mfma_f32_16x16x32_bf16 v[100:103], v[178:181], v[218:221], v[100:103]
	v_mfma_f32_16x16x32_bf16 v[96:99], v[186:189], v[218:221], v[96:99]
	s_barrier
; #define PG8_STAGE(bufoff, gbase, voff) do { _Pragma("unroll") for (int _i = 0; _i < 2; ++_i) \
;         __builtin_amdgcn_global_load_lds((const unsigned*)((const char*)(gbase) + (voff)[_i]), (PG8_LAS unsigned*)(lds + (bufoff) + ldsw + _i * 8192), 16, 0, 0); } while (0)
; #define PG8_LDA(dst, b, h) do { _Pragma("unroll") for (int m = 0; m < 4; ++m) _Pragma("unroll") for (int k = 0; k < 2; ++k) dst[m][k] = *(const PG8_LAS bf16x8*)(lds + PG8_SA(b, h) + aoff + m * 2048 + k * 1024); } while (0)
; #define PG8_LDB(dst, b, h) do { _Pragma("unroll") for (int n = 0; n < 2; ++n) _Pragma("unroll") for (int k = 0; k < 2; ++k) dst[n][k] = *(const PG8_LAS bf16x8*)(lds + PG8_SB(b, h) + boff + n * 2048 + k * 1024); } while (0)
; #define PG8_MMA(ai, bj, At, Bt) do { __builtin_amdgcn_s_setprio(1); _Pragma("unroll") for (int m = 0; m < 4; ++m) _Pragma("unroll") for (int n = 0; n < 2; ++n) _Pragma("unroll") for (int k = 0; k < 2; ++k) \
;         acc[ai][bj][m][n] = __builtin_amdgcn_mfma_f32_16x16x32_bf16(Bt[n][k], At[m][k], acc[ai][bj][m][n], 0, 0, 0); __builtin_amdgcn_s_setprio(0); } while (0)
; #define PG8_WAIT_V(n) asm volatile("s_waitcnt vmcnt(" #n ")" ::: "memory")
; #define PG8_WAIT_L(n) asm volatile("s_waitcnt lgkmcnt(" #n ")" ::: "memory")
; #define PG8_BAR __builtin_amdgcn_s_barrier()
; #define PG8_SCHED __builtin_amdgcn_sched_barrier(0)
; template <class Epi, class Sched, bool ALIGN_EPI = false, bool SP2 = false>
; __device__ __forceinline__ void gemm_phase(PG8_LAS unsigned char* lds, const Gemm g, const Sched& S, const Epi& E) {
;     ...
;             PG8_LDB(B0, 0, 0); PG8_LDB(B1, 0, 1); PG8_SCHED; PG8_LDA(At, 0, 0); PG8_STAGE(PG8_SA(1, 1), a1 + hstep, voffA);
;             PG8_WAIT_V(8); PG8_WAIT_L(0); PG8_BAR; PG8_MMA(0, 0, At, B0); PG8_MMA(0, 1, At, B1); PG8_BAR; PG8_SCHED;
;     ...
;             PG8_LDA(At, 1, 1); PG8_STAGE(PG8_SB(1, 0), b3, voffB); PG8_STAGE(PG8_SB(1, 1), b3 + hstep, voffB); PG8_STAGE(PG8_SA(1, 0), a3, voffA);
;             PG8_WAIT_V(8); PG8_WAIT_L(0); PG8_BAR; PG8_MMA(1, 0, At, B0); PG8_MMA(1, 1, At, B1); PG8_BAR; PG8_SCHED;
	s_add_i32 s36, s36, s57
	v_lshl_add_u64 v[152:153], v[152:153], 0, s[12:13]
	s_mov_b32 m0, s36
	ds_read_b128 v[190:193], v158 offset:49152
	ds_read_b128 v[194:197], v242 offset:49152
	ds_read_b128 v[198:201], v158 offset:51200
	ds_read_b128 v[202:205], v242 offset:51200
	ds_read_b128 v[206:209], v158 offset:53248
	ds_read_b128 v[210:213], v242 offset:53248
	ds_read_b128 v[214:217], v158 offset:55296
	ds_read_b128 v[218:221], v242 offset:55296
	global_load_lds_dwordx4 v[152:153], off
	s_add_i32 m0, s36, 0x2000
	s_add_u32 s50, s50, 0x80080
	v_lshl_add_u64 v[152:153], v[222:223], 0, s[12:13]
	s_addc_u32 s51, s51, 0
	s_add_i32 s36, s37, s57
	global_load_lds_dwordx4 v[152:153], off
	v_lshl_add_u64 v[152:153], s[50:51], 0, v[132:133]
	s_mov_b32 m0, s36
	s_nop 0
	global_load_lds_dwordx4 v[152:153], off
	v_lshl_add_u64 v[152:153], s[50:51], 0, v[128:129]
	s_add_i32 m0, s36, 0x2000
	s_nop 0
	global_load_lds_dwordx4 v[152:153], off
	v_lshl_add_u64 v[152:153], v[224:225], 0, s[12:13]
	s_mov_b32 m0, s65
	s_nop 0
	global_load_lds_dwordx4 v[152:153], off
	v_lshl_add_u64 v[152:153], v[226:227], 0, s[12:13]
	s_mov_b32 m0, s66
	s_nop 0
	global_load_lds_dwordx4 v[152:153], off
	s_waitcnt vmcnt(8)
	s_waitcnt lgkmcnt(0)
	s_barrier
	s_waitcnt lgkmcnt(0)
	v_mfma_f32_16x16x32_bf16 v[32:35], v[148:151], v[190:193], v[32:35]
	v_mfma_f32_16x16x32_bf16 v[24:27], v[166:169], v[190:193], v[24:27]
	v_mfma_f32_16x16x32_bf16 v[20:23], v[148:151], v[198:201], v[20:23]
	v_mfma_f32_16x16x32_bf16 v[16:19], v[166:169], v[198:201], v[16:19]
	v_mfma_f32_16x16x32_bf16 v[12:15], v[148:151], v[206:209], v[12:15]
	v_mfma_f32_16x16x32_bf16 v[8:11], v[166:169], v[206:209], v[8:11]
	v_mfma_f32_16x16x32_bf16 v[4:7], v[148:151], v[214:217], v[4:7]
	v_mfma_f32_16x16x32_bf16 v[0:3], v[166:169], v[214:217], v[0:3]
	v_mfma_f32_16x16x32_bf16 v[32:35], v[162:165], v[194:197], v[32:35]
	v_mfma_f32_16x16x32_bf16 v[24:27], v[170:173], v[194:197], v[24:27]
	v_mfma_f32_16x16x32_bf16 v[20:23], v[162:165], v[202:205], v[20:23]
	v_mfma_f32_16x16x32_bf16 v[16:19], v[170:173], v[202:205], v[16:19]
	v_mfma_f32_16x16x32_bf16 v[12:15], v[162:165], v[210:213], v[12:15]
	v_mfma_f32_16x16x32_bf16 v[8:11], v[170:173], v[210:213], v[8:11]
	v_mfma_f32_16x16x32_bf16 v[4:7], v[162:165], v[218:221], v[4:7]
	v_mfma_f32_16x16x32_bf16 v[0:3], v[170:173], v[218:221], v[0:3]
	v_mfma_f32_16x16x32_bf16 v[92:95], v[174:177], v[190:193], v[92:95]
	v_mfma_f32_16x16x32_bf16 v[88:91], v[182:185], v[190:193], v[88:91]
	v_mfma_f32_16x16x32_bf16 v[84:87], v[174:177], v[198:201], v[84:87]
	v_mfma_f32_16x16x32_bf16 v[80:83], v[182:185], v[198:201], v[80:83]
	v_mfma_f32_16x16x32_bf16 v[56:59], v[174:177], v[206:209], v[56:59]
	v_mfma_f32_16x16x32_bf16 v[48:51], v[182:185], v[206:209], v[48:51]
	v_mfma_f32_16x16x32_bf16 v[36:39], v[174:177], v[214:217], v[36:39]
	v_mfma_f32_16x16x32_bf16 v[28:31], v[182:185], v[214:217], v[28:31]
	v_mfma_f32_16x16x32_bf16 v[92:95], v[178:181], v[194:197], v[92:95]
	v_mfma_f32_16x16x32_bf16 v[88:91], v[186:189], v[194:197], v[88:91]
	v_mfma_f32_16x16x32_bf16 v[84:87], v[178:181], v[202:205], v[84:87]
	v_mfma_f32_16x16x32_bf16 v[80:83], v[186:189], v[202:205], v[80:83]
	v_mfma_f32_16x16x32_bf16 v[56:59], v[178:181], v[210:213], v[56:59]
	v_mfma_f32_16x16x32_bf16 v[48:51], v[186:189], v[210:213], v[48:51]
	v_mfma_f32_16x16x32_bf16 v[36:39], v[178:181], v[218:221], v[36:39]
	v_mfma_f32_16x16x32_bf16 v[28:31], v[186:189], v[218:221], v[28:31]
	s_barrier
	s_add_i32 s73, s73, 2
	s_add_u32 s48, s48, 0x100
	s_addc_u32 s49, s49, 0
	s_add_u32 s71, s71, 0x100
	s_addc_u32 s72, s72, 0
.LBB0_131:
	ds_read_b128 v[148:151], v156
	ds_read_b128 v[162:165], v157
	ds_read_b128 v[166:169], v156 offset:2048
	ds_read_b128 v[170:173], v157 offset:2048
	ds_read_b128 v[174:177], v156 offset:16384
	ds_read_b128 v[178:181], v157 offset:16384
	ds_read_b128 v[182:185], v156 offset:18432
	ds_read_b128 v[186:189], v157 offset:18432
	s_add_u32 s36, s48, 0xfff80080
	s_addc_u32 s37, s49, -1
	s_cmp_eq_u32 s73, 28
	s_cselect_b32 s53, s33, s37
	s_cselect_b32 s52, s41, s36
	s_cselect_b32 s51, s39, s72
	s_cselect_b32 s50, s47, s71
	v_lshl_add_u64 v[152:153], s[48:49], 0, v[138:139]
	s_add_i32 m0, s60, 0xc000
	ds_read_b128 v[190:193], v158
	ds_read_b128 v[194:197], v242
	ds_read_b128 v[198:201], v158 offset:2048
	ds_read_b128 v[202:205], v242 offset:2048
	ds_read_b128 v[206:209], v158 offset:4096
	ds_read_b128 v[210:213], v242 offset:4096
	ds_read_b128 v[214:217], v158 offset:6144
	ds_read_b128 v[218:221], v242 offset:6144
	global_load_lds_dwordx4 v[152:153], off
	v_lshl_add_u64 v[152:153], s[48:49], 0, v[140:141]
	s_add_i32 m0, s60, 0xe000
	s_nop 0
	global_load_lds_dwordx4 v[152:153], off
	s_waitcnt vmcnt(8)
	s_waitcnt lgkmcnt(0)
	s_barrier
; #define PG8_STAGE(bufoff, gbase, voff) do { _Pragma("unroll") for (int _i = 0; _i < 2; ++_i) \
;         __builtin_amdgcn_global_load_lds((const unsigned*)((const char*)(gbase) + (voff)[_i]), (PG8_LAS unsigned*)(lds + (bufoff) + ldsw + _i * 8192), 16, 0, 0); } while (0)
; #define PG8_LDA(dst, b, h) do { _Pragma("unroll") for (int m = 0; m < 4; ++m) _Pragma("unroll") for (int k = 0; k < 2; ++k) dst[m][k] = *(const PG8_LAS bf16x8*)(lds + PG8_SA(b, h) + aoff + m * 2048 + k * 1024); } while (0)
; #define PG8_MMA(ai, bj, At, Bt) do { __builtin_amdgcn_s_setprio(1); _Pragma("unroll") for (int m = 0; m < 4; ++m) _Pragma("unroll") for (int n = 0; n < 2; ++n) _Pragma("unroll") for (int k = 0; k < 2; ++k) \
;         acc[ai][bj][m][n] = __builtin_amdgcn_mfma_f32_16x16x32_bf16(Bt[n][k], At[m][k], acc[ai][bj][m][n], 0, 0, 0); __builtin_amdgcn_s_setprio(0); } while (0)
; #define PG8_WAIT_V(n) asm volatile("s_waitcnt vmcnt(" #n ")" ::: "memory")
; #define PG8_WAIT_L(n) asm volatile("s_waitcnt lgkmcnt(" #n ")" ::: "memory")
; #define PG8_BAR __builtin_amdgcn_s_barrier()
; #define PG8_SCHED __builtin_amdgcn_sched_barrier(0)
; template <class Epi, class Sched, bool ALIGN_EPI = false, bool SP2 = false>
; __device__ __forceinline__ void gemm_phase(PG8_LAS unsigned char* lds, const Gemm g, const Sched& S, const Epi& E) {
;     ...
;             PG8_WAIT_V(8); PG8_WAIT_L(0); PG8_BAR; PG8_MMA(0, 0, At, B0); PG8_MMA(0, 1, At, B1); PG8_BAR; PG8_SCHED;
;             PG8_LDA(At, 0, 1); PG8_STAGE(PG8_SB(0, 0), b2, voffB); PG8_STAGE(PG8_SB(0, 1), b2 + hstep, voffB); PG8_STAGE(PG8_SA(0, 0), a2, voffA);
;             PG8_WAIT_V(8); PG8_WAIT_L(0); PG8_BAR; PG8_MMA(1, 0, At, B0); PG8_MMA(1, 1, At, B1); PG8_BAR; PG8_SCHED;
	s_waitcnt lgkmcnt(0)
	v_mfma_f32_16x16x32_bf16 v[76:79], v[148:151], v[190:193], v[76:79]
	v_mfma_f32_16x16x32_bf16 v[72:75], v[166:169], v[190:193], v[72:75]
	v_mfma_f32_16x16x32_bf16 v[68:71], v[148:151], v[198:201], v[68:71]
	v_mfma_f32_16x16x32_bf16 v[64:67], v[166:169], v[198:201], v[64:67]
	v_mfma_f32_16x16x32_bf16 v[60:63], v[148:151], v[206:209], v[60:63]
	v_mfma_f32_16x16x32_bf16 v[52:55], v[166:169], v[206:209], v[52:55]
	v_mfma_f32_16x16x32_bf16 v[44:47], v[148:151], v[214:217], v[44:47]
	v_mfma_f32_16x16x32_bf16 v[40:43], v[166:169], v[214:217], v[40:43]
	v_mfma_f32_16x16x32_bf16 v[76:79], v[162:165], v[194:197], v[76:79]
	v_mfma_f32_16x16x32_bf16 v[72:75], v[170:173], v[194:197], v[72:75]
	v_mfma_f32_16x16x32_bf16 v[68:71], v[162:165], v[202:205], v[68:71]
	v_mfma_f32_16x16x32_bf16 v[64:67], v[170:173], v[202:205], v[64:67]
	v_mfma_f32_16x16x32_bf16 v[60:63], v[162:165], v[210:213], v[60:63]
	v_mfma_f32_16x16x32_bf16 v[52:55], v[170:173], v[210:213], v[52:55]
	v_mfma_f32_16x16x32_bf16 v[44:47], v[162:165], v[218:221], v[44:47]
	v_mfma_f32_16x16x32_bf16 v[40:43], v[170:173], v[218:221], v[40:43]
	v_mfma_f32_16x16x32_bf16 v[124:127], v[174:177], v[190:193], v[124:127]
	v_mfma_f32_16x16x32_bf16 v[120:123], v[182:185], v[190:193], v[120:123]
	v_mfma_f32_16x16x32_bf16 v[116:119], v[174:177], v[198:201], v[116:119]
	v_mfma_f32_16x16x32_bf16 v[112:115], v[182:185], v[198:201], v[112:115]
	v_mfma_f32_16x16x32_bf16 v[108:111], v[174:177], v[206:209], v[108:111]
	v_mfma_f32_16x16x32_bf16 v[104:107], v[182:185], v[206:209], v[104:107]
	v_mfma_f32_16x16x32_bf16 v[100:103], v[174:177], v[214:217], v[100:103]
	v_mfma_f32_16x16x32_bf16 v[96:99], v[182:185], v[214:217], v[96:99]
	v_mfma_f32_16x16x32_bf16 v[124:127], v[178:181], v[194:197], v[124:127]
	v_mfma_f32_16x16x32_bf16 v[120:123], v[186:189], v[194:197], v[120:123]
	v_mfma_f32_16x16x32_bf16 v[116:119], v[178:181], v[202:205], v[116:119]
	v_mfma_f32_16x16x32_bf16 v[112:115], v[186:189], v[202:205], v[112:115]
	v_mfma_f32_16x16x32_bf16 v[108:111], v[178:181], v[210:213], v[108:111]
	v_mfma_f32_16x16x32_bf16 v[104:107], v[186:189], v[210:213], v[104:107]
	v_mfma_f32_16x16x32_bf16 v[100:103], v[178:181], v[218:221], v[100:103]
	v_mfma_f32_16x16x32_bf16 v[96:99], v[186:189], v[218:221], v[96:99]
	s_barrier
	s_add_i32 s36, s68, s57
	v_lshl_add_u64 v[152:153], s[50:51], 0, v[132:133]
	s_mov_b32 m0, s36
	ds_read_b128 v[190:193], v158 offset:16384
	ds_read_b128 v[194:197], v242 offset:16384
	ds_read_b128 v[198:201], v158 offset:18432
	ds_read_b128 v[202:205], v242 offset:18432
	ds_read_b128 v[206:209], v158 offset:20480
	ds_read_b128 v[210:213], v242 offset:20480
	ds_read_b128 v[214:217], v158 offset:22528
	ds_read_b128 v[218:221], v242 offset:22528
	global_load_lds_dwordx4 v[152:153], off
	s_add_i32 m0, s36, 0x2000
	s_add_u32 s74, s50, 0x80000
	v_lshl_add_u64 v[222:223], s[50:51], 0, v[128:129]
	s_addc_u32 s75, s51, 0
	s_add_i32 s36, s69, s57
	global_load_lds_dwordx4 v[222:223], off
	v_lshl_add_u64 v[224:225], s[74:75], 0, v[132:133]
	s_mov_b32 m0, s36
	v_lshl_add_u64 v[226:227], s[52:53], 0, v[130:131]
	global_load_lds_dwordx4 v[224:225], off
	v_lshl_add_u64 v[224:225], s[74:75], 0, v[128:129]
	s_add_i32 m0, s36, 0x2000
	s_nop 0
	global_load_lds_dwordx4 v[224:225], off
	v_lshl_add_u64 v[224:225], s[52:53], 0, v[134:135]
	s_mov_b32 m0, s60
	s_nop 0
	global_load_lds_dwordx4 v[224:225], off
	s_mov_b32 m0, s61
	s_nop 0
	global_load_lds_dwordx4 v[226:227], off
	s_waitcnt vmcnt(8)
	s_waitcnt lgkmcnt(0)
	s_barrier
	s_waitcnt lgkmcnt(0)
	v_mfma_f32_16x16x32_bf16 v[32:35], v[148:151], v[190:193], v[32:35]
	v_mfma_f32_16x16x32_bf16 v[24:27], v[166:169], v[190:193], v[24:27]
	v_mfma_f32_16x16x32_bf16 v[20:23], v[148:151], v[198:201], v[20:23]
	v_mfma_f32_16x16x32_bf16 v[16:19], v[166:169], v[198:201], v[16:19]
	v_mfma_f32_16x16x32_bf16 v[12:15], v[148:151], v[206:209], v[12:15]
	v_mfma_f32_16x16x32_bf16 v[8:11], v[166:169], v[206:209], v[8:11]
	v_mfma_f32_16x16x32_bf16 v[4:7], v[148:151], v[214:217], v[4:7]
	v_mfma_f32_16x16x32_bf16 v[0:3], v[166:169], v[214:217], v[0:3]
	v_mfma_f32_16x16x32_bf16 v[32:35], v[162:165], v[194:197], v[32:35]
	v_mfma_f32_16x16x32_bf16 v[24:27], v[170:173], v[194:197], v[24:27]
	v_mfma_f32_16x16x32_bf16 v[20:23], v[162:165], v[202:205], v[20:23]
	v_mfma_f32_16x16x32_bf16 v[16:19], v[170:173], v[202:205], v[16:19]
	v_mfma_f32_16x16x32_bf16 v[12:15], v[162:165], v[210:213], v[12:15]
	v_mfma_f32_16x16x32_bf16 v[8:11], v[170:173], v[210:213], v[8:11]
	v_mfma_f32_16x16x32_bf16 v[4:7], v[162:165], v[218:221], v[4:7]
	v_mfma_f32_16x16x32_bf16 v[0:3], v[170:173], v[218:221], v[0:3]
	v_mfma_f32_16x16x32_bf16 v[92:95], v[174:177], v[190:193], v[92:95]
	v_mfma_f32_16x16x32_bf16 v[88:91], v[182:185], v[190:193], v[88:91]
	v_mfma_f32_16x16x32_bf16 v[84:87], v[174:177], v[198:201], v[84:87]
	v_mfma_f32_16x16x32_bf16 v[80:83], v[182:185], v[198:201], v[80:83]
	v_mfma_f32_16x16x32_bf16 v[56:59], v[174:177], v[206:209], v[56:59]
	v_mfma_f32_16x16x32_bf16 v[48:51], v[182:185], v[206:209], v[48:51]
	v_mfma_f32_16x16x32_bf16 v[36:39], v[174:177], v[214:217], v[36:39]
	v_mfma_f32_16x16x32_bf16 v[28:31], v[182:185], v[214:217], v[28:31]
	v_mfma_f32_16x16x32_bf16 v[92:95], v[178:181], v[194:197], v[92:95]
	v_mfma_f32_16x16x32_bf16 v[88:91], v[186:189], v[194:197], v[88:91]
	v_mfma_f32_16x16x32_bf16 v[84:87], v[178:181], v[202:205], v[84:87]
	v_mfma_f32_16x16x32_bf16 v[80:83], v[186:189], v[202:205], v[80:83]
	v_mfma_f32_16x16x32_bf16 v[56:59], v[178:181], v[210:213], v[56:59]
	v_mfma_f32_16x16x32_bf16 v[48:51], v[186:189], v[210:213], v[48:51]
	v_mfma_f32_16x16x32_bf16 v[36:39], v[178:181], v[218:221], v[36:39]
	v_mfma_f32_16x16x32_bf16 v[28:31], v[186:189], v[218:221], v[28:31]
	s_barrier
; #define PG8_STAGE(bufoff, gbase, voff) do { _Pragma("unroll") for (int _i = 0; _i < 2; ++_i) \
;         __builtin_amdgcn_global_load_lds((const unsigned*)((const char*)(gbase) + (voff)[_i]), (PG8_LAS unsigned*)(lds + (bufoff) + ldsw + _i * 8192), 16, 0, 0); } while (0)
; #define PG8_LDA(dst, b, h) do { _Pragma("unroll") for (int m = 0; m < 4; ++m) _Pragma("unroll") for (int k = 0; k < 2; ++k) dst[m][k] = *(const PG8_LAS bf16x8*)(lds + PG8_SA(b, h) + aoff + m * 2048 + k * 1024); } while (0)
; #define PG8_LDB(dst, b, h) do { _Pragma("unroll") for (int n = 0; n < 2; ++n) _Pragma("unroll") for (int k = 0; k < 2; ++k) dst[n][k] = *(const PG8_LAS bf16x8*)(lds + PG8_SB(b, h) + boff + n * 2048 + k * 1024); } while (0)
; #define PG8_MMA(ai, bj, At, Bt) do { __builtin_amdgcn_s_setprio(1); _Pragma("unroll") for (int m = 0; m < 4; ++m) _Pragma("unroll") for (int n = 0; n < 2; ++n) _Pragma("unroll") for (int k = 0; k < 2; ++k) \
;         acc[ai][bj][m][n] = __builtin_amdgcn_mfma_f32_16x16x32_bf16(Bt[n][k], At[m][k], acc[ai][bj][m][n], 0, 0, 0); __builtin_amdgcn_s_setprio(0); } while (0)
; #define PG8_WAIT_V(n) asm volatile("s_waitcnt vmcnt(" #n ")" ::: "memory")
; #define PG8_WAIT_L(n) asm volatile("s_waitcnt lgkmcnt(" #n ")" ::: "memory")
; #define PG8_BAR __builtin_amdgcn_s_barrier()
; #define PG8_SCHED __builtin_amdgcn_sched_barrier(0)
; template <class Epi, class Sched, bool ALIGN_EPI = false, bool SP2 = false>
; __device__ __forceinline__ void gemm_phase(PG8_LAS unsigned char* lds, const Gemm g, const Sched& S, const Epi& E) {
;     ...
;             PG8_LDB(B0, 1, 0); PG8_LDB(B1, 1, 1); PG8_SCHED; PG8_LDA(At, 1, 0); PG8_STAGE(PG8_SA(0, 1), a2 + hstep, voffA);
;             PG8_WAIT_V(8); PG8_WAIT_L(0); PG8_BAR; PG8_MMA(0, 0, At, B0); PG8_MMA(0, 1, At, B1); PG8_BAR; PG8_SCHED;
	s_add_i32 s36, 0, 0x18000
	v_add_u32_e32 v161, s36, v154
	s_add_i32 s37, 0, 0x1c000
	ds_read_b128 v[148:151], v156 offset:32768
	ds_read_b128 v[162:165], v157 offset:32768
	ds_read_b128 v[166:169], v156 offset:34816
	ds_read_b128 v[170:173], v157 offset:34816
	v_add_u32_e32 v161, s37, v154
	ds_read_b128 v[174:177], v156 offset:49152
	ds_read_b128 v[178:181], v157 offset:49152
	ds_read_b128 v[182:185], v156 offset:51200
	ds_read_b128 v[186:189], v157 offset:51200
	s_add_u32 s52, s52, 0x80000
	s_addc_u32 s53, s53, 0
	s_mov_b32 m0, s62
	v_lshl_add_u64 v[228:229], s[52:53], 0, v[134:135]
	ds_read_b128 v[190:193], v158 offset:32768
	ds_read_b128 v[194:197], v242 offset:32768
	ds_read_b128 v[198:201], v158 offset:34816
	ds_read_b128 v[202:205], v242 offset:34816
	ds_read_b128 v[206:209], v158 offset:36864
	ds_read_b128 v[210:213], v242 offset:36864
	ds_read_b128 v[214:217], v158 offset:38912
	ds_read_b128 v[218:221], v242 offset:38912
	global_load_lds_dwordx4 v[228:229], off
	v_lshl_add_u64 v[228:229], s[52:53], 0, v[130:131]
	s_mov_b32 m0, s63
	s_nop 0
	global_load_lds_dwordx4 v[228:229], off
	s_waitcnt vmcnt(8)
	s_waitcnt lgkmcnt(0)
	s_barrier
	s_waitcnt lgkmcnt(0)
	v_mfma_f32_16x16x32_bf16 v[76:79], v[148:151], v[190:193], v[76:79]
	v_mfma_f32_16x16x32_bf16 v[72:75], v[166:169], v[190:193], v[72:75]
	v_mfma_f32_16x16x32_bf16 v[68:71], v[148:151], v[198:201], v[68:71]
	v_mfma_f32_16x16x32_bf16 v[64:67], v[166:169], v[198:201], v[64:67]
	v_mfma_f32_16x16x32_bf16 v[60:63], v[148:151], v[206:209], v[60:63]
	v_mfma_f32_16x16x32_bf16 v[52:55], v[166:169], v[206:209], v[52:55]
	v_mfma_f32_16x16x32_bf16 v[44:47], v[148:151], v[214:217], v[44:47]
	v_mfma_f32_16x16x32_bf16 v[40:43], v[166:169], v[214:217], v[40:43]
	v_mfma_f32_16x16x32_bf16 v[76:79], v[162:165], v[194:197], v[76:79]
	v_mfma_f32_16x16x32_bf16 v[72:75], v[170:173], v[194:197], v[72:75]
	v_mfma_f32_16x16x32_bf16 v[68:71], v[162:165], v[202:205], v[68:71]
	v_mfma_f32_16x16x32_bf16 v[64:67], v[170:173], v[202:205], v[64:67]
	v_mfma_f32_16x16x32_bf16 v[60:63], v[162:165], v[210:213], v[60:63]
	v_mfma_f32_16x16x32_bf16 v[52:55], v[170:173], v[210:213], v[52:55]
	v_mfma_f32_16x16x32_bf16 v[44:47], v[162:165], v[218:221], v[44:47]
	v_mfma_f32_16x16x32_bf16 v[40:43], v[170:173], v[218:221], v[40:43]
	v_mfma_f32_16x16x32_bf16 v[124:127], v[174:177], v[190:193], v[124:127]
	v_mfma_f32_16x16x32_bf16 v[120:123], v[182:185], v[190:193], v[120:123]
	v_mfma_f32_16x16x32_bf16 v[116:119], v[174:177], v[198:201], v[116:119]
	v_mfma_f32_16x16x32_bf16 v[112:115], v[182:185], v[198:201], v[112:115]
	v_mfma_f32_16x16x32_bf16 v[108:111], v[174:177], v[206:209], v[108:111]
	v_mfma_f32_16x16x32_bf16 v[104:107], v[182:185], v[206:209], v[104:107]
	v_mfma_f32_16x16x32_bf16 v[100:103], v[174:177], v[214:217], v[100:103]
	v_mfma_f32_16x16x32_bf16 v[96:99], v[182:185], v[214:217], v[96:99]
	v_mfma_f32_16x16x32_bf16 v[124:127], v[178:181], v[194:197], v[124:127]
	v_mfma_f32_16x16x32_bf16 v[120:123], v[186:189], v[194:197], v[120:123]
	v_mfma_f32_16x16x32_bf16 v[116:119], v[178:181], v[202:205], v[116:119]
	v_mfma_f32_16x16x32_bf16 v[112:115], v[186:189], v[202:205], v[112:115]
	v_mfma_f32_16x16x32_bf16 v[108:111], v[178:181], v[210:213], v[108:111]
	v_mfma_f32_16x16x32_bf16 v[104:107], v[186:189], v[210:213], v[104:107]
	v_mfma_f32_16x16x32_bf16 v[100:103], v[178:181], v[218:221], v[100:103]
	v_mfma_f32_16x16x32_bf16 v[96:99], v[186:189], v[218:221], v[96:99]
	s_barrier
; #define PG8_STAGE(bufoff, gbase, voff) do { _Pragma("unroll") for (int _i = 0; _i < 2; ++_i) \
;         __builtin_amdgcn_global_load_lds((const unsigned*)((const char*)(gbase) + (voff)[_i]), (PG8_LAS unsigned*)(lds + (bufoff) + ldsw + _i * 8192), 16, 0, 0); } while (0)
; #define PG8_LDA(dst, b, h) do { _Pragma("unroll") for (int m = 0; m < 4; ++m) _Pragma("unroll") for (int k = 0; k < 2; ++k) dst[m][k] = *(const PG8_LAS bf16x8*)(lds + PG8_SA(b, h) + aoff + m * 2048 + k * 1024); } while (0)
; #define PG8_MMA(ai, bj, At, Bt) do { __builtin_amdgcn_s_setprio(1); _Pragma("unroll") for (int m = 0; m < 4; ++m) _Pragma("unroll") for (int n = 0; n < 2; ++n) _Pragma("unroll") for (int k = 0; k < 2; ++k) \
;         acc[ai][bj][m][n] = __builtin_amdgcn_mfma_f32_16x16x32_bf16(Bt[n][k], At[m][k], acc[ai][bj][m][n], 0, 0, 0); __builtin_amdgcn_s_setprio(0); } while (0)
; #define PG8_WAIT_V(n) asm volatile("s_waitcnt vmcnt(" #n ")" ::: "memory")
; #define PG8_WAIT_L(n) asm volatile("s_waitcnt lgkmcnt(" #n ")" ::: "memory")
; #define PG8_BAR __builtin_amdgcn_s_barrier()
; #define PG8_SCHED __builtin_amdgcn_sched_barrier(0)
; template <class Epi, class Sched, bool ALIGN_EPI = false, bool SP2 = false>
; __device__ __forceinline__ void gemm_phase(PG8_LAS unsigned char* lds, const Gemm g, const Sched& S, const Epi& E) {
;     ...
;             PG8_LDA(At, 1, 1); PG8_STAGE(PG8_SB(1, 0), b3, voffB); PG8_STAGE(PG8_SB(1, 1), b3 + hstep, voffB); PG8_STAGE(PG8_SA(1, 0), a3, voffA);
;             PG8_WAIT_V(8); PG8_WAIT_L(0); PG8_BAR; PG8_MMA(1, 0, At, B0); PG8_MMA(1, 1, At, B1); PG8_BAR; PG8_SCHED;
;     ...
;         if constexpr (ALIGN_EPI) { if (wr == 0) PG8_BAR; }
;         if constexpr (!Epi::AFTER_DRAIN) { E(acc, cur, wr, wc, fr, fq); S.done(cur); }
;         if (!has_next) break;
	s_add_i32 s36, s36, s57
	v_lshl_add_u64 v[152:153], v[152:153], 0, s[12:13]
	s_mov_b32 m0, s36
	ds_read_b128 v[190:193], v158 offset:49152
	ds_read_b128 v[194:197], v242 offset:49152
	ds_read_b128 v[198:201], v158 offset:51200
	ds_read_b128 v[202:205], v242 offset:51200
	ds_read_b128 v[206:209], v158 offset:53248
	ds_read_b128 v[210:213], v242 offset:53248
	ds_read_b128 v[214:217], v158 offset:55296
	ds_read_b128 v[218:221], v242 offset:55296
	global_load_lds_dwordx4 v[152:153], off
	s_add_i32 m0, s36, 0x2000
	s_add_u32 s50, s50, 0x80080
	v_lshl_add_u64 v[152:153], v[222:223], 0, s[12:13]
	s_addc_u32 s51, s51, 0
	s_add_i32 s36, s37, s57
	global_load_lds_dwordx4 v[152:153], off
	v_lshl_add_u64 v[152:153], s[50:51], 0, v[132:133]
	s_mov_b32 m0, s36
	s_nop 0
	global_load_lds_dwordx4 v[152:153], off
	v_lshl_add_u64 v[152:153], s[50:51], 0, v[128:129]
	s_add_i32 m0, s36, 0x2000
	s_nop 0
	global_load_lds_dwordx4 v[152:153], off
	v_lshl_add_u64 v[152:153], v[224:225], 0, s[12:13]
	s_mov_b32 m0, s65
	s_nop 0
	global_load_lds_dwordx4 v[152:153], off
	v_lshl_add_u64 v[152:153], v[226:227], 0, s[12:13]
	s_mov_b32 m0, s66
	s_nop 0
	global_load_lds_dwordx4 v[152:153], off
	s_waitcnt vmcnt(8)
	s_waitcnt lgkmcnt(0)
	s_barrier
	s_waitcnt lgkmcnt(0)
	v_mfma_f32_16x16x32_bf16 v[32:35], v[148:151], v[190:193], v[32:35]
	v_mfma_f32_16x16x32_bf16 v[24:27], v[166:169], v[190:193], v[24:27]
	v_mfma_f32_16x16x32_bf16 v[20:23], v[148:151], v[198:201], v[20:23]
	v_mfma_f32_16x16x32_bf16 v[16:19], v[166:169], v[198:201], v[16:19]
	v_mfma_f32_16x16x32_bf16 v[12:15], v[148:151], v[206:209], v[12:15]
	v_mfma_f32_16x16x32_bf16 v[8:11], v[166:169], v[206:209], v[8:11]
	v_mfma_f32_16x16x32_bf16 v[4:7], v[148:151], v[214:217], v[4:7]
	v_mfma_f32_16x16x32_bf16 v[0:3], v[166:169], v[214:217], v[0:3]
	v_mfma_f32_16x16x32_bf16 v[32:35], v[162:165], v[194:197], v[32:35]
	v_mfma_f32_16x16x32_bf16 v[24:27], v[170:173], v[194:197], v[24:27]
	v_mfma_f32_16x16x32_bf16 v[20:23], v[162:165], v[202:205], v[20:23]
	v_mfma_f32_16x16x32_bf16 v[16:19], v[170:173], v[202:205], v[16:19]
	v_mfma_f32_16x16x32_bf16 v[12:15], v[162:165], v[210:213], v[12:15]
	v_mfma_f32_16x16x32_bf16 v[8:11], v[170:173], v[210:213], v[8:11]
	v_mfma_f32_16x16x32_bf16 v[4:7], v[162:165], v[218:221], v[4:7]
	v_mfma_f32_16x16x32_bf16 v[0:3], v[170:173], v[218:221], v[0:3]
	v_mfma_f32_16x16x32_bf16 v[92:95], v[174:177], v[190:193], v[92:95]
	v_mfma_f32_16x16x32_bf16 v[88:91], v[182:185], v[190:193], v[88:91]
	v_mfma_f32_16x16x32_bf16 v[84:87], v[174:177], v[198:201], v[84:87]
	v_mfma_f32_16x16x32_bf16 v[80:83], v[182:185], v[198:201], v[80:83]
	v_mfma_f32_16x16x32_bf16 v[56:59], v[174:177], v[206:209], v[56:59]
	v_mfma_f32_16x16x32_bf16 v[48:51], v[182:185], v[206:209], v[48:51]
	v_mfma_f32_16x16x32_bf16 v[36:39], v[174:177], v[214:217], v[36:39]
	v_mfma_f32_16x16x32_bf16 v[28:31], v[182:185], v[214:217], v[28:31]
	v_mfma_f32_16x16x32_bf16 v[92:95], v[178:181], v[194:197], v[92:95]
	v_mfma_f32_16x16x32_bf16 v[88:91], v[186:189], v[194:197], v[88:91]
	v_mfma_f32_16x16x32_bf16 v[84:87], v[178:181], v[202:205], v[84:87]
	v_mfma_f32_16x16x32_bf16 v[80:83], v[186:189], v[202:205], v[80:83]
	v_mfma_f32_16x16x32_bf16 v[56:59], v[178:181], v[210:213], v[56:59]
	v_mfma_f32_16x16x32_bf16 v[48:51], v[186:189], v[210:213], v[48:51]
	v_mfma_f32_16x16x32_bf16 v[36:39], v[178:181], v[218:221], v[36:39]
	v_mfma_f32_16x16x32_bf16 v[28:31], v[186:189], v[218:221], v[28:31]
	s_barrier
	s_add_i32 s73, s73, 2
	s_add_u32 s48, s48, 0x100
	s_addc_u32 s49, s49, 0
	s_add_u32 s71, s71, 0x100
	s_addc_u32 s72, s72, 0
	s_cmp_gt_u32 s73, 29
	s_cbranch_scc0 .LBB0_131
	s_setprio 0
	s_and_b64 vcc, exec, s[14:15]
	s_cbranch_vccz .LBB0_138
	s_barrier
	v_lshl_add_u32 v148, s46, 8, v145
	s_cmp_lg_u32 s70, 44
	s_mov_b64 s[46:47], -1
	s_cbranch_scc1 .LBB0_139

; #define PG8_STAGE(bufoff, gbase, voff) do { _Pragma("unroll") for (int _i = 0; _i < 2; ++_i) \
;         __builtin_amdgcn_global_load_lds((const unsigned*)((const char*)(gbase) + (voff)[_i]), (PG8_LAS unsigned*)(lds + (bufoff) + ldsw + _i * 8192), 16, 0, 0); } while (0)
; #define PG8_LDA(dst, b, h) do { _Pragma("unroll") for (int m = 0; m < 4; ++m) _Pragma("unroll") for (int k = 0; k < 2; ++k) dst[m][k] = *(const PG8_LAS bf16x8*)(lds + PG8_SA(b, h) + aoff + m * 2048 + k * 1024); } while (0)
; #define PG8_LDB(dst, b, h) do { _Pragma("unroll") for (int n = 0; n < 2; ++n) _Pragma("unroll") for (int k = 0; k < 2; ++k) dst[n][k] = *(const PG8_LAS bf16x8*)(lds + PG8_SB(b, h) + boff + n * 2048 + k * 1024); } while (0)
; #define PG8_MMA(ai, bj, At, Bt) do { __builtin_amdgcn_s_setprio(1); _Pragma("unroll") for (int m = 0; m < 4; ++m) _Pragma("unroll") for (int n = 0; n < 2; ++n) _Pragma("unroll") for (int k = 0; k < 2; ++k) \
;         acc[ai][bj][m][n] = __builtin_amdgcn_mfma_f32_16x16x32_bf16(Bt[n][k], At[m][k], acc[ai][bj][m][n], 0, 0, 0); __builtin_amdgcn_s_setprio(0); } while (0)
; #define PG8_WAIT_V(n) asm volatile("s_waitcnt vmcnt(" #n ")" ::: "memory")
; #define PG8_WAIT_L(n) asm volatile("s_waitcnt lgkmcnt(" #n ")" ::: "memory")
; #define PG8_BAR __builtin_amdgcn_s_barrier()
; #define PG8_SCHED __builtin_amdgcn_sched_barrier(0)
;     __device__ bool next(int i, pg8::Unit& u) const { if (!base.next(i >> 1, u)) return false; u.seg = i & 1; return true; }
; template <class Epi, class Sched, bool ALIGN_EPI = false, bool SP2 = false>
; __device__ __forceinline__ void gemm_phase(PG8_LAS unsigned char* lds, const Gemm g, const Sched& S, const Epi& E) {
;     ...
;         const bool has_next = S.next(ui + 1, nxt);
;         const char* nA = has_next ? (const char*)(nxt.seg ? g.A2 : g.A) + (size_t)nxt.pm * tstep : cA; const char* nB = has_next ? (const char*)(nxt.seg ? g.Bt2 : g.Bt) + (size_t)nxt.pn * tstep : cB;
;     ...
;             PG8_LDB(B0, 0, 0); PG8_LDB(B1, 0, 1); PG8_SCHED; PG8_LDA(At, 0, 0); PG8_STAGE(PG8_SA(1, 1), a1 + hstep, voffA);
;             PG8_WAIT_V(8); PG8_WAIT_L(0); PG8_BAR; PG8_MMA(0, 0, At, B0); PG8_MMA(0, 1, At, B1); PG8_BAR; PG8_SCHED;
;             PG8_LDA(At, 0, 1); PG8_STAGE(PG8_SB(0, 0), b2, voffB); PG8_STAGE(PG8_SB(0, 1), b2 + hstep, voffB); PG8_STAGE(PG8_SA(0, 0), a2, voffA);
.LBB0_749:
	s_ashr_i32 s25, s24, 31
	s_lshl_b64 s[26:27], s[24:25], 20
	s_add_u32 s26, s35, s26
	s_addc_u32 s27, s44, s27
	s_and_b64 s[28:29], s[0:1], exec
	s_cselect_b32 s25, s27, s39
	s_cselect_b32 s62, s26, s38
	s_ashr_i32 s23, s22, 31
	s_lshl_b64 s[28:29], s[22:23], 20
	s_add_u32 s28, s45, s28
	s_addc_u32 s29, s46, s29
	s_and_b64 s[36:37], s[0:1], exec
	s_cselect_b32 s23, s29, s41
	s_cselect_b32 s63, s28, s40
	s_add_u32 s38, s38, 0x80080
	s_addc_u32 s39, s39, 0
	s_add_u32 s64, s40, 0x100
	v_mov_b32_e32 v0, 0
	s_addc_u32 s65, s41, 0
	s_mov_b32 s66, -2
	s_cmp_lg_u64 s[12:13], 0
	s_cbranch_scc1 .Lsp1_lead
	s_setprio 1
.Lsp1_lead:
	ds_read_b128 v[154:157], v150
	ds_read_b128 v[160:163], v151
	ds_read_b128 v[164:167], v150 offset:2048
	ds_read_b128 v[168:171], v151 offset:2048
	ds_read_b128 v[172:175], v150 offset:16384
	ds_read_b128 v[176:179], v151 offset:16384
	ds_read_b128 v[180:183], v150 offset:18432
	ds_read_b128 v[184:187], v151 offset:18432
	s_add_u32 s36, s38, 0xfff80080
	s_addc_u32 s37, s39, -1
	s_cmp_eq_u32 s66, 28
	s_cselect_b32 s43, s25, s37
	s_cselect_b32 s42, s62, s36
	s_cselect_b32 s41, s23, s65
	s_cselect_b32 s40, s63, s64
	v_lshl_add_u64 v[146:147], s[38:39], 0, v[136:137]
	s_add_i32 m0, s31, 0xc000
	ds_read_b128 v[188:191], v152
	ds_read_b128 v[192:195], v242
	ds_read_b128 v[196:199], v152 offset:2048
	ds_read_b128 v[200:203], v242 offset:2048
	ds_read_b128 v[204:207], v152 offset:4096
	ds_read_b128 v[208:211], v242 offset:4096
	ds_read_b128 v[212:215], v152 offset:6144
	ds_read_b128 v[216:219], v242 offset:6144
	global_load_lds_dwordx4 v[146:147], off
	v_lshl_add_u64 v[146:147], s[38:39], 0, v[138:139]
	s_add_i32 m0, s31, 0xe000
	s_nop 0
	global_load_lds_dwordx4 v[146:147], off
	s_waitcnt vmcnt(8)
	s_waitcnt lgkmcnt(0)
	s_barrier
	s_waitcnt lgkmcnt(0)
	v_mfma_f32_16x16x32_bf16 v[124:127], v[154:157], v[188:191], 0
	v_mfma_f32_16x16x32_bf16 v[120:123], v[164:167], v[188:191], 0
	v_mfma_f32_16x16x32_bf16 v[116:119], v[154:157], v[196:199], 0
	v_mfma_f32_16x16x32_bf16 v[108:111], v[164:167], v[196:199], 0
	v_mfma_f32_16x16x32_bf16 v[100:103], v[154:157], v[204:207], 0
	v_mfma_f32_16x16x32_bf16 v[92:95], v[164:167], v[204:207], 0
	v_mfma_f32_16x16x32_bf16 v[84:87], v[154:157], v[212:215], 0
	v_mfma_f32_16x16x32_bf16 v[76:79], v[164:167], v[212:215], 0
	v_mfma_f32_16x16x32_bf16 v[124:127], v[160:163], v[192:195], v[124:127]
	v_mfma_f32_16x16x32_bf16 v[120:123], v[168:171], v[192:195], v[120:123]
	v_mfma_f32_16x16x32_bf16 v[116:119], v[160:163], v[200:203], v[116:119]
	v_mfma_f32_16x16x32_bf16 v[108:111], v[168:171], v[200:203], v[108:111]
	v_mfma_f32_16x16x32_bf16 v[100:103], v[160:163], v[208:211], v[100:103]
	v_mfma_f32_16x16x32_bf16 v[92:95], v[168:171], v[208:211], v[92:95]
	v_mfma_f32_16x16x32_bf16 v[84:87], v[160:163], v[216:219], v[84:87]
	v_mfma_f32_16x16x32_bf16 v[76:79], v[168:171], v[216:219], v[76:79]
	v_mfma_f32_16x16x32_bf16 v[112:115], v[172:175], v[188:191], 0
	v_mfma_f32_16x16x32_bf16 v[104:107], v[180:183], v[188:191], 0
	v_mfma_f32_16x16x32_bf16 v[96:99], v[172:175], v[196:199], 0
	v_mfma_f32_16x16x32_bf16 v[88:91], v[180:183], v[196:199], 0
	v_mfma_f32_16x16x32_bf16 v[80:83], v[172:175], v[204:207], 0
	v_mfma_f32_16x16x32_bf16 v[72:75], v[180:183], v[204:207], 0
	v_mfma_f32_16x16x32_bf16 v[68:71], v[172:175], v[212:215], 0
	v_mfma_f32_16x16x32_bf16 v[64:67], v[180:183], v[212:215], 0
	v_mfma_f32_16x16x32_bf16 v[112:115], v[176:179], v[192:195], v[112:115]
	v_mfma_f32_16x16x32_bf16 v[104:107], v[184:187], v[192:195], v[104:107]
	v_mfma_f32_16x16x32_bf16 v[96:99], v[176:179], v[200:203], v[96:99]
	v_mfma_f32_16x16x32_bf16 v[88:91], v[184:187], v[200:203], v[88:91]
	v_mfma_f32_16x16x32_bf16 v[80:83], v[176:179], v[208:211], v[80:83]
	v_mfma_f32_16x16x32_bf16 v[72:75], v[184:187], v[208:211], v[72:75]
	v_mfma_f32_16x16x32_bf16 v[68:71], v[176:179], v[216:219], v[68:71]
	v_mfma_f32_16x16x32_bf16 v[64:67], v[184:187], v[216:219], v[64:67]
	s_barrier
	s_add_i32 s36, s55, s47
	v_lshl_add_u64 v[146:147], s[40:41], 0, v[130:131]
	s_mov_b32 m0, s36
	ds_read_b128 v[188:191], v152 offset:16384
	ds_read_b128 v[192:195], v242 offset:16384
	ds_read_b128 v[196:199], v152 offset:18432
	ds_read_b128 v[200:203], v242 offset:18432
	ds_read_b128 v[204:207], v152 offset:20480
	ds_read_b128 v[208:211], v242 offset:20480
	ds_read_b128 v[212:215], v152 offset:22528
	ds_read_b128 v[216:219], v242 offset:22528
	global_load_lds_dwordx4 v[146:147], off
	s_add_i32 m0, s36, 0x2000
	s_add_u32 s36, s40, 0x80000
	v_lshl_add_u64 v[220:221], s[40:41], 0, v[134:135]
	s_addc_u32 s37, s41, 0
	s_add_i32 s67, s56, s47
	global_load_lds_dwordx4 v[220:221], off
	v_lshl_add_u64 v[222:223], s[36:37], 0, v[130:131]
	s_mov_b32 m0, s67
	v_lshl_add_u64 v[224:225], s[42:43], 0, v[132:133]
	global_load_lds_dwordx4 v[222:223], off
	v_lshl_add_u64 v[222:223], s[36:37], 0, v[134:135]
	s_add_i32 m0, s67, 0x2000
	s_nop 0
	global_load_lds_dwordx4 v[222:223], off
	v_lshl_add_u64 v[222:223], s[42:43], 0, v[128:129]
	s_mov_b32 m0, s31
	s_nop 0
	global_load_lds_dwordx4 v[222:223], off
	s_mov_b32 m0, s48
	s_nop 0
	global_load_lds_dwordx4 v[224:225], off
	s_waitcnt vmcnt(8)
	s_waitcnt lgkmcnt(0)
	s_barrier
; #define PG8_STAGE(bufoff, gbase, voff) do { _Pragma("unroll") for (int _i = 0; _i < 2; ++_i) \
;         __builtin_amdgcn_global_load_lds((const unsigned*)((const char*)(gbase) + (voff)[_i]), (PG8_LAS unsigned*)(lds + (bufoff) + ldsw + _i * 8192), 16, 0, 0); } while (0)
; #define PG8_LDA(dst, b, h) do { _Pragma("unroll") for (int m = 0; m < 4; ++m) _Pragma("unroll") for (int k = 0; k < 2; ++k) dst[m][k] = *(const PG8_LAS bf16x8*)(lds + PG8_SA(b, h) + aoff + m * 2048 + k * 1024); } while (0)
; #define PG8_LDB(dst, b, h) do { _Pragma("unroll") for (int n = 0; n < 2; ++n) _Pragma("unroll") for (int k = 0; k < 2; ++k) dst[n][k] = *(const PG8_LAS bf16x8*)(lds + PG8_SB(b, h) + boff + n * 2048 + k * 1024); } while (0)
; #define PG8_MMA(ai, bj, At, Bt) do { __builtin_amdgcn_s_setprio(1); _Pragma("unroll") for (int m = 0; m < 4; ++m) _Pragma("unroll") for (int n = 0; n < 2; ++n) _Pragma("unroll") for (int k = 0; k < 2; ++k) \
;         acc[ai][bj][m][n] = __builtin_amdgcn_mfma_f32_16x16x32_bf16(Bt[n][k], At[m][k], acc[ai][bj][m][n], 0, 0, 0); __builtin_amdgcn_s_setprio(0); } while (0)
; #define PG8_WAIT_V(n) asm volatile("s_waitcnt vmcnt(" #n ")" ::: "memory")
; #define PG8_WAIT_L(n) asm volatile("s_waitcnt lgkmcnt(" #n ")" ::: "memory")
; #define PG8_BAR __builtin_amdgcn_s_barrier()
; #define PG8_SCHED __builtin_amdgcn_sched_barrier(0)
; template <class Epi, class Sched, bool ALIGN_EPI = false, bool SP2 = false>
; __device__ __forceinline__ void gemm_phase(PG8_LAS unsigned char* lds, const Gemm g, const Sched& S, const Epi& E) {
;     ...
;             PG8_WAIT_V(8); PG8_WAIT_L(0); PG8_BAR; PG8_MMA(1, 0, At, B0); PG8_MMA(1, 1, At, B1); PG8_BAR; PG8_SCHED;
;             PG8_LDB(B0, 1, 0); PG8_LDB(B1, 1, 1); PG8_SCHED; PG8_LDA(At, 1, 0); PG8_STAGE(PG8_SA(0, 1), a2 + hstep, voffA);
;             PG8_WAIT_V(8); PG8_WAIT_L(0); PG8_BAR; PG8_MMA(0, 0, At, B0); PG8_MMA(0, 1, At, B1); PG8_BAR; PG8_SCHED;
	s_waitcnt lgkmcnt(0)
	v_mfma_f32_16x16x32_bf16 v[60:63], v[154:157], v[188:191], 0
	v_mfma_f32_16x16x32_bf16 v[56:59], v[164:167], v[188:191], 0
	v_mfma_f32_16x16x32_bf16 v[52:55], v[154:157], v[196:199], 0
	v_mfma_f32_16x16x32_bf16 v[44:47], v[164:167], v[196:199], 0
	v_mfma_f32_16x16x32_bf16 v[36:39], v[154:157], v[204:207], 0
	v_mfma_f32_16x16x32_bf16 v[28:31], v[164:167], v[204:207], 0
	v_mfma_f32_16x16x32_bf16 v[20:23], v[154:157], v[212:215], 0
	v_mfma_f32_16x16x32_bf16 v[12:15], v[164:167], v[212:215], 0
	v_mfma_f32_16x16x32_bf16 v[60:63], v[160:163], v[192:195], v[60:63]
	v_mfma_f32_16x16x32_bf16 v[56:59], v[168:171], v[192:195], v[56:59]
	v_mfma_f32_16x16x32_bf16 v[52:55], v[160:163], v[200:203], v[52:55]
	v_mfma_f32_16x16x32_bf16 v[44:47], v[168:171], v[200:203], v[44:47]
	v_mfma_f32_16x16x32_bf16 v[36:39], v[160:163], v[208:211], v[36:39]
	v_mfma_f32_16x16x32_bf16 v[28:31], v[168:171], v[208:211], v[28:31]
	v_mfma_f32_16x16x32_bf16 v[20:23], v[160:163], v[216:219], v[20:23]
	v_mfma_f32_16x16x32_bf16 v[12:15], v[168:171], v[216:219], v[12:15]
	v_mfma_f32_16x16x32_bf16 v[48:51], v[172:175], v[188:191], 0
	v_mfma_f32_16x16x32_bf16 v[40:43], v[180:183], v[188:191], 0
	v_mfma_f32_16x16x32_bf16 v[32:35], v[172:175], v[196:199], 0
	v_mfma_f32_16x16x32_bf16 v[24:27], v[180:183], v[196:199], 0
	v_mfma_f32_16x16x32_bf16 v[16:19], v[172:175], v[204:207], 0
	v_mfma_f32_16x16x32_bf16 v[8:11], v[180:183], v[204:207], 0
	v_mfma_f32_16x16x32_bf16 v[4:7], v[172:175], v[212:215], 0
	v_mfma_f32_16x16x32_bf16 v[0:3], v[180:183], v[212:215], 0
	v_mfma_f32_16x16x32_bf16 v[48:51], v[176:179], v[192:195], v[48:51]
	v_mfma_f32_16x16x32_bf16 v[40:43], v[184:187], v[192:195], v[40:43]
	v_mfma_f32_16x16x32_bf16 v[32:35], v[176:179], v[200:203], v[32:35]
	v_mfma_f32_16x16x32_bf16 v[24:27], v[184:187], v[200:203], v[24:27]
	v_mfma_f32_16x16x32_bf16 v[16:19], v[176:179], v[208:211], v[16:19]
	v_mfma_f32_16x16x32_bf16 v[8:11], v[184:187], v[208:211], v[8:11]
	v_mfma_f32_16x16x32_bf16 v[4:7], v[176:179], v[216:219], v[4:7]
	v_mfma_f32_16x16x32_bf16 v[0:3], v[184:187], v[216:219], v[0:3]
	s_barrier
	s_add_i32 s67, 0, 0x18000
	v_add_u32_e32 v153, s67, v148
	s_add_i32 s68, 0, 0x1c000
	ds_read_b128 v[154:157], v150 offset:32768
	ds_read_b128 v[160:163], v151 offset:32768
	ds_read_b128 v[164:167], v150 offset:34816
	ds_read_b128 v[168:171], v151 offset:34816
	v_add_u32_e32 v153, s68, v148
	ds_read_b128 v[172:175], v150 offset:49152
	ds_read_b128 v[176:179], v151 offset:49152
	ds_read_b128 v[180:183], v150 offset:51200
	ds_read_b128 v[184:187], v151 offset:51200
	s_add_u32 s36, s42, 0x80000
	s_addc_u32 s37, s43, 0
	s_mov_b32 m0, s49
	v_lshl_add_u64 v[226:227], s[36:37], 0, v[128:129]
	ds_read_b128 v[188:191], v152 offset:32768
	ds_read_b128 v[192:195], v242 offset:32768
	ds_read_b128 v[196:199], v152 offset:34816
	ds_read_b128 v[200:203], v242 offset:34816
	ds_read_b128 v[204:207], v152 offset:36864
	ds_read_b128 v[208:211], v242 offset:36864
	ds_read_b128 v[212:215], v152 offset:38912
	ds_read_b128 v[216:219], v242 offset:38912
	global_load_lds_dwordx4 v[226:227], off
	v_lshl_add_u64 v[226:227], s[36:37], 0, v[132:133]
	s_mov_b32 m0, s50
	s_nop 0
	global_load_lds_dwordx4 v[226:227], off
	s_waitcnt vmcnt(8)
	s_waitcnt lgkmcnt(0)
	s_barrier
	s_waitcnt lgkmcnt(0)
	v_mfma_f32_16x16x32_bf16 v[124:127], v[154:157], v[188:191], v[124:127]
	v_mfma_f32_16x16x32_bf16 v[120:123], v[164:167], v[188:191], v[120:123]
	v_mfma_f32_16x16x32_bf16 v[116:119], v[154:157], v[196:199], v[116:119]
	v_mfma_f32_16x16x32_bf16 v[108:111], v[164:167], v[196:199], v[108:111]
	v_mfma_f32_16x16x32_bf16 v[100:103], v[154:157], v[204:207], v[100:103]
	v_mfma_f32_16x16x32_bf16 v[92:95], v[164:167], v[204:207], v[92:95]
	v_mfma_f32_16x16x32_bf16 v[84:87], v[154:157], v[212:215], v[84:87]
	v_mfma_f32_16x16x32_bf16 v[76:79], v[164:167], v[212:215], v[76:79]
	v_mfma_f32_16x16x32_bf16 v[124:127], v[160:163], v[192:195], v[124:127]
	v_mfma_f32_16x16x32_bf16 v[120:123], v[168:171], v[192:195], v[120:123]
	v_mfma_f32_16x16x32_bf16 v[116:119], v[160:163], v[200:203], v[116:119]
	v_mfma_f32_16x16x32_bf16 v[108:111], v[168:171], v[200:203], v[108:111]
	v_mfma_f32_16x16x32_bf16 v[100:103], v[160:163], v[208:211], v[100:103]
	v_mfma_f32_16x16x32_bf16 v[92:95], v[168:171], v[208:211], v[92:95]
	v_mfma_f32_16x16x32_bf16 v[84:87], v[160:163], v[216:219], v[84:87]
	v_mfma_f32_16x16x32_bf16 v[76:79], v[168:171], v[216:219], v[76:79]
	v_mfma_f32_16x16x32_bf16 v[112:115], v[172:175], v[188:191], v[112:115]
	v_mfma_f32_16x16x32_bf16 v[104:107], v[180:183], v[188:191], v[104:107]
	v_mfma_f32_16x16x32_bf16 v[96:99], v[172:175], v[196:199], v[96:99]
	v_mfma_f32_16x16x32_bf16 v[88:91], v[180:183], v[196:199], v[88:91]
	v_mfma_f32_16x16x32_bf16 v[80:83], v[172:175], v[204:207], v[80:83]
	v_mfma_f32_16x16x32_bf16 v[72:75], v[180:183], v[204:207], v[72:75]
	v_mfma_f32_16x16x32_bf16 v[68:71], v[172:175], v[212:215], v[68:71]
	v_mfma_f32_16x16x32_bf16 v[64:67], v[180:183], v[212:215], v[64:67]
	v_mfma_f32_16x16x32_bf16 v[112:115], v[176:179], v[192:195], v[112:115]
	v_mfma_f32_16x16x32_bf16 v[104:107], v[184:187], v[192:195], v[104:107]
	v_mfma_f32_16x16x32_bf16 v[96:99], v[176:179], v[200:203], v[96:99]
	v_mfma_f32_16x16x32_bf16 v[88:91], v[184:187], v[200:203], v[88:91]
	v_mfma_f32_16x16x32_bf16 v[80:83], v[176:179], v[208:211], v[80:83]
	v_mfma_f32_16x16x32_bf16 v[72:75], v[184:187], v[208:211], v[72:75]
	v_mfma_f32_16x16x32_bf16 v[68:71], v[176:179], v[216:219], v[68:71]
	v_mfma_f32_16x16x32_bf16 v[64:67], v[184:187], v[216:219], v[64:67]
	s_barrier
; #define PG8_STAGE(bufoff, gbase, voff) do { _Pragma("unroll") for (int _i = 0; _i < 2; ++_i) \
;         __builtin_amdgcn_global_load_lds((const unsigned*)((const char*)(gbase) + (voff)[_i]), (PG8_LAS unsigned*)(lds + (bufoff) + ldsw + _i * 8192), 16, 0, 0); } while (0)
; #define PG8_LDA(dst, b, h) do { _Pragma("unroll") for (int m = 0; m < 4; ++m) _Pragma("unroll") for (int k = 0; k < 2; ++k) dst[m][k] = *(const PG8_LAS bf16x8*)(lds + PG8_SA(b, h) + aoff + m * 2048 + k * 1024); } while (0)
; #define PG8_LDB(dst, b, h) do { _Pragma("unroll") for (int n = 0; n < 2; ++n) _Pragma("unroll") for (int k = 0; k < 2; ++k) dst[n][k] = *(const PG8_LAS bf16x8*)(lds + PG8_SB(b, h) + boff + n * 2048 + k * 1024); } while (0)
; #define PG8_MMA(ai, bj, At, Bt) do { __builtin_amdgcn_s_setprio(1); _Pragma("unroll") for (int m = 0; m < 4; ++m) _Pragma("unroll") for (int n = 0; n < 2; ++n) _Pragma("unroll") for (int k = 0; k < 2; ++k) \
;         acc[ai][bj][m][n] = __builtin_amdgcn_mfma_f32_16x16x32_bf16(Bt[n][k], At[m][k], acc[ai][bj][m][n], 0, 0, 0); __builtin_amdgcn_s_setprio(0); } while (0)
; #define PG8_WAIT_V(n) asm volatile("s_waitcnt vmcnt(" #n ")" ::: "memory")
; #define PG8_WAIT_L(n) asm volatile("s_waitcnt lgkmcnt(" #n ")" ::: "memory")
; #define PG8_BAR __builtin_amdgcn_s_barrier()
; #define PG8_SCHED __builtin_amdgcn_sched_barrier(0)
; template <class Epi, class Sched, bool ALIGN_EPI = false, bool SP2 = false>
; __device__ __forceinline__ void gemm_phase(PG8_LAS unsigned char* lds, const Gemm g, const Sched& S, const Epi& E) {
;     ...
;             PG8_LDB(B0, 0, 0); PG8_LDB(B1, 0, 1); PG8_SCHED; PG8_LDA(At, 0, 0); PG8_STAGE(PG8_SA(1, 1), a1 + hstep, voffA);
;             PG8_WAIT_V(8); PG8_WAIT_L(0); PG8_BAR; PG8_MMA(0, 0, At, B0); PG8_MMA(0, 1, At, B1); PG8_BAR; PG8_SCHED;
;     ...
;             PG8_LDA(At, 1, 1); PG8_STAGE(PG8_SB(1, 0), b3, voffB); PG8_STAGE(PG8_SB(1, 1), b3 + hstep, voffB); PG8_STAGE(PG8_SA(1, 0), a3, voffA);
;             PG8_WAIT_V(8); PG8_WAIT_L(0); PG8_BAR; PG8_MMA(1, 0, At, B0); PG8_MMA(1, 1, At, B1); PG8_BAR; PG8_SCHED;
	s_add_i32 s36, s67, s47
	v_lshl_add_u64 v[146:147], v[146:147], 0, s[10:11]
	s_mov_b32 m0, s36
	ds_read_b128 v[188:191], v152 offset:49152
	ds_read_b128 v[192:195], v242 offset:49152
	ds_read_b128 v[196:199], v152 offset:51200
	ds_read_b128 v[200:203], v242 offset:51200
	ds_read_b128 v[204:207], v152 offset:53248
	ds_read_b128 v[208:211], v242 offset:53248
	ds_read_b128 v[212:215], v152 offset:55296
	ds_read_b128 v[216:219], v242 offset:55296
	global_load_lds_dwordx4 v[146:147], off
	s_add_i32 m0, s36, 0x2000
	s_add_u32 s36, s40, 0x80080
	v_lshl_add_u64 v[146:147], v[220:221], 0, s[10:11]
	s_addc_u32 s37, s41, 0
	s_add_i32 s40, s68, s47
	global_load_lds_dwordx4 v[146:147], off
	v_lshl_add_u64 v[146:147], s[36:37], 0, v[130:131]
	s_mov_b32 m0, s40
	s_nop 0
	global_load_lds_dwordx4 v[146:147], off
	v_lshl_add_u64 v[146:147], s[36:37], 0, v[134:135]
	s_add_i32 m0, s40, 0x2000
	s_nop 0
	global_load_lds_dwordx4 v[146:147], off
	v_lshl_add_u64 v[146:147], v[222:223], 0, s[10:11]
	s_mov_b32 m0, s52
	s_nop 0
	global_load_lds_dwordx4 v[146:147], off
	v_lshl_add_u64 v[146:147], v[224:225], 0, s[10:11]
	s_mov_b32 m0, s53
	s_nop 0
	global_load_lds_dwordx4 v[146:147], off
	s_waitcnt vmcnt(8)
	s_waitcnt lgkmcnt(0)
	s_barrier
	s_waitcnt lgkmcnt(0)
	v_mfma_f32_16x16x32_bf16 v[60:63], v[154:157], v[188:191], v[60:63]
	v_mfma_f32_16x16x32_bf16 v[56:59], v[164:167], v[188:191], v[56:59]
	v_mfma_f32_16x16x32_bf16 v[52:55], v[154:157], v[196:199], v[52:55]
	v_mfma_f32_16x16x32_bf16 v[44:47], v[164:167], v[196:199], v[44:47]
	v_mfma_f32_16x16x32_bf16 v[36:39], v[154:157], v[204:207], v[36:39]
	v_mfma_f32_16x16x32_bf16 v[28:31], v[164:167], v[204:207], v[28:31]
	v_mfma_f32_16x16x32_bf16 v[20:23], v[154:157], v[212:215], v[20:23]
	v_mfma_f32_16x16x32_bf16 v[12:15], v[164:167], v[212:215], v[12:15]
	v_mfma_f32_16x16x32_bf16 v[60:63], v[160:163], v[192:195], v[60:63]
	v_mfma_f32_16x16x32_bf16 v[56:59], v[168:171], v[192:195], v[56:59]
	v_mfma_f32_16x16x32_bf16 v[52:55], v[160:163], v[200:203], v[52:55]
	v_mfma_f32_16x16x32_bf16 v[44:47], v[168:171], v[200:203], v[44:47]
	v_mfma_f32_16x16x32_bf16 v[36:39], v[160:163], v[208:211], v[36:39]
	v_mfma_f32_16x16x32_bf16 v[28:31], v[168:171], v[208:211], v[28:31]
	v_mfma_f32_16x16x32_bf16 v[20:23], v[160:163], v[216:219], v[20:23]
	v_mfma_f32_16x16x32_bf16 v[12:15], v[168:171], v[216:219], v[12:15]
	v_mfma_f32_16x16x32_bf16 v[48:51], v[172:175], v[188:191], v[48:51]
	v_mfma_f32_16x16x32_bf16 v[40:43], v[180:183], v[188:191], v[40:43]
	v_mfma_f32_16x16x32_bf16 v[32:35], v[172:175], v[196:199], v[32:35]
	v_mfma_f32_16x16x32_bf16 v[24:27], v[180:183], v[196:199], v[24:27]
	v_mfma_f32_16x16x32_bf16 v[16:19], v[172:175], v[204:207], v[16:19]
	v_mfma_f32_16x16x32_bf16 v[8:11], v[180:183], v[204:207], v[8:11]
	v_mfma_f32_16x16x32_bf16 v[4:7], v[172:175], v[212:215], v[4:7]
	v_mfma_f32_16x16x32_bf16 v[0:3], v[180:183], v[212:215], v[0:3]
	v_mfma_f32_16x16x32_bf16 v[48:51], v[176:179], v[192:195], v[48:51]
	v_mfma_f32_16x16x32_bf16 v[40:43], v[184:187], v[192:195], v[40:43]
	v_mfma_f32_16x16x32_bf16 v[32:35], v[176:179], v[200:203], v[32:35]
	v_mfma_f32_16x16x32_bf16 v[24:27], v[184:187], v[200:203], v[24:27]
	v_mfma_f32_16x16x32_bf16 v[16:19], v[176:179], v[208:211], v[16:19]
	v_mfma_f32_16x16x32_bf16 v[8:11], v[184:187], v[208:211], v[8:11]
	v_mfma_f32_16x16x32_bf16 v[4:7], v[176:179], v[216:219], v[4:7]
	v_mfma_f32_16x16x32_bf16 v[0:3], v[184:187], v[216:219], v[0:3]
	s_barrier
	s_add_i32 s66, s66, 2
	s_add_u32 s38, s38, 0x100
	s_addc_u32 s39, s39, 0
	s_add_u32 s64, s64, 0x100
	s_addc_u32 s65, s65, 0
.LBB0_750:
	ds_read_b128 v[154:157], v150
	ds_read_b128 v[160:163], v151
	ds_read_b128 v[164:167], v150 offset:2048
	ds_read_b128 v[168:171], v151 offset:2048
	ds_read_b128 v[172:175], v150 offset:16384
	ds_read_b128 v[176:179], v151 offset:16384
	ds_read_b128 v[180:183], v150 offset:18432
	ds_read_b128 v[184:187], v151 offset:18432
	s_add_u32 s36, s38, 0xfff80080
	s_addc_u32 s37, s39, -1
	s_cmp_eq_u32 s66, 28
	s_cselect_b32 s43, s25, s37
	s_cselect_b32 s42, s62, s36
	s_cselect_b32 s41, s23, s65
	s_cselect_b32 s40, s63, s64
	v_lshl_add_u64 v[146:147], s[38:39], 0, v[136:137]
	s_add_i32 m0, s31, 0xc000
	ds_read_b128 v[188:191], v152
	ds_read_b128 v[192:195], v242
	ds_read_b128 v[196:199], v152 offset:2048
	ds_read_b128 v[200:203], v242 offset:2048
	ds_read_b128 v[204:207], v152 offset:4096
	ds_read_b128 v[208:211], v242 offset:4096
	ds_read_b128 v[212:215], v152 offset:6144
	ds_read_b128 v[216:219], v242 offset:6144
	global_load_lds_dwordx4 v[146:147], off
	v_lshl_add_u64 v[146:147], s[38:39], 0, v[138:139]
	s_add_i32 m0, s31, 0xe000
	s_nop 0
	global_load_lds_dwordx4 v[146:147], off
	s_waitcnt vmcnt(8)
	s_waitcnt lgkmcnt(0)
	s_barrier
; #define PG8_STAGE(bufoff, gbase, voff) do { _Pragma("unroll") for (int _i = 0; _i < 2; ++_i) \
;         __builtin_amdgcn_global_load_lds((const unsigned*)((const char*)(gbase) + (voff)[_i]), (PG8_LAS unsigned*)(lds + (bufoff) + ldsw + _i * 8192), 16, 0, 0); } while (0)
; #define PG8_LDA(dst, b, h) do { _Pragma("unroll") for (int m = 0; m < 4; ++m) _Pragma("unroll") for (int k = 0; k < 2; ++k) dst[m][k] = *(const PG8_LAS bf16x8*)(lds + PG8_SA(b, h) + aoff + m * 2048 + k * 1024); } while (0)
; #define PG8_MMA(ai, bj, At, Bt) do { __builtin_amdgcn_s_setprio(1); _Pragma("unroll") for (int m = 0; m < 4; ++m) _Pragma("unroll") for (int n = 0; n < 2; ++n) _Pragma("unroll") for (int k = 0; k < 2; ++k) \
;         acc[ai][bj][m][n] = __builtin_amdgcn_mfma_f32_16x16x32_bf16(Bt[n][k], At[m][k], acc[ai][bj][m][n], 0, 0, 0); __builtin_amdgcn_s_setprio(0); } while (0)
; #define PG8_WAIT_V(n) asm volatile("s_waitcnt vmcnt(" #n ")" ::: "memory")
; #define PG8_WAIT_L(n) asm volatile("s_waitcnt lgkmcnt(" #n ")" ::: "memory")
; #define PG8_BAR __builtin_amdgcn_s_barrier()
; #define PG8_SCHED __builtin_amdgcn_sched_barrier(0)
; template <class Epi, class Sched, bool ALIGN_EPI = false, bool SP2 = false>
; __device__ __forceinline__ void gemm_phase(PG8_LAS unsigned char* lds, const Gemm g, const Sched& S, const Epi& E) {
;     ...
;             PG8_WAIT_V(8); PG8_WAIT_L(0); PG8_BAR; PG8_MMA(0, 0, At, B0); PG8_MMA(0, 1, At, B1); PG8_BAR; PG8_SCHED;
;             PG8_LDA(At, 0, 1); PG8_STAGE(PG8_SB(0, 0), b2, voffB); PG8_STAGE(PG8_SB(0, 1), b2 + hstep, voffB); PG8_STAGE(PG8_SA(0, 0), a2, voffA);
;             PG8_WAIT_V(8); PG8_WAIT_L(0); PG8_BAR; PG8_MMA(1, 0, At, B0); PG8_MMA(1, 1, At, B1); PG8_BAR; PG8_SCHED;
	s_waitcnt lgkmcnt(0)
	v_mfma_f32_16x16x32_bf16 v[124:127], v[154:157], v[188:191], v[124:127]
	v_mfma_f32_16x16x32_bf16 v[120:123], v[164:167], v[188:191], v[120:123]
	v_mfma_f32_16x16x32_bf16 v[116:119], v[154:157], v[196:199], v[116:119]
	v_mfma_f32_16x16x32_bf16 v[108:111], v[164:167], v[196:199], v[108:111]
	v_mfma_f32_16x16x32_bf16 v[100:103], v[154:157], v[204:207], v[100:103]
	v_mfma_f32_16x16x32_bf16 v[92:95], v[164:167], v[204:207], v[92:95]
	v_mfma_f32_16x16x32_bf16 v[84:87], v[154:157], v[212:215], v[84:87]
	v_mfma_f32_16x16x32_bf16 v[76:79], v[164:167], v[212:215], v[76:79]
	v_mfma_f32_16x16x32_bf16 v[124:127], v[160:163], v[192:195], v[124:127]
	v_mfma_f32_16x16x32_bf16 v[120:123], v[168:171], v[192:195], v[120:123]
	v_mfma_f32_16x16x32_bf16 v[116:119], v[160:163], v[200:203], v[116:119]
	v_mfma_f32_16x16x32_bf16 v[108:111], v[168:171], v[200:203], v[108:111]
	v_mfma_f32_16x16x32_bf16 v[100:103], v[160:163], v[208:211], v[100:103]
	v_mfma_f32_16x16x32_bf16 v[92:95], v[168:171], v[208:211], v[92:95]
	v_mfma_f32_16x16x32_bf16 v[84:87], v[160:163], v[216:219], v[84:87]
	v_mfma_f32_16x16x32_bf16 v[76:79], v[168:171], v[216:219], v[76:79]
	v_mfma_f32_16x16x32_bf16 v[112:115], v[172:175], v[188:191], v[112:115]
	v_mfma_f32_16x16x32_bf16 v[104:107], v[180:183], v[188:191], v[104:107]
	v_mfma_f32_16x16x32_bf16 v[96:99], v[172:175], v[196:199], v[96:99]
	v_mfma_f32_16x16x32_bf16 v[88:91], v[180:183], v[196:199], v[88:91]
	v_mfma_f32_16x16x32_bf16 v[80:83], v[172:175], v[204:207], v[80:83]
	v_mfma_f32_16x16x32_bf16 v[72:75], v[180:183], v[204:207], v[72:75]
	v_mfma_f32_16x16x32_bf16 v[68:71], v[172:175], v[212:215], v[68:71]
	v_mfma_f32_16x16x32_bf16 v[64:67], v[180:183], v[212:215], v[64:67]
	v_mfma_f32_16x16x32_bf16 v[112:115], v[176:179], v[192:195], v[112:115]
	v_mfma_f32_16x16x32_bf16 v[104:107], v[184:187], v[192:195], v[104:107]
	v_mfma_f32_16x16x32_bf16 v[96:99], v[176:179], v[200:203], v[96:99]
	v_mfma_f32_16x16x32_bf16 v[88:91], v[184:187], v[200:203], v[88:91]
	v_mfma_f32_16x16x32_bf16 v[80:83], v[176:179], v[208:211], v[80:83]
	v_mfma_f32_16x16x32_bf16 v[72:75], v[184:187], v[208:211], v[72:75]
	v_mfma_f32_16x16x32_bf16 v[68:71], v[176:179], v[216:219], v[68:71]
	v_mfma_f32_16x16x32_bf16 v[64:67], v[184:187], v[216:219], v[64:67]
	s_barrier
	s_add_i32 s36, s55, s47
	v_lshl_add_u64 v[146:147], s[40:41], 0, v[130:131]
	s_mov_b32 m0, s36
	ds_read_b128 v[188:191], v152 offset:16384
	ds_read_b128 v[192:195], v242 offset:16384
	ds_read_b128 v[196:199], v152 offset:18432
	ds_read_b128 v[200:203], v242 offset:18432
	ds_read_b128 v[204:207], v152 offset:20480
	ds_read_b128 v[208:211], v242 offset:20480
	ds_read_b128 v[212:215], v152 offset:22528
	ds_read_b128 v[216:219], v242 offset:22528
	global_load_lds_dwordx4 v[146:147], off
	s_add_i32 m0, s36, 0x2000
	s_add_u32 s36, s40, 0x80000
	v_lshl_add_u64 v[220:221], s[40:41], 0, v[134:135]
	s_addc_u32 s37, s41, 0
	s_add_i32 s67, s56, s47
	global_load_lds_dwordx4 v[220:221], off
	v_lshl_add_u64 v[222:223], s[36:37], 0, v[130:131]
	s_mov_b32 m0, s67
	v_lshl_add_u64 v[224:225], s[42:43], 0, v[132:133]
	global_load_lds_dwordx4 v[222:223], off
	v_lshl_add_u64 v[222:223], s[36:37], 0, v[134:135]
	s_add_i32 m0, s67, 0x2000
	s_nop 0
	global_load_lds_dwordx4 v[222:223], off
	v_lshl_add_u64 v[222:223], s[42:43], 0, v[128:129]
	s_mov_b32 m0, s31
	s_nop 0
	global_load_lds_dwordx4 v[222:223], off
	s_mov_b32 m0, s48
	s_nop 0
	global_load_lds_dwordx4 v[224:225], off
	s_waitcnt vmcnt(8)
	s_waitcnt lgkmcnt(0)
	s_barrier
	s_waitcnt lgkmcnt(0)
	v_mfma_f32_16x16x32_bf16 v[60:63], v[154:157], v[188:191], v[60:63]
	v_mfma_f32_16x16x32_bf16 v[56:59], v[164:167], v[188:191], v[56:59]
	v_mfma_f32_16x16x32_bf16 v[52:55], v[154:157], v[196:199], v[52:55]
	v_mfma_f32_16x16x32_bf16 v[44:47], v[164:167], v[196:199], v[44:47]
	v_mfma_f32_16x16x32_bf16 v[36:39], v[154:157], v[204:207], v[36:39]
	v_mfma_f32_16x16x32_bf16 v[28:31], v[164:167], v[204:207], v[28:31]
	v_mfma_f32_16x16x32_bf16 v[20:23], v[154:157], v[212:215], v[20:23]
	v_mfma_f32_16x16x32_bf16 v[12:15], v[164:167], v[212:215], v[12:15]
	v_mfma_f32_16x16x32_bf16 v[60:63], v[160:163], v[192:195], v[60:63]
	v_mfma_f32_16x16x32_bf16 v[56:59], v[168:171], v[192:195], v[56:59]
	v_mfma_f32_16x16x32_bf16 v[52:55], v[160:163], v[200:203], v[52:55]
	v_mfma_f32_16x16x32_bf16 v[44:47], v[168:171], v[200:203], v[44:47]
	v_mfma_f32_16x16x32_bf16 v[36:39], v[160:163], v[208:211], v[36:39]
	v_mfma_f32_16x16x32_bf16 v[28:31], v[168:171], v[208:211], v[28:31]
	v_mfma_f32_16x16x32_bf16 v[20:23], v[160:163], v[216:219], v[20:23]
	v_mfma_f32_16x16x32_bf16 v[12:15], v[168:171], v[216:219], v[12:15]
	v_mfma_f32_16x16x32_bf16 v[48:51], v[172:175], v[188:191], v[48:51]
	v_mfma_f32_16x16x32_bf16 v[40:43], v[180:183], v[188:191], v[40:43]
	v_mfma_f32_16x16x32_bf16 v[32:35], v[172:175], v[196:199], v[32:35]
	v_mfma_f32_16x16x32_bf16 v[24:27], v[180:183], v[196:199], v[24:27]
	v_mfma_f32_16x16x32_bf16 v[16:19], v[172:175], v[204:207], v[16:19]
	v_mfma_f32_16x16x32_bf16 v[8:11], v[180:183], v[204:207], v[8:11]
	v_mfma_f32_16x16x32_bf16 v[4:7], v[172:175], v[212:215], v[4:7]
	v_mfma_f32_16x16x32_bf16 v[0:3], v[180:183], v[212:215], v[0:3]
	v_mfma_f32_16x16x32_bf16 v[48:51], v[176:179], v[192:195], v[48:51]
	v_mfma_f32_16x16x32_bf16 v[40:43], v[184:187], v[192:195], v[40:43]
	v_mfma_f32_16x16x32_bf16 v[32:35], v[176:179], v[200:203], v[32:35]
	v_mfma_f32_16x16x32_bf16 v[24:27], v[184:187], v[200:203], v[24:27]
	v_mfma_f32_16x16x32_bf16 v[16:19], v[176:179], v[208:211], v[16:19]
	v_mfma_f32_16x16x32_bf16 v[8:11], v[184:187], v[208:211], v[8:11]
	v_mfma_f32_16x16x32_bf16 v[4:7], v[176:179], v[216:219], v[4:7]
	v_mfma_f32_16x16x32_bf16 v[0:3], v[184:187], v[216:219], v[0:3]
	s_barrier
; #define PG8_STAGE(bufoff, gbase, voff) do { _Pragma("unroll") for (int _i = 0; _i < 2; ++_i) \
;         __builtin_amdgcn_global_load_lds((const unsigned*)((const char*)(gbase) + (voff)[_i]), (PG8_LAS unsigned*)(lds + (bufoff) + ldsw + _i * 8192), 16, 0, 0); } while (0)
; #define PG8_LDA(dst, b, h) do { _Pragma("unroll") for (int m = 0; m < 4; ++m) _Pragma("unroll") for (int k = 0; k < 2; ++k) dst[m][k] = *(const PG8_LAS bf16x8*)(lds + PG8_SA(b, h) + aoff + m * 2048 + k * 1024); } while (0)
; #define PG8_LDB(dst, b, h) do { _Pragma("unroll") for (int n = 0; n < 2; ++n) _Pragma("unroll") for (int k = 0; k < 2; ++k) dst[n][k] = *(const PG8_LAS bf16x8*)(lds + PG8_SB(b, h) + boff + n * 2048 + k * 1024); } while (0)
; #define PG8_MMA(ai, bj, At, Bt) do { __builtin_amdgcn_s_setprio(1); _Pragma("unroll") for (int m = 0; m < 4; ++m) _Pragma("unroll") for (int n = 0; n < 2; ++n) _Pragma("unroll") for (int k = 0; k < 2; ++k) \
;         acc[ai][bj][m][n] = __builtin_amdgcn_mfma_f32_16x16x32_bf16(Bt[n][k], At[m][k], acc[ai][bj][m][n], 0, 0, 0); __builtin_amdgcn_s_setprio(0); } while (0)
; #define PG8_WAIT_V(n) asm volatile("s_waitcnt vmcnt(" #n ")" ::: "memory")
; #define PG8_WAIT_L(n) asm volatile("s_waitcnt lgkmcnt(" #n ")" ::: "memory")
; #define PG8_BAR __builtin_amdgcn_s_barrier()
; #define PG8_SCHED __builtin_amdgcn_sched_barrier(0)
; template <class Epi, class Sched, bool ALIGN_EPI = false, bool SP2 = false>
; __device__ __forceinline__ void gemm_phase(PG8_LAS unsigned char* lds, const Gemm g, const Sched& S, const Epi& E) {
;     ...
;             PG8_LDB(B0, 1, 0); PG8_LDB(B1, 1, 1); PG8_SCHED; PG8_LDA(At, 1, 0); PG8_STAGE(PG8_SA(0, 1), a2 + hstep, voffA);
;             PG8_WAIT_V(8); PG8_WAIT_L(0); PG8_BAR; PG8_MMA(0, 0, At, B0); PG8_MMA(0, 1, At, B1); PG8_BAR; PG8_SCHED;
	s_add_i32 s67, 0, 0x18000
	v_add_u32_e32 v153, s67, v148
	s_add_i32 s68, 0, 0x1c000
	ds_read_b128 v[154:157], v150 offset:32768
	ds_read_b128 v[160:163], v151 offset:32768
	ds_read_b128 v[164:167], v150 offset:34816
	ds_read_b128 v[168:171], v151 offset:34816
	v_add_u32_e32 v153, s68, v148
	ds_read_b128 v[172:175], v150 offset:49152
	ds_read_b128 v[176:179], v151 offset:49152
	ds_read_b128 v[180:183], v150 offset:51200
	ds_read_b128 v[184:187], v151 offset:51200
	s_add_u32 s36, s42, 0x80000
	s_addc_u32 s37, s43, 0
	s_mov_b32 m0, s49
	v_lshl_add_u64 v[226:227], s[36:37], 0, v[128:129]
	ds_read_b128 v[188:191], v152 offset:32768
	ds_read_b128 v[192:195], v242 offset:32768
	ds_read_b128 v[196:199], v152 offset:34816
	ds_read_b128 v[200:203], v242 offset:34816
	ds_read_b128 v[204:207], v152 offset:36864
	ds_read_b128 v[208:211], v242 offset:36864
	ds_read_b128 v[212:215], v152 offset:38912
	ds_read_b128 v[216:219], v242 offset:38912
	global_load_lds_dwordx4 v[226:227], off
	v_lshl_add_u64 v[226:227], s[36:37], 0, v[132:133]
	s_mov_b32 m0, s50
	s_nop 0
	global_load_lds_dwordx4 v[226:227], off
	s_waitcnt vmcnt(8)
	s_waitcnt lgkmcnt(0)
	s_barrier
	s_waitcnt lgkmcnt(0)
	v_mfma_f32_16x16x32_bf16 v[124:127], v[154:157], v[188:191], v[124:127]
	v_mfma_f32_16x16x32_bf16 v[120:123], v[164:167], v[188:191], v[120:123]
	v_mfma_f32_16x16x32_bf16 v[116:119], v[154:157], v[196:199], v[116:119]
	v_mfma_f32_16x16x32_bf16 v[108:111], v[164:167], v[196:199], v[108:111]
	v_mfma_f32_16x16x32_bf16 v[100:103], v[154:157], v[204:207], v[100:103]
	v_mfma_f32_16x16x32_bf16 v[92:95], v[164:167], v[204:207], v[92:95]
	v_mfma_f32_16x16x32_bf16 v[84:87], v[154:157], v[212:215], v[84:87]
	v_mfma_f32_16x16x32_bf16 v[76:79], v[164:167], v[212:215], v[76:79]
	v_mfma_f32_16x16x32_bf16 v[124:127], v[160:163], v[192:195], v[124:127]
	v_mfma_f32_16x16x32_bf16 v[120:123], v[168:171], v[192:195], v[120:123]
	v_mfma_f32_16x16x32_bf16 v[116:119], v[160:163], v[200:203], v[116:119]
	v_mfma_f32_16x16x32_bf16 v[108:111], v[168:171], v[200:203], v[108:111]
	v_mfma_f32_16x16x32_bf16 v[100:103], v[160:163], v[208:211], v[100:103]
	v_mfma_f32_16x16x32_bf16 v[92:95], v[168:171], v[208:211], v[92:95]
	v_mfma_f32_16x16x32_bf16 v[84:87], v[160:163], v[216:219], v[84:87]
	v_mfma_f32_16x16x32_bf16 v[76:79], v[168:171], v[216:219], v[76:79]
	v_mfma_f32_16x16x32_bf16 v[112:115], v[172:175], v[188:191], v[112:115]
	v_mfma_f32_16x16x32_bf16 v[104:107], v[180:183], v[188:191], v[104:107]
	v_mfma_f32_16x16x32_bf16 v[96:99], v[172:175], v[196:199], v[96:99]
	v_mfma_f32_16x16x32_bf16 v[88:91], v[180:183], v[196:199], v[88:91]
	v_mfma_f32_16x16x32_bf16 v[80:83], v[172:175], v[204:207], v[80:83]
	v_mfma_f32_16x16x32_bf16 v[72:75], v[180:183], v[204:207], v[72:75]
	v_mfma_f32_16x16x32_bf16 v[68:71], v[172:175], v[212:215], v[68:71]
	v_mfma_f32_16x16x32_bf16 v[64:67], v[180:183], v[212:215], v[64:67]
	v_mfma_f32_16x16x32_bf16 v[112:115], v[176:179], v[192:195], v[112:115]
	v_mfma_f32_16x16x32_bf16 v[104:107], v[184:187], v[192:195], v[104:107]
	v_mfma_f32_16x16x32_bf16 v[96:99], v[176:179], v[200:203], v[96:99]
	v_mfma_f32_16x16x32_bf16 v[88:91], v[184:187], v[200:203], v[88:91]
	v_mfma_f32_16x16x32_bf16 v[80:83], v[176:179], v[208:211], v[80:83]
	v_mfma_f32_16x16x32_bf16 v[72:75], v[184:187], v[208:211], v[72:75]
	v_mfma_f32_16x16x32_bf16 v[68:71], v[176:179], v[216:219], v[68:71]
	v_mfma_f32_16x16x32_bf16 v[64:67], v[184:187], v[216:219], v[64:67]
	s_barrier
; #define PG8_STAGE(bufoff, gbase, voff) do { _Pragma("unroll") for (int _i = 0; _i < 2; ++_i) \
;         __builtin_amdgcn_global_load_lds((const unsigned*)((const char*)(gbase) + (voff)[_i]), (PG8_LAS unsigned*)(lds + (bufoff) + ldsw + _i * 8192), 16, 0, 0); } while (0)
; #define PG8_LDA(dst, b, h) do { _Pragma("unroll") for (int m = 0; m < 4; ++m) _Pragma("unroll") for (int k = 0; k < 2; ++k) dst[m][k] = *(const PG8_LAS bf16x8*)(lds + PG8_SA(b, h) + aoff + m * 2048 + k * 1024); } while (0)
; #define PG8_MMA(ai, bj, At, Bt) do { __builtin_amdgcn_s_setprio(1); _Pragma("unroll") for (int m = 0; m < 4; ++m) _Pragma("unroll") for (int n = 0; n < 2; ++n) _Pragma("unroll") for (int k = 0; k < 2; ++k) \
;         acc[ai][bj][m][n] = __builtin_amdgcn_mfma_f32_16x16x32_bf16(Bt[n][k], At[m][k], acc[ai][bj][m][n], 0, 0, 0); __builtin_amdgcn_s_setprio(0); } while (0)
; #define PG8_WAIT_V(n) asm volatile("s_waitcnt vmcnt(" #n ")" ::: "memory")
; #define PG8_WAIT_L(n) asm volatile("s_waitcnt lgkmcnt(" #n ")" ::: "memory")
; #define PG8_BAR __builtin_amdgcn_s_barrier()
; #define PG8_SCHED __builtin_amdgcn_sched_barrier(0)
; template <class Epi, class Sched, bool ALIGN_EPI = false, bool SP2 = false>
; __device__ __forceinline__ void gemm_phase(PG8_LAS unsigned char* lds, const Gemm g, const Sched& S, const Epi& E) {
;     ...
;             PG8_LDA(At, 1, 1); PG8_STAGE(PG8_SB(1, 0), b3, voffB); PG8_STAGE(PG8_SB(1, 1), b3 + hstep, voffB); PG8_STAGE(PG8_SA(1, 0), a3, voffA);
;             PG8_WAIT_V(8); PG8_WAIT_L(0); PG8_BAR; PG8_MMA(1, 0, At, B0); PG8_MMA(1, 1, At, B1); PG8_BAR; PG8_SCHED;
;     ...
;         if constexpr (ALIGN_EPI) { if (wr == 0) PG8_BAR; }
	s_add_i32 s36, s67, s47
	v_lshl_add_u64 v[146:147], v[146:147], 0, s[10:11]
	s_mov_b32 m0, s36
	ds_read_b128 v[188:191], v152 offset:49152
	ds_read_b128 v[192:195], v242 offset:49152
	ds_read_b128 v[196:199], v152 offset:51200
	ds_read_b128 v[200:203], v242 offset:51200
	ds_read_b128 v[204:207], v152 offset:53248
	ds_read_b128 v[208:211], v242 offset:53248
	ds_read_b128 v[212:215], v152 offset:55296
	ds_read_b128 v[216:219], v242 offset:55296
	global_load_lds_dwordx4 v[146:147], off
	s_add_i32 m0, s36, 0x2000
	s_add_u32 s36, s40, 0x80080
	v_lshl_add_u64 v[146:147], v[220:221], 0, s[10:11]
	s_addc_u32 s37, s41, 0
	s_add_i32 s40, s68, s47
	global_load_lds_dwordx4 v[146:147], off
	v_lshl_add_u64 v[146:147], s[36:37], 0, v[130:131]
	s_mov_b32 m0, s40
	s_nop 0
	global_load_lds_dwordx4 v[146:147], off
	v_lshl_add_u64 v[146:147], s[36:37], 0, v[134:135]
	s_add_i32 m0, s40, 0x2000
	s_nop 0
	global_load_lds_dwordx4 v[146:147], off
	v_lshl_add_u64 v[146:147], v[222:223], 0, s[10:11]
	s_mov_b32 m0, s52
	s_nop 0
	global_load_lds_dwordx4 v[146:147], off
	v_lshl_add_u64 v[146:147], v[224:225], 0, s[10:11]
	s_mov_b32 m0, s53
	s_nop 0
	global_load_lds_dwordx4 v[146:147], off
	s_waitcnt vmcnt(8)
	s_waitcnt lgkmcnt(0)
	s_barrier
	s_waitcnt lgkmcnt(0)
	v_mfma_f32_16x16x32_bf16 v[60:63], v[154:157], v[188:191], v[60:63]
	v_mfma_f32_16x16x32_bf16 v[56:59], v[164:167], v[188:191], v[56:59]
	v_mfma_f32_16x16x32_bf16 v[52:55], v[154:157], v[196:199], v[52:55]
	v_mfma_f32_16x16x32_bf16 v[44:47], v[164:167], v[196:199], v[44:47]
	v_mfma_f32_16x16x32_bf16 v[36:39], v[154:157], v[204:207], v[36:39]
	v_mfma_f32_16x16x32_bf16 v[28:31], v[164:167], v[204:207], v[28:31]
	v_mfma_f32_16x16x32_bf16 v[20:23], v[154:157], v[212:215], v[20:23]
	v_mfma_f32_16x16x32_bf16 v[12:15], v[164:167], v[212:215], v[12:15]
	v_mfma_f32_16x16x32_bf16 v[60:63], v[160:163], v[192:195], v[60:63]
	v_mfma_f32_16x16x32_bf16 v[56:59], v[168:171], v[192:195], v[56:59]
	v_mfma_f32_16x16x32_bf16 v[52:55], v[160:163], v[200:203], v[52:55]
	v_mfma_f32_16x16x32_bf16 v[44:47], v[168:171], v[200:203], v[44:47]
	v_mfma_f32_16x16x32_bf16 v[36:39], v[160:163], v[208:211], v[36:39]
	v_mfma_f32_16x16x32_bf16 v[28:31], v[168:171], v[208:211], v[28:31]
	v_mfma_f32_16x16x32_bf16 v[20:23], v[160:163], v[216:219], v[20:23]
	v_mfma_f32_16x16x32_bf16 v[12:15], v[168:171], v[216:219], v[12:15]
	v_mfma_f32_16x16x32_bf16 v[48:51], v[172:175], v[188:191], v[48:51]
	v_mfma_f32_16x16x32_bf16 v[40:43], v[180:183], v[188:191], v[40:43]
	v_mfma_f32_16x16x32_bf16 v[32:35], v[172:175], v[196:199], v[32:35]
	v_mfma_f32_16x16x32_bf16 v[24:27], v[180:183], v[196:199], v[24:27]
	v_mfma_f32_16x16x32_bf16 v[16:19], v[172:175], v[204:207], v[16:19]
	v_mfma_f32_16x16x32_bf16 v[8:11], v[180:183], v[204:207], v[8:11]
	v_mfma_f32_16x16x32_bf16 v[4:7], v[172:175], v[212:215], v[4:7]
	v_mfma_f32_16x16x32_bf16 v[0:3], v[180:183], v[212:215], v[0:3]
	v_mfma_f32_16x16x32_bf16 v[48:51], v[176:179], v[192:195], v[48:51]
	v_mfma_f32_16x16x32_bf16 v[40:43], v[184:187], v[192:195], v[40:43]
	v_mfma_f32_16x16x32_bf16 v[32:35], v[176:179], v[200:203], v[32:35]
	v_mfma_f32_16x16x32_bf16 v[24:27], v[184:187], v[200:203], v[24:27]
	v_mfma_f32_16x16x32_bf16 v[16:19], v[176:179], v[208:211], v[16:19]
	v_mfma_f32_16x16x32_bf16 v[8:11], v[184:187], v[208:211], v[8:11]
	v_mfma_f32_16x16x32_bf16 v[4:7], v[176:179], v[216:219], v[4:7]
	v_mfma_f32_16x16x32_bf16 v[0:3], v[184:187], v[216:219], v[0:3]
	s_barrier
	s_add_i32 s66, s66, 2
	s_add_u32 s38, s38, 0x100
	s_addc_u32 s39, s39, 0
	s_add_u32 s64, s64, 0x100
	s_addc_u32 s65, s65, 0
	s_cmp_gt_u32 s66, 29
	s_cbranch_scc0 .LBB0_750
	s_setprio 0
	s_and_b64 vcc, exec, s[12:13]
	s_cbranch_vccz .LBB0_753
	s_barrier

; #define PG8_STAGE(bufoff, gbase, voff) do { _Pragma("unroll") for (int _i = 0; _i < 2; ++_i) \
;         __builtin_amdgcn_global_load_lds((const unsigned*)((const char*)(gbase) + (voff)[_i]), (PG8_LAS unsigned*)(lds + (bufoff) + ldsw + _i * 8192), 16, 0, 0); } while (0)
; #define PG8_LDA(dst, b, h) do { _Pragma("unroll") for (int m = 0; m < 4; ++m) _Pragma("unroll") for (int k = 0; k < 2; ++k) dst[m][k] = *(const PG8_LAS bf16x8*)(lds + PG8_SA(b, h) + aoff + m * 2048 + k * 1024); } while (0)
; #define PG8_LDB(dst, b, h) do { _Pragma("unroll") for (int n = 0; n < 2; ++n) _Pragma("unroll") for (int k = 0; k < 2; ++k) dst[n][k] = *(const PG8_LAS bf16x8*)(lds + PG8_SB(b, h) + boff + n * 2048 + k * 1024); } while (0)
; #define PG8_MMA(ai, bj, At, Bt) do { __builtin_amdgcn_s_setprio(1); _Pragma("unroll") for (int m = 0; m < 4; ++m) _Pragma("unroll") for (int n = 0; n < 2; ++n) _Pragma("unroll") for (int k = 0; k < 2; ++k) \
;         acc[ai][bj][m][n] = __builtin_amdgcn_mfma_f32_16x16x32_bf16(Bt[n][k], At[m][k], acc[ai][bj][m][n], 0, 0, 0); __builtin_amdgcn_s_setprio(0); } while (0)
; #define PG8_WAIT_V(n) asm volatile("s_waitcnt vmcnt(" #n ")" ::: "memory")
; #define PG8_WAIT_L(n) asm volatile("s_waitcnt lgkmcnt(" #n ")" ::: "memory")
; #define PG8_BAR __builtin_amdgcn_s_barrier()
; #define PG8_SCHED __builtin_amdgcn_sched_barrier(0)
;     __device__ bool next(int i, pg8::Unit& u) const { if (!base.next(i >> 1, u)) return false; u.seg = i & 1; return true; }
; template <class Epi, class Sched, bool ALIGN_EPI = false, bool SP2 = false>
; __device__ __forceinline__ void gemm_phase(PG8_LAS unsigned char* lds, const Gemm g, const Sched& S, const Epi& E) {
;     ...
;         const bool has_next = S.next(ui + 1, nxt);
;         const char* nA = has_next ? (const char*)(nxt.seg ? g.A2 : g.A) + (size_t)nxt.pm * tstep : cA; const char* nB = has_next ? (const char*)(nxt.seg ? g.Bt2 : g.Bt) + (size_t)nxt.pn * tstep : cB;
;     ...
;             PG8_LDB(B0, 0, 0); PG8_LDB(B1, 0, 1); PG8_SCHED; PG8_LDA(At, 0, 0); PG8_STAGE(PG8_SA(1, 1), a1 + hstep, voffA);
;             PG8_WAIT_V(8); PG8_WAIT_L(0); PG8_BAR; PG8_MMA(0, 0, At, B0); PG8_MMA(0, 1, At, B1); PG8_BAR; PG8_SCHED;
;             PG8_LDA(At, 0, 1); PG8_STAGE(PG8_SB(0, 0), b2, voffB); PG8_STAGE(PG8_SB(0, 1), b2 + hstep, voffB); PG8_STAGE(PG8_SA(0, 0), a2, voffA);
.LBB0_881:
	s_ashr_i32 s49, s48, 31
	s_lshl_b64 s[36:37], s[48:49], 20
	s_add_u32 s50, s33, s36
	s_addc_u32 s51, s35, s37
	s_and_b64 s[36:37], s[12:13], exec
	s_cselect_b32 s15, s51, s19
	s_cselect_b32 s17, s50, s18
	s_ashr_i32 s47, s46, 31
	s_lshl_b64 s[36:37], s[46:47], 20
	s_add_u32 s52, s56, s36
	s_addc_u32 s53, s57, s37
	s_and_b64 s[36:37], s[12:13], exec
	s_cselect_b32 s47, s53, s21
	s_cselect_b32 s49, s52, s20
	s_add_u32 s18, s18, 0x80080
	s_addc_u32 s19, s19, 0
	s_add_u32 s76, s20, 0x100
	v_mov_b32_e32 v120, 0
	s_addc_u32 s77, s21, 0
	s_mov_b32 s78, -2
	s_cmp_lg_u64 s[30:31], 0
	s_cbranch_scc1 .Lsp2_lead
	s_setprio 1
.Lsp2_lead:
	ds_read_b128 v[128:131], v187
	ds_read_b128 v[132:135], v188
	ds_read_b128 v[136:139], v187 offset:2048
	ds_read_b128 v[140:143], v188 offset:2048
	ds_read_b128 v[168:171], v187 offset:16384
	ds_read_b128 v[172:175], v188 offset:16384
	ds_read_b128 v[176:179], v187 offset:18432
	ds_read_b128 v[194:197], v188 offset:18432
	s_add_u32 s20, s18, 0xfff80080
	s_addc_u32 s21, s19, -1
	s_cmp_eq_u32 s78, 28
	s_cselect_b32 s55, s15, s21
	s_cselect_b32 s54, s17, s20
	s_cselect_b32 s21, s47, s77
	s_cselect_b32 s20, s49, s76
	v_lshl_add_u64 v[180:181], s[18:19], 0, v[160:161]
	s_add_i32 m0, s60, 0xc000
	ds_read_b128 v[198:201], v189
	ds_read_b128 v[202:205], v242
	ds_read_b128 v[206:209], v189 offset:2048
	ds_read_b128 v[210:213], v242 offset:2048
	ds_read_b128 v[214:217], v189 offset:4096
	ds_read_b128 v[218:221], v242 offset:4096
	ds_read_b128 v[222:225], v189 offset:6144
	ds_read_b128 v[226:229], v242 offset:6144
	global_load_lds_dwordx4 v[180:181], off
	v_lshl_add_u64 v[180:181], s[18:19], 0, v[162:163]
	s_add_i32 m0, s60, 0xe000
	s_nop 0
	global_load_lds_dwordx4 v[180:181], off
	s_waitcnt vmcnt(8)
	s_waitcnt lgkmcnt(0)
	s_barrier
	s_waitcnt lgkmcnt(0)
	v_mfma_f32_16x16x32_bf16 v[120:123], v[128:131], v[198:201], 0
	v_mfma_f32_16x16x32_bf16 v[88:91], v[136:139], v[198:201], 0
	v_mfma_f32_16x16x32_bf16 v[116:119], v[128:131], v[206:209], 0
	v_mfma_f32_16x16x32_bf16 v[84:87], v[136:139], v[206:209], 0
	v_mfma_f32_16x16x32_bf16 v[112:115], v[128:131], v[214:217], 0
	v_mfma_f32_16x16x32_bf16 v[80:83], v[136:139], v[214:217], 0
	v_mfma_f32_16x16x32_bf16 v[100:103], v[128:131], v[222:225], 0
	v_mfma_f32_16x16x32_bf16 v[68:71], v[136:139], v[222:225], 0
	v_mfma_f32_16x16x32_bf16 v[120:123], v[132:135], v[202:205], v[120:123]
	v_mfma_f32_16x16x32_bf16 v[88:91], v[140:143], v[202:205], v[88:91]
	v_mfma_f32_16x16x32_bf16 v[116:119], v[132:135], v[210:213], v[116:119]
	v_mfma_f32_16x16x32_bf16 v[84:87], v[140:143], v[210:213], v[84:87]
	v_mfma_f32_16x16x32_bf16 v[112:115], v[132:135], v[218:221], v[112:115]
	v_mfma_f32_16x16x32_bf16 v[80:83], v[140:143], v[218:221], v[80:83]
	v_mfma_f32_16x16x32_bf16 v[100:103], v[132:135], v[226:229], v[100:103]
	v_mfma_f32_16x16x32_bf16 v[68:71], v[140:143], v[226:229], v[68:71]
	v_mfma_f32_16x16x32_bf16 v[124:127], v[168:171], v[198:201], 0
	v_mfma_f32_16x16x32_bf16 v[92:95], v[176:179], v[198:201], 0
	v_mfma_f32_16x16x32_bf16 v[108:111], v[168:171], v[206:209], 0
	v_mfma_f32_16x16x32_bf16 v[76:79], v[176:179], v[206:209], 0
	v_mfma_f32_16x16x32_bf16 v[104:107], v[168:171], v[214:217], 0
	v_mfma_f32_16x16x32_bf16 v[72:75], v[176:179], v[214:217], 0
	v_mfma_f32_16x16x32_bf16 v[96:99], v[168:171], v[222:225], 0
	v_mfma_f32_16x16x32_bf16 v[64:67], v[176:179], v[222:225], 0
	v_mfma_f32_16x16x32_bf16 v[124:127], v[172:175], v[202:205], v[124:127]
	v_mfma_f32_16x16x32_bf16 v[92:95], v[194:197], v[202:205], v[92:95]
	v_mfma_f32_16x16x32_bf16 v[108:111], v[172:175], v[210:213], v[108:111]
	v_mfma_f32_16x16x32_bf16 v[76:79], v[194:197], v[210:213], v[76:79]
	v_mfma_f32_16x16x32_bf16 v[104:107], v[172:175], v[218:221], v[104:107]
	v_mfma_f32_16x16x32_bf16 v[72:75], v[194:197], v[218:221], v[72:75]
	v_mfma_f32_16x16x32_bf16 v[96:99], v[172:175], v[226:229], v[96:99]
	v_mfma_f32_16x16x32_bf16 v[64:67], v[194:197], v[226:229], v[64:67]
	s_barrier
	s_add_i32 s36, s72, s59
	v_lshl_add_u64 v[180:181], s[20:21], 0, v[148:149]
	s_mov_b32 m0, s36
	ds_read_b128 v[198:201], v189 offset:16384
	ds_read_b128 v[202:205], v242 offset:16384
	ds_read_b128 v[206:209], v189 offset:18432
	ds_read_b128 v[210:213], v242 offset:18432
	ds_read_b128 v[214:217], v189 offset:20480
	ds_read_b128 v[218:221], v242 offset:20480
	ds_read_b128 v[222:225], v189 offset:22528
	ds_read_b128 v[226:229], v242 offset:22528
	global_load_lds_dwordx4 v[180:181], off
	s_add_i32 m0, s36, 0x2000
	s_add_u32 s36, s20, 0x80000
	v_lshl_add_u64 v[230:231], s[20:21], 0, v[152:153]
	s_addc_u32 s37, s21, 0
	s_add_i32 s79, s73, s59
	global_load_lds_dwordx4 v[230:231], off
	v_lshl_add_u64 v[232:233], s[36:37], 0, v[148:149]
	s_mov_b32 m0, s79
	v_lshl_add_u64 v[234:235], s[54:55], 0, v[150:151]
	global_load_lds_dwordx4 v[232:233], off
	v_lshl_add_u64 v[232:233], s[36:37], 0, v[152:153]
	s_add_i32 m0, s79, 0x2000
	s_nop 0
	global_load_lds_dwordx4 v[232:233], off
	v_lshl_add_u64 v[232:233], s[54:55], 0, v[146:147]
	s_mov_b32 m0, s60
	s_nop 0
	global_load_lds_dwordx4 v[232:233], off
	s_mov_b32 m0, s61
	s_nop 0
	global_load_lds_dwordx4 v[234:235], off
	s_waitcnt vmcnt(8)
	s_waitcnt lgkmcnt(0)
	s_barrier
; #define PG8_STAGE(bufoff, gbase, voff) do { _Pragma("unroll") for (int _i = 0; _i < 2; ++_i) \
;         __builtin_amdgcn_global_load_lds((const unsigned*)((const char*)(gbase) + (voff)[_i]), (PG8_LAS unsigned*)(lds + (bufoff) + ldsw + _i * 8192), 16, 0, 0); } while (0)
; #define PG8_LDA(dst, b, h) do { _Pragma("unroll") for (int m = 0; m < 4; ++m) _Pragma("unroll") for (int k = 0; k < 2; ++k) dst[m][k] = *(const PG8_LAS bf16x8*)(lds + PG8_SA(b, h) + aoff + m * 2048 + k * 1024); } while (0)
; #define PG8_LDB(dst, b, h) do { _Pragma("unroll") for (int n = 0; n < 2; ++n) _Pragma("unroll") for (int k = 0; k < 2; ++k) dst[n][k] = *(const PG8_LAS bf16x8*)(lds + PG8_SB(b, h) + boff + n * 2048 + k * 1024); } while (0)
; #define PG8_MMA(ai, bj, At, Bt) do { __builtin_amdgcn_s_setprio(1); _Pragma("unroll") for (int m = 0; m < 4; ++m) _Pragma("unroll") for (int n = 0; n < 2; ++n) _Pragma("unroll") for (int k = 0; k < 2; ++k) \
;         acc[ai][bj][m][n] = __builtin_amdgcn_mfma_f32_16x16x32_bf16(Bt[n][k], At[m][k], acc[ai][bj][m][n], 0, 0, 0); __builtin_amdgcn_s_setprio(0); } while (0)
; #define PG8_WAIT_V(n) asm volatile("s_waitcnt vmcnt(" #n ")" ::: "memory")
; #define PG8_WAIT_L(n) asm volatile("s_waitcnt lgkmcnt(" #n ")" ::: "memory")
; #define PG8_BAR __builtin_amdgcn_s_barrier()
; #define PG8_SCHED __builtin_amdgcn_sched_barrier(0)
; template <class Epi, class Sched, bool ALIGN_EPI = false, bool SP2 = false>
; __device__ __forceinline__ void gemm_phase(PG8_LAS unsigned char* lds, const Gemm g, const Sched& S, const Epi& E) {
;     ...
;             PG8_WAIT_V(8); PG8_WAIT_L(0); PG8_BAR; PG8_MMA(1, 0, At, B0); PG8_MMA(1, 1, At, B1); PG8_BAR; PG8_SCHED;
;             PG8_LDB(B0, 1, 0); PG8_LDB(B1, 1, 1); PG8_SCHED; PG8_LDA(At, 1, 0); PG8_STAGE(PG8_SA(0, 1), a2 + hstep, voffA);
;             PG8_WAIT_V(8); PG8_WAIT_L(0); PG8_BAR; PG8_MMA(0, 0, At, B0); PG8_MMA(0, 1, At, B1); PG8_BAR; PG8_SCHED;
	s_waitcnt lgkmcnt(0)
	v_mfma_f32_16x16x32_bf16 v[60:63], v[128:131], v[198:201], 0
	v_mfma_f32_16x16x32_bf16 v[28:31], v[136:139], v[198:201], 0
	v_mfma_f32_16x16x32_bf16 v[52:55], v[128:131], v[206:209], 0
	v_mfma_f32_16x16x32_bf16 v[20:23], v[136:139], v[206:209], 0
	v_mfma_f32_16x16x32_bf16 v[48:51], v[128:131], v[214:217], 0
	v_mfma_f32_16x16x32_bf16 v[16:19], v[136:139], v[214:217], 0
	v_mfma_f32_16x16x32_bf16 v[44:47], v[128:131], v[222:225], 0
	v_mfma_f32_16x16x32_bf16 v[8:11], v[136:139], v[222:225], 0
	v_mfma_f32_16x16x32_bf16 v[60:63], v[132:135], v[202:205], v[60:63]
	v_mfma_f32_16x16x32_bf16 v[28:31], v[140:143], v[202:205], v[28:31]
	v_mfma_f32_16x16x32_bf16 v[52:55], v[132:135], v[210:213], v[52:55]
	v_mfma_f32_16x16x32_bf16 v[20:23], v[140:143], v[210:213], v[20:23]
	v_mfma_f32_16x16x32_bf16 v[48:51], v[132:135], v[218:221], v[48:51]
	v_mfma_f32_16x16x32_bf16 v[16:19], v[140:143], v[218:221], v[16:19]
	v_mfma_f32_16x16x32_bf16 v[44:47], v[132:135], v[226:229], v[44:47]
	v_mfma_f32_16x16x32_bf16 v[8:11], v[140:143], v[226:229], v[8:11]
	v_mfma_f32_16x16x32_bf16 v[56:59], v[168:171], v[198:201], 0
	v_mfma_f32_16x16x32_bf16 v[24:27], v[176:179], v[198:201], 0
	v_mfma_f32_16x16x32_bf16 v[40:43], v[168:171], v[206:209], 0
	v_mfma_f32_16x16x32_bf16 v[12:15], v[176:179], v[206:209], 0
	v_mfma_f32_16x16x32_bf16 v[36:39], v[168:171], v[214:217], 0
	v_mfma_f32_16x16x32_bf16 v[4:7], v[176:179], v[214:217], 0
	v_mfma_f32_16x16x32_bf16 v[32:35], v[168:171], v[222:225], 0
	v_mfma_f32_16x16x32_bf16 v[0:3], v[176:179], v[222:225], 0
	v_mfma_f32_16x16x32_bf16 v[56:59], v[172:175], v[202:205], v[56:59]
	v_mfma_f32_16x16x32_bf16 v[24:27], v[194:197], v[202:205], v[24:27]
	v_mfma_f32_16x16x32_bf16 v[40:43], v[172:175], v[210:213], v[40:43]
	v_mfma_f32_16x16x32_bf16 v[12:15], v[194:197], v[210:213], v[12:15]
	v_mfma_f32_16x16x32_bf16 v[36:39], v[172:175], v[218:221], v[36:39]
	v_mfma_f32_16x16x32_bf16 v[4:7], v[194:197], v[218:221], v[4:7]
	v_mfma_f32_16x16x32_bf16 v[32:35], v[172:175], v[226:229], v[32:35]
	v_mfma_f32_16x16x32_bf16 v[0:3], v[194:197], v[226:229], v[0:3]
	s_barrier
	s_add_i32 s79, 0, 0x18000
	s_add_i32 s80, 0, 0x1c000
	v_add_u32_e32 v140, s79, v182
	v_add_u32_e32 v154, s80, v182
	ds_read_b128 v[128:131], v187 offset:32768
	ds_read_b128 v[132:135], v188 offset:32768
	ds_read_b128 v[136:139], v187 offset:34816
	ds_read_b128 v[140:143], v188 offset:34816
	ds_read_b128 v[168:171], v187 offset:49152
	ds_read_b128 v[172:175], v188 offset:49152
	ds_read_b128 v[176:179], v187 offset:51200
	ds_read_b128 v[194:197], v188 offset:51200
	s_add_u32 s36, s54, 0x80000
	s_addc_u32 s37, s55, 0
	s_mov_b32 m0, s62
	v_lshl_add_u64 v[236:237], s[36:37], 0, v[146:147]
	ds_read_b128 v[198:201], v189 offset:32768
	ds_read_b128 v[202:205], v242 offset:32768
	ds_read_b128 v[206:209], v189 offset:34816
	ds_read_b128 v[210:213], v242 offset:34816
	ds_read_b128 v[214:217], v189 offset:36864
	ds_read_b128 v[218:221], v242 offset:36864
	ds_read_b128 v[222:225], v189 offset:38912
	ds_read_b128 v[226:229], v242 offset:38912
	global_load_lds_dwordx4 v[236:237], off
	v_lshl_add_u64 v[236:237], s[36:37], 0, v[150:151]
	s_mov_b32 m0, s63
	s_nop 0
	global_load_lds_dwordx4 v[236:237], off
	s_waitcnt vmcnt(8)
	s_waitcnt lgkmcnt(0)
	s_barrier
	s_waitcnt lgkmcnt(0)
	v_mfma_f32_16x16x32_bf16 v[120:123], v[128:131], v[198:201], v[120:123]
	v_mfma_f32_16x16x32_bf16 v[88:91], v[136:139], v[198:201], v[88:91]
	v_mfma_f32_16x16x32_bf16 v[116:119], v[128:131], v[206:209], v[116:119]
	v_mfma_f32_16x16x32_bf16 v[84:87], v[136:139], v[206:209], v[84:87]
	v_mfma_f32_16x16x32_bf16 v[112:115], v[128:131], v[214:217], v[112:115]
	v_mfma_f32_16x16x32_bf16 v[80:83], v[136:139], v[214:217], v[80:83]
	v_mfma_f32_16x16x32_bf16 v[100:103], v[128:131], v[222:225], v[100:103]
	v_mfma_f32_16x16x32_bf16 v[68:71], v[136:139], v[222:225], v[68:71]
	v_mfma_f32_16x16x32_bf16 v[120:123], v[132:135], v[202:205], v[120:123]
	v_mfma_f32_16x16x32_bf16 v[88:91], v[140:143], v[202:205], v[88:91]
	v_mfma_f32_16x16x32_bf16 v[116:119], v[132:135], v[210:213], v[116:119]
	v_mfma_f32_16x16x32_bf16 v[84:87], v[140:143], v[210:213], v[84:87]
	v_mfma_f32_16x16x32_bf16 v[112:115], v[132:135], v[218:221], v[112:115]
	v_mfma_f32_16x16x32_bf16 v[80:83], v[140:143], v[218:221], v[80:83]
	v_mfma_f32_16x16x32_bf16 v[100:103], v[132:135], v[226:229], v[100:103]
	v_mfma_f32_16x16x32_bf16 v[68:71], v[140:143], v[226:229], v[68:71]
	v_mfma_f32_16x16x32_bf16 v[124:127], v[168:171], v[198:201], v[124:127]
	v_mfma_f32_16x16x32_bf16 v[92:95], v[176:179], v[198:201], v[92:95]
	v_mfma_f32_16x16x32_bf16 v[108:111], v[168:171], v[206:209], v[108:111]
	v_mfma_f32_16x16x32_bf16 v[76:79], v[176:179], v[206:209], v[76:79]
	v_mfma_f32_16x16x32_bf16 v[104:107], v[168:171], v[214:217], v[104:107]
	v_mfma_f32_16x16x32_bf16 v[72:75], v[176:179], v[214:217], v[72:75]
	v_mfma_f32_16x16x32_bf16 v[96:99], v[168:171], v[222:225], v[96:99]
	v_mfma_f32_16x16x32_bf16 v[64:67], v[176:179], v[222:225], v[64:67]
	v_mfma_f32_16x16x32_bf16 v[124:127], v[172:175], v[202:205], v[124:127]
	v_mfma_f32_16x16x32_bf16 v[92:95], v[194:197], v[202:205], v[92:95]
	v_mfma_f32_16x16x32_bf16 v[108:111], v[172:175], v[210:213], v[108:111]
	v_mfma_f32_16x16x32_bf16 v[76:79], v[194:197], v[210:213], v[76:79]
	v_mfma_f32_16x16x32_bf16 v[104:107], v[172:175], v[218:221], v[104:107]
	v_mfma_f32_16x16x32_bf16 v[72:75], v[194:197], v[218:221], v[72:75]
	v_mfma_f32_16x16x32_bf16 v[96:99], v[172:175], v[226:229], v[96:99]
	v_mfma_f32_16x16x32_bf16 v[64:67], v[194:197], v[226:229], v[64:67]
	s_barrier
; #define PG8_STAGE(bufoff, gbase, voff) do { _Pragma("unroll") for (int _i = 0; _i < 2; ++_i) \
;         __builtin_amdgcn_global_load_lds((const unsigned*)((const char*)(gbase) + (voff)[_i]), (PG8_LAS unsigned*)(lds + (bufoff) + ldsw + _i * 8192), 16, 0, 0); } while (0)
; #define PG8_LDA(dst, b, h) do { _Pragma("unroll") for (int m = 0; m < 4; ++m) _Pragma("unroll") for (int k = 0; k < 2; ++k) dst[m][k] = *(const PG8_LAS bf16x8*)(lds + PG8_SA(b, h) + aoff + m * 2048 + k * 1024); } while (0)
; #define PG8_LDB(dst, b, h) do { _Pragma("unroll") for (int n = 0; n < 2; ++n) _Pragma("unroll") for (int k = 0; k < 2; ++k) dst[n][k] = *(const PG8_LAS bf16x8*)(lds + PG8_SB(b, h) + boff + n * 2048 + k * 1024); } while (0)
; #define PG8_MMA(ai, bj, At, Bt) do { __builtin_amdgcn_s_setprio(1); _Pragma("unroll") for (int m = 0; m < 4; ++m) _Pragma("unroll") for (int n = 0; n < 2; ++n) _Pragma("unroll") for (int k = 0; k < 2; ++k) \
;         acc[ai][bj][m][n] = __builtin_amdgcn_mfma_f32_16x16x32_bf16(Bt[n][k], At[m][k], acc[ai][bj][m][n], 0, 0, 0); __builtin_amdgcn_s_setprio(0); } while (0)
; #define PG8_WAIT_V(n) asm volatile("s_waitcnt vmcnt(" #n ")" ::: "memory")
; #define PG8_WAIT_L(n) asm volatile("s_waitcnt lgkmcnt(" #n ")" ::: "memory")
; #define PG8_BAR __builtin_amdgcn_s_barrier()
; #define PG8_SCHED __builtin_amdgcn_sched_barrier(0)
; template <class Epi, class Sched, bool ALIGN_EPI = false, bool SP2 = false>
; __device__ __forceinline__ void gemm_phase(PG8_LAS unsigned char* lds, const Gemm g, const Sched& S, const Epi& E) {
;     ...
;             PG8_LDB(B0, 0, 0); PG8_LDB(B1, 0, 1); PG8_SCHED; PG8_LDA(At, 0, 0); PG8_STAGE(PG8_SA(1, 1), a1 + hstep, voffA);
;             PG8_WAIT_V(8); PG8_WAIT_L(0); PG8_BAR; PG8_MMA(0, 0, At, B0); PG8_MMA(0, 1, At, B1); PG8_BAR; PG8_SCHED;
;     ...
;             PG8_LDA(At, 1, 1); PG8_STAGE(PG8_SB(1, 0), b3, voffB); PG8_STAGE(PG8_SB(1, 1), b3 + hstep, voffB); PG8_STAGE(PG8_SA(1, 0), a3, voffA);
;             PG8_WAIT_V(8); PG8_WAIT_L(0); PG8_BAR; PG8_MMA(1, 0, At, B0); PG8_MMA(1, 1, At, B1); PG8_BAR; PG8_SCHED;
	s_add_i32 s36, s79, s59
	v_lshl_add_u64 v[180:181], v[180:181], 0, s[28:29]
	s_mov_b32 m0, s36
	ds_read_b128 v[198:201], v189 offset:49152
	ds_read_b128 v[202:205], v242 offset:49152
	ds_read_b128 v[206:209], v189 offset:51200
	ds_read_b128 v[210:213], v242 offset:51200
	ds_read_b128 v[214:217], v189 offset:53248
	ds_read_b128 v[218:221], v242 offset:53248
	ds_read_b128 v[222:225], v189 offset:55296
	ds_read_b128 v[226:229], v242 offset:55296
	global_load_lds_dwordx4 v[180:181], off
	s_add_i32 m0, s36, 0x2000
	s_add_u32 s20, s20, 0x80080
	v_lshl_add_u64 v[180:181], v[230:231], 0, s[28:29]
	s_addc_u32 s21, s21, 0
	s_add_i32 s36, s80, s59
	global_load_lds_dwordx4 v[180:181], off
	v_lshl_add_u64 v[180:181], s[20:21], 0, v[148:149]
	s_mov_b32 m0, s36
	s_nop 0
	global_load_lds_dwordx4 v[180:181], off
	v_lshl_add_u64 v[180:181], s[20:21], 0, v[152:153]
	s_add_i32 m0, s36, 0x2000
	s_nop 0
	global_load_lds_dwordx4 v[180:181], off
	v_lshl_add_u64 v[180:181], v[232:233], 0, s[28:29]
	s_mov_b32 m0, s67
	s_nop 0
	global_load_lds_dwordx4 v[180:181], off
	v_lshl_add_u64 v[180:181], v[234:235], 0, s[28:29]
	s_mov_b32 m0, s68
	s_nop 0
	global_load_lds_dwordx4 v[180:181], off
	s_waitcnt vmcnt(8)
	s_waitcnt lgkmcnt(0)
	s_barrier
	s_waitcnt lgkmcnt(0)
	v_mfma_f32_16x16x32_bf16 v[60:63], v[128:131], v[198:201], v[60:63]
	v_mfma_f32_16x16x32_bf16 v[28:31], v[136:139], v[198:201], v[28:31]
	v_mfma_f32_16x16x32_bf16 v[52:55], v[128:131], v[206:209], v[52:55]
	v_mfma_f32_16x16x32_bf16 v[20:23], v[136:139], v[206:209], v[20:23]
	v_mfma_f32_16x16x32_bf16 v[48:51], v[128:131], v[214:217], v[48:51]
	v_mfma_f32_16x16x32_bf16 v[16:19], v[136:139], v[214:217], v[16:19]
	v_mfma_f32_16x16x32_bf16 v[44:47], v[128:131], v[222:225], v[44:47]
	v_mfma_f32_16x16x32_bf16 v[8:11], v[136:139], v[222:225], v[8:11]
	v_mfma_f32_16x16x32_bf16 v[60:63], v[132:135], v[202:205], v[60:63]
	v_mfma_f32_16x16x32_bf16 v[28:31], v[140:143], v[202:205], v[28:31]
	v_mfma_f32_16x16x32_bf16 v[52:55], v[132:135], v[210:213], v[52:55]
	v_mfma_f32_16x16x32_bf16 v[20:23], v[140:143], v[210:213], v[20:23]
	v_mfma_f32_16x16x32_bf16 v[48:51], v[132:135], v[218:221], v[48:51]
	v_mfma_f32_16x16x32_bf16 v[16:19], v[140:143], v[218:221], v[16:19]
	v_mfma_f32_16x16x32_bf16 v[44:47], v[132:135], v[226:229], v[44:47]
	v_mfma_f32_16x16x32_bf16 v[8:11], v[140:143], v[226:229], v[8:11]
	v_mfma_f32_16x16x32_bf16 v[56:59], v[168:171], v[198:201], v[56:59]
	v_mfma_f32_16x16x32_bf16 v[24:27], v[176:179], v[198:201], v[24:27]
	v_mfma_f32_16x16x32_bf16 v[40:43], v[168:171], v[206:209], v[40:43]
	v_mfma_f32_16x16x32_bf16 v[12:15], v[176:179], v[206:209], v[12:15]
	v_mfma_f32_16x16x32_bf16 v[36:39], v[168:171], v[214:217], v[36:39]
	v_mfma_f32_16x16x32_bf16 v[4:7], v[176:179], v[214:217], v[4:7]
	v_mfma_f32_16x16x32_bf16 v[32:35], v[168:171], v[222:225], v[32:35]
	v_mfma_f32_16x16x32_bf16 v[0:3], v[176:179], v[222:225], v[0:3]
	v_mfma_f32_16x16x32_bf16 v[56:59], v[172:175], v[202:205], v[56:59]
	v_mfma_f32_16x16x32_bf16 v[24:27], v[194:197], v[202:205], v[24:27]
	v_mfma_f32_16x16x32_bf16 v[40:43], v[172:175], v[210:213], v[40:43]
	v_mfma_f32_16x16x32_bf16 v[12:15], v[194:197], v[210:213], v[12:15]
	v_mfma_f32_16x16x32_bf16 v[36:39], v[172:175], v[218:221], v[36:39]
	v_mfma_f32_16x16x32_bf16 v[4:7], v[194:197], v[218:221], v[4:7]
	v_mfma_f32_16x16x32_bf16 v[32:35], v[172:175], v[226:229], v[32:35]
	v_mfma_f32_16x16x32_bf16 v[0:3], v[194:197], v[226:229], v[0:3]
	s_barrier
	s_add_i32 s78, s78, 2
	s_add_u32 s18, s18, 0x100
	s_addc_u32 s19, s19, 0
	s_add_u32 s76, s76, 0x100
	s_addc_u32 s77, s77, 0
.LBB0_882:
	ds_read_b128 v[128:131], v187
	ds_read_b128 v[132:135], v188
	ds_read_b128 v[136:139], v187 offset:2048
	ds_read_b128 v[140:143], v188 offset:2048
	ds_read_b128 v[168:171], v187 offset:16384
	ds_read_b128 v[172:175], v188 offset:16384
	ds_read_b128 v[176:179], v187 offset:18432
	ds_read_b128 v[194:197], v188 offset:18432
	s_add_u32 s20, s18, 0xfff80080
	s_addc_u32 s21, s19, -1
	s_cmp_eq_u32 s78, 28
	s_cselect_b32 s55, s15, s21
	s_cselect_b32 s54, s17, s20
	s_cselect_b32 s21, s47, s77
	s_cselect_b32 s20, s49, s76
	v_lshl_add_u64 v[180:181], s[18:19], 0, v[160:161]
	s_add_i32 m0, s60, 0xc000
	ds_read_b128 v[198:201], v189
	ds_read_b128 v[202:205], v242
	ds_read_b128 v[206:209], v189 offset:2048
	ds_read_b128 v[210:213], v242 offset:2048
	ds_read_b128 v[214:217], v189 offset:4096
	ds_read_b128 v[218:221], v242 offset:4096
	ds_read_b128 v[222:225], v189 offset:6144
	ds_read_b128 v[226:229], v242 offset:6144
	global_load_lds_dwordx4 v[180:181], off
	v_lshl_add_u64 v[180:181], s[18:19], 0, v[162:163]
	s_add_i32 m0, s60, 0xe000
	s_nop 0
	global_load_lds_dwordx4 v[180:181], off
	s_waitcnt vmcnt(8)
	s_waitcnt lgkmcnt(0)
	s_barrier
; #define PG8_STAGE(bufoff, gbase, voff) do { _Pragma("unroll") for (int _i = 0; _i < 2; ++_i) \
;         __builtin_amdgcn_global_load_lds((const unsigned*)((const char*)(gbase) + (voff)[_i]), (PG8_LAS unsigned*)(lds + (bufoff) + ldsw + _i * 8192), 16, 0, 0); } while (0)
; #define PG8_LDA(dst, b, h) do { _Pragma("unroll") for (int m = 0; m < 4; ++m) _Pragma("unroll") for (int k = 0; k < 2; ++k) dst[m][k] = *(const PG8_LAS bf16x8*)(lds + PG8_SA(b, h) + aoff + m * 2048 + k * 1024); } while (0)
; #define PG8_MMA(ai, bj, At, Bt) do { __builtin_amdgcn_s_setprio(1); _Pragma("unroll") for (int m = 0; m < 4; ++m) _Pragma("unroll") for (int n = 0; n < 2; ++n) _Pragma("unroll") for (int k = 0; k < 2; ++k) \
;         acc[ai][bj][m][n] = __builtin_amdgcn_mfma_f32_16x16x32_bf16(Bt[n][k], At[m][k], acc[ai][bj][m][n], 0, 0, 0); __builtin_amdgcn_s_setprio(0); } while (0)
; #define PG8_WAIT_V(n) asm volatile("s_waitcnt vmcnt(" #n ")" ::: "memory")
; #define PG8_WAIT_L(n) asm volatile("s_waitcnt lgkmcnt(" #n ")" ::: "memory")
; #define PG8_BAR __builtin_amdgcn_s_barrier()
; #define PG8_SCHED __builtin_amdgcn_sched_barrier(0)
; template <class Epi, class Sched, bool ALIGN_EPI = false, bool SP2 = false>
; __device__ __forceinline__ void gemm_phase(PG8_LAS unsigned char* lds, const Gemm g, const Sched& S, const Epi& E) {
;     ...
;             PG8_WAIT_V(8); PG8_WAIT_L(0); PG8_BAR; PG8_MMA(0, 0, At, B0); PG8_MMA(0, 1, At, B1); PG8_BAR; PG8_SCHED;
;             PG8_LDA(At, 0, 1); PG8_STAGE(PG8_SB(0, 0), b2, voffB); PG8_STAGE(PG8_SB(0, 1), b2 + hstep, voffB); PG8_STAGE(PG8_SA(0, 0), a2, voffA);
;             PG8_WAIT_V(8); PG8_WAIT_L(0); PG8_BAR; PG8_MMA(1, 0, At, B0); PG8_MMA(1, 1, At, B1); PG8_BAR; PG8_SCHED;
	s_waitcnt lgkmcnt(0)
	v_mfma_f32_16x16x32_bf16 v[120:123], v[128:131], v[198:201], v[120:123]
	v_mfma_f32_16x16x32_bf16 v[88:91], v[136:139], v[198:201], v[88:91]
	v_mfma_f32_16x16x32_bf16 v[116:119], v[128:131], v[206:209], v[116:119]
	v_mfma_f32_16x16x32_bf16 v[84:87], v[136:139], v[206:209], v[84:87]
	v_mfma_f32_16x16x32_bf16 v[112:115], v[128:131], v[214:217], v[112:115]
	v_mfma_f32_16x16x32_bf16 v[80:83], v[136:139], v[214:217], v[80:83]
	v_mfma_f32_16x16x32_bf16 v[100:103], v[128:131], v[222:225], v[100:103]
	v_mfma_f32_16x16x32_bf16 v[68:71], v[136:139], v[222:225], v[68:71]
	v_mfma_f32_16x16x32_bf16 v[120:123], v[132:135], v[202:205], v[120:123]
	v_mfma_f32_16x16x32_bf16 v[88:91], v[140:143], v[202:205], v[88:91]
	v_mfma_f32_16x16x32_bf16 v[116:119], v[132:135], v[210:213], v[116:119]
	v_mfma_f32_16x16x32_bf16 v[84:87], v[140:143], v[210:213], v[84:87]
	v_mfma_f32_16x16x32_bf16 v[112:115], v[132:135], v[218:221], v[112:115]
	v_mfma_f32_16x16x32_bf16 v[80:83], v[140:143], v[218:221], v[80:83]
	v_mfma_f32_16x16x32_bf16 v[100:103], v[132:135], v[226:229], v[100:103]
	v_mfma_f32_16x16x32_bf16 v[68:71], v[140:143], v[226:229], v[68:71]
	v_mfma_f32_16x16x32_bf16 v[124:127], v[168:171], v[198:201], v[124:127]
	v_mfma_f32_16x16x32_bf16 v[92:95], v[176:179], v[198:201], v[92:95]
	v_mfma_f32_16x16x32_bf16 v[108:111], v[168:171], v[206:209], v[108:111]
	v_mfma_f32_16x16x32_bf16 v[76:79], v[176:179], v[206:209], v[76:79]
	v_mfma_f32_16x16x32_bf16 v[104:107], v[168:171], v[214:217], v[104:107]
	v_mfma_f32_16x16x32_bf16 v[72:75], v[176:179], v[214:217], v[72:75]
	v_mfma_f32_16x16x32_bf16 v[96:99], v[168:171], v[222:225], v[96:99]
	v_mfma_f32_16x16x32_bf16 v[64:67], v[176:179], v[222:225], v[64:67]
	v_mfma_f32_16x16x32_bf16 v[124:127], v[172:175], v[202:205], v[124:127]
	v_mfma_f32_16x16x32_bf16 v[92:95], v[194:197], v[202:205], v[92:95]
	v_mfma_f32_16x16x32_bf16 v[108:111], v[172:175], v[210:213], v[108:111]
	v_mfma_f32_16x16x32_bf16 v[76:79], v[194:197], v[210:213], v[76:79]
	v_mfma_f32_16x16x32_bf16 v[104:107], v[172:175], v[218:221], v[104:107]
	v_mfma_f32_16x16x32_bf16 v[72:75], v[194:197], v[218:221], v[72:75]
	v_mfma_f32_16x16x32_bf16 v[96:99], v[172:175], v[226:229], v[96:99]
	v_mfma_f32_16x16x32_bf16 v[64:67], v[194:197], v[226:229], v[64:67]
	s_barrier
	s_add_i32 s36, s72, s59
	v_lshl_add_u64 v[180:181], s[20:21], 0, v[148:149]
	s_mov_b32 m0, s36
	ds_read_b128 v[198:201], v189 offset:16384
	ds_read_b128 v[202:205], v242 offset:16384
	ds_read_b128 v[206:209], v189 offset:18432
	ds_read_b128 v[210:213], v242 offset:18432
	ds_read_b128 v[214:217], v189 offset:20480
	ds_read_b128 v[218:221], v242 offset:20480
	ds_read_b128 v[222:225], v189 offset:22528
	ds_read_b128 v[226:229], v242 offset:22528
	global_load_lds_dwordx4 v[180:181], off
	s_add_i32 m0, s36, 0x2000
	s_add_u32 s36, s20, 0x80000
	v_lshl_add_u64 v[230:231], s[20:21], 0, v[152:153]
	s_addc_u32 s37, s21, 0
	s_add_i32 s79, s73, s59
	global_load_lds_dwordx4 v[230:231], off
	v_lshl_add_u64 v[232:233], s[36:37], 0, v[148:149]
	s_mov_b32 m0, s79
	v_lshl_add_u64 v[234:235], s[54:55], 0, v[150:151]
	global_load_lds_dwordx4 v[232:233], off
	v_lshl_add_u64 v[232:233], s[36:37], 0, v[152:153]
	s_add_i32 m0, s79, 0x2000
	s_nop 0
	global_load_lds_dwordx4 v[232:233], off
	v_lshl_add_u64 v[232:233], s[54:55], 0, v[146:147]
	s_mov_b32 m0, s60
	s_nop 0
	global_load_lds_dwordx4 v[232:233], off
	s_mov_b32 m0, s61
	s_nop 0
	global_load_lds_dwordx4 v[234:235], off
	s_waitcnt vmcnt(8)
	s_waitcnt lgkmcnt(0)
	s_barrier
	s_waitcnt lgkmcnt(0)
	v_mfma_f32_16x16x32_bf16 v[60:63], v[128:131], v[198:201], v[60:63]
	v_mfma_f32_16x16x32_bf16 v[28:31], v[136:139], v[198:201], v[28:31]
	v_mfma_f32_16x16x32_bf16 v[52:55], v[128:131], v[206:209], v[52:55]
	v_mfma_f32_16x16x32_bf16 v[20:23], v[136:139], v[206:209], v[20:23]
	v_mfma_f32_16x16x32_bf16 v[48:51], v[128:131], v[214:217], v[48:51]
	v_mfma_f32_16x16x32_bf16 v[16:19], v[136:139], v[214:217], v[16:19]
	v_mfma_f32_16x16x32_bf16 v[44:47], v[128:131], v[222:225], v[44:47]
	v_mfma_f32_16x16x32_bf16 v[8:11], v[136:139], v[222:225], v[8:11]
	v_mfma_f32_16x16x32_bf16 v[60:63], v[132:135], v[202:205], v[60:63]
	v_mfma_f32_16x16x32_bf16 v[28:31], v[140:143], v[202:205], v[28:31]
	v_mfma_f32_16x16x32_bf16 v[52:55], v[132:135], v[210:213], v[52:55]
	v_mfma_f32_16x16x32_bf16 v[20:23], v[140:143], v[210:213], v[20:23]
	v_mfma_f32_16x16x32_bf16 v[48:51], v[132:135], v[218:221], v[48:51]
	v_mfma_f32_16x16x32_bf16 v[16:19], v[140:143], v[218:221], v[16:19]
	v_mfma_f32_16x16x32_bf16 v[44:47], v[132:135], v[226:229], v[44:47]
	v_mfma_f32_16x16x32_bf16 v[8:11], v[140:143], v[226:229], v[8:11]
	v_mfma_f32_16x16x32_bf16 v[56:59], v[168:171], v[198:201], v[56:59]
	v_mfma_f32_16x16x32_bf16 v[24:27], v[176:179], v[198:201], v[24:27]
	v_mfma_f32_16x16x32_bf16 v[40:43], v[168:171], v[206:209], v[40:43]
	v_mfma_f32_16x16x32_bf16 v[12:15], v[176:179], v[206:209], v[12:15]
	v_mfma_f32_16x16x32_bf16 v[36:39], v[168:171], v[214:217], v[36:39]
	v_mfma_f32_16x16x32_bf16 v[4:7], v[176:179], v[214:217], v[4:7]
	v_mfma_f32_16x16x32_bf16 v[32:35], v[168:171], v[222:225], v[32:35]
	v_mfma_f32_16x16x32_bf16 v[0:3], v[176:179], v[222:225], v[0:3]
	v_mfma_f32_16x16x32_bf16 v[56:59], v[172:175], v[202:205], v[56:59]
	v_mfma_f32_16x16x32_bf16 v[24:27], v[194:197], v[202:205], v[24:27]
	v_mfma_f32_16x16x32_bf16 v[40:43], v[172:175], v[210:213], v[40:43]
	v_mfma_f32_16x16x32_bf16 v[12:15], v[194:197], v[210:213], v[12:15]
	v_mfma_f32_16x16x32_bf16 v[36:39], v[172:175], v[218:221], v[36:39]
	v_mfma_f32_16x16x32_bf16 v[4:7], v[194:197], v[218:221], v[4:7]
	v_mfma_f32_16x16x32_bf16 v[32:35], v[172:175], v[226:229], v[32:35]
	v_mfma_f32_16x16x32_bf16 v[0:3], v[194:197], v[226:229], v[0:3]
	s_barrier
; #define PG8_STAGE(bufoff, gbase, voff) do { _Pragma("unroll") for (int _i = 0; _i < 2; ++_i) \
;         __builtin_amdgcn_global_load_lds((const unsigned*)((const char*)(gbase) + (voff)[_i]), (PG8_LAS unsigned*)(lds + (bufoff) + ldsw + _i * 8192), 16, 0, 0); } while (0)
; #define PG8_LDA(dst, b, h) do { _Pragma("unroll") for (int m = 0; m < 4; ++m) _Pragma("unroll") for (int k = 0; k < 2; ++k) dst[m][k] = *(const PG8_LAS bf16x8*)(lds + PG8_SA(b, h) + aoff + m * 2048 + k * 1024); } while (0)
; #define PG8_LDB(dst, b, h) do { _Pragma("unroll") for (int n = 0; n < 2; ++n) _Pragma("unroll") for (int k = 0; k < 2; ++k) dst[n][k] = *(const PG8_LAS bf16x8*)(lds + PG8_SB(b, h) + boff + n * 2048 + k * 1024); } while (0)
; #define PG8_MMA(ai, bj, At, Bt) do { __builtin_amdgcn_s_setprio(1); _Pragma("unroll") for (int m = 0; m < 4; ++m) _Pragma("unroll") for (int n = 0; n < 2; ++n) _Pragma("unroll") for (int k = 0; k < 2; ++k) \
;         acc[ai][bj][m][n] = __builtin_amdgcn_mfma_f32_16x16x32_bf16(Bt[n][k], At[m][k], acc[ai][bj][m][n], 0, 0, 0); __builtin_amdgcn_s_setprio(0); } while (0)
; #define PG8_WAIT_V(n) asm volatile("s_waitcnt vmcnt(" #n ")" ::: "memory")
; #define PG8_WAIT_L(n) asm volatile("s_waitcnt lgkmcnt(" #n ")" ::: "memory")
; #define PG8_BAR __builtin_amdgcn_s_barrier()
; #define PG8_SCHED __builtin_amdgcn_sched_barrier(0)
; template <class Epi, class Sched, bool ALIGN_EPI = false, bool SP2 = false>
; __device__ __forceinline__ void gemm_phase(PG8_LAS unsigned char* lds, const Gemm g, const Sched& S, const Epi& E) {
;     ...
;             PG8_LDB(B0, 1, 0); PG8_LDB(B1, 1, 1); PG8_SCHED; PG8_LDA(At, 1, 0); PG8_STAGE(PG8_SA(0, 1), a2 + hstep, voffA);
;             PG8_WAIT_V(8); PG8_WAIT_L(0); PG8_BAR; PG8_MMA(0, 0, At, B0); PG8_MMA(0, 1, At, B1); PG8_BAR; PG8_SCHED;
	s_add_i32 s79, 0, 0x18000
	s_add_i32 s80, 0, 0x1c000
	v_add_u32_e32 v140, s79, v182
	v_add_u32_e32 v154, s80, v182
	ds_read_b128 v[128:131], v187 offset:32768
	ds_read_b128 v[132:135], v188 offset:32768
	ds_read_b128 v[136:139], v187 offset:34816
	ds_read_b128 v[140:143], v188 offset:34816
	ds_read_b128 v[168:171], v187 offset:49152
	ds_read_b128 v[172:175], v188 offset:49152
	ds_read_b128 v[176:179], v187 offset:51200
	ds_read_b128 v[194:197], v188 offset:51200
	s_add_u32 s36, s54, 0x80000
	s_addc_u32 s37, s55, 0
	s_mov_b32 m0, s62
	v_lshl_add_u64 v[236:237], s[36:37], 0, v[146:147]
	ds_read_b128 v[198:201], v189 offset:32768
	ds_read_b128 v[202:205], v242 offset:32768
	ds_read_b128 v[206:209], v189 offset:34816
	ds_read_b128 v[210:213], v242 offset:34816
	ds_read_b128 v[214:217], v189 offset:36864
	ds_read_b128 v[218:221], v242 offset:36864
	ds_read_b128 v[222:225], v189 offset:38912
	ds_read_b128 v[226:229], v242 offset:38912
	global_load_lds_dwordx4 v[236:237], off
	v_lshl_add_u64 v[236:237], s[36:37], 0, v[150:151]
	s_mov_b32 m0, s63
	s_nop 0
	global_load_lds_dwordx4 v[236:237], off
	s_waitcnt vmcnt(8)
	s_waitcnt lgkmcnt(0)
	s_barrier
	s_waitcnt lgkmcnt(0)
	v_mfma_f32_16x16x32_bf16 v[120:123], v[128:131], v[198:201], v[120:123]
	v_mfma_f32_16x16x32_bf16 v[88:91], v[136:139], v[198:201], v[88:91]
	v_mfma_f32_16x16x32_bf16 v[116:119], v[128:131], v[206:209], v[116:119]
	v_mfma_f32_16x16x32_bf16 v[84:87], v[136:139], v[206:209], v[84:87]
	v_mfma_f32_16x16x32_bf16 v[112:115], v[128:131], v[214:217], v[112:115]
	v_mfma_f32_16x16x32_bf16 v[80:83], v[136:139], v[214:217], v[80:83]
	v_mfma_f32_16x16x32_bf16 v[100:103], v[128:131], v[222:225], v[100:103]
	v_mfma_f32_16x16x32_bf16 v[68:71], v[136:139], v[222:225], v[68:71]
	v_mfma_f32_16x16x32_bf16 v[120:123], v[132:135], v[202:205], v[120:123]
	v_mfma_f32_16x16x32_bf16 v[88:91], v[140:143], v[202:205], v[88:91]
	v_mfma_f32_16x16x32_bf16 v[116:119], v[132:135], v[210:213], v[116:119]
	v_mfma_f32_16x16x32_bf16 v[84:87], v[140:143], v[210:213], v[84:87]
	v_mfma_f32_16x16x32_bf16 v[112:115], v[132:135], v[218:221], v[112:115]
	v_mfma_f32_16x16x32_bf16 v[80:83], v[140:143], v[218:221], v[80:83]
	v_mfma_f32_16x16x32_bf16 v[100:103], v[132:135], v[226:229], v[100:103]
	v_mfma_f32_16x16x32_bf16 v[68:71], v[140:143], v[226:229], v[68:71]
	v_mfma_f32_16x16x32_bf16 v[124:127], v[168:171], v[198:201], v[124:127]
	v_mfma_f32_16x16x32_bf16 v[92:95], v[176:179], v[198:201], v[92:95]
	v_mfma_f32_16x16x32_bf16 v[108:111], v[168:171], v[206:209], v[108:111]
	v_mfma_f32_16x16x32_bf16 v[76:79], v[176:179], v[206:209], v[76:79]
	v_mfma_f32_16x16x32_bf16 v[104:107], v[168:171], v[214:217], v[104:107]
	v_mfma_f32_16x16x32_bf16 v[72:75], v[176:179], v[214:217], v[72:75]
	v_mfma_f32_16x16x32_bf16 v[96:99], v[168:171], v[222:225], v[96:99]
	v_mfma_f32_16x16x32_bf16 v[64:67], v[176:179], v[222:225], v[64:67]
	v_mfma_f32_16x16x32_bf16 v[124:127], v[172:175], v[202:205], v[124:127]
	v_mfma_f32_16x16x32_bf16 v[92:95], v[194:197], v[202:205], v[92:95]
	v_mfma_f32_16x16x32_bf16 v[108:111], v[172:175], v[210:213], v[108:111]
	v_mfma_f32_16x16x32_bf16 v[76:79], v[194:197], v[210:213], v[76:79]
	v_mfma_f32_16x16x32_bf16 v[104:107], v[172:175], v[218:221], v[104:107]
	v_mfma_f32_16x16x32_bf16 v[72:75], v[194:197], v[218:221], v[72:75]
	v_mfma_f32_16x16x32_bf16 v[96:99], v[172:175], v[226:229], v[96:99]
	v_mfma_f32_16x16x32_bf16 v[64:67], v[194:197], v[226:229], v[64:67]
	s_barrier
; #define PG8_STAGE(bufoff, gbase, voff) do { _Pragma("unroll") for (int _i = 0; _i < 2; ++_i) \
;         __builtin_amdgcn_global_load_lds((const unsigned*)((const char*)(gbase) + (voff)[_i]), (PG8_LAS unsigned*)(lds + (bufoff) + ldsw + _i * 8192), 16, 0, 0); } while (0)
; #define PG8_LDA(dst, b, h) do { _Pragma("unroll") for (int m = 0; m < 4; ++m) _Pragma("unroll") for (int k = 0; k < 2; ++k) dst[m][k] = *(const PG8_LAS bf16x8*)(lds + PG8_SA(b, h) + aoff + m * 2048 + k * 1024); } while (0)
; #define PG8_MMA(ai, bj, At, Bt) do { __builtin_amdgcn_s_setprio(1); _Pragma("unroll") for (int m = 0; m < 4; ++m) _Pragma("unroll") for (int n = 0; n < 2; ++n) _Pragma("unroll") for (int k = 0; k < 2; ++k) \
;         acc[ai][bj][m][n] = __builtin_amdgcn_mfma_f32_16x16x32_bf16(Bt[n][k], At[m][k], acc[ai][bj][m][n], 0, 0, 0); __builtin_amdgcn_s_setprio(0); } while (0)
; #define PG8_WAIT_V(n) asm volatile("s_waitcnt vmcnt(" #n ")" ::: "memory")
; #define PG8_WAIT_L(n) asm volatile("s_waitcnt lgkmcnt(" #n ")" ::: "memory")
; #define PG8_BAR __builtin_amdgcn_s_barrier()
; #define PG8_SCHED __builtin_amdgcn_sched_barrier(0)
; template <class Epi, class Sched, bool ALIGN_EPI = false, bool SP2 = false>
; __device__ __forceinline__ void gemm_phase(PG8_LAS unsigned char* lds, const Gemm g, const Sched& S, const Epi& E) {
;     ...
;             PG8_LDA(At, 1, 1); PG8_STAGE(PG8_SB(1, 0), b3, voffB); PG8_STAGE(PG8_SB(1, 1), b3 + hstep, voffB); PG8_STAGE(PG8_SA(1, 0), a3, voffA);
;             PG8_WAIT_V(8); PG8_WAIT_L(0); PG8_BAR; PG8_MMA(1, 0, At, B0); PG8_MMA(1, 1, At, B1); PG8_BAR; PG8_SCHED;
;     ...
;         if constexpr (ALIGN_EPI) { if (wr == 0) PG8_BAR; }
	s_add_i32 s36, s79, s59
	v_lshl_add_u64 v[180:181], v[180:181], 0, s[28:29]
	s_mov_b32 m0, s36
	ds_read_b128 v[198:201], v189 offset:49152
	ds_read_b128 v[202:205], v242 offset:49152
	ds_read_b128 v[206:209], v189 offset:51200
	ds_read_b128 v[210:213], v242 offset:51200
	ds_read_b128 v[214:217], v189 offset:53248
	ds_read_b128 v[218:221], v242 offset:53248
	ds_read_b128 v[222:225], v189 offset:55296
	ds_read_b128 v[226:229], v242 offset:55296
	global_load_lds_dwordx4 v[180:181], off
	s_add_i32 m0, s36, 0x2000
	s_add_u32 s20, s20, 0x80080
	v_lshl_add_u64 v[180:181], v[230:231], 0, s[28:29]
	s_addc_u32 s21, s21, 0
	s_add_i32 s36, s80, s59
	global_load_lds_dwordx4 v[180:181], off
	v_lshl_add_u64 v[180:181], s[20:21], 0, v[148:149]
	s_mov_b32 m0, s36
	s_nop 0
	global_load_lds_dwordx4 v[180:181], off
	v_lshl_add_u64 v[180:181], s[20:21], 0, v[152:153]
	s_add_i32 m0, s36, 0x2000
	s_nop 0
	global_load_lds_dwordx4 v[180:181], off
	v_lshl_add_u64 v[180:181], v[232:233], 0, s[28:29]
	s_mov_b32 m0, s67
	s_nop 0
	global_load_lds_dwordx4 v[180:181], off
	v_lshl_add_u64 v[180:181], v[234:235], 0, s[28:29]
	s_mov_b32 m0, s68
	s_nop 0
	global_load_lds_dwordx4 v[180:181], off
	s_waitcnt vmcnt(8)
	s_waitcnt lgkmcnt(0)
	s_barrier
	s_waitcnt lgkmcnt(0)
	v_mfma_f32_16x16x32_bf16 v[60:63], v[128:131], v[198:201], v[60:63]
	v_mfma_f32_16x16x32_bf16 v[28:31], v[136:139], v[198:201], v[28:31]
	v_mfma_f32_16x16x32_bf16 v[52:55], v[128:131], v[206:209], v[52:55]
	v_mfma_f32_16x16x32_bf16 v[20:23], v[136:139], v[206:209], v[20:23]
	v_mfma_f32_16x16x32_bf16 v[48:51], v[128:131], v[214:217], v[48:51]
	v_mfma_f32_16x16x32_bf16 v[16:19], v[136:139], v[214:217], v[16:19]
	v_mfma_f32_16x16x32_bf16 v[44:47], v[128:131], v[222:225], v[44:47]
	v_mfma_f32_16x16x32_bf16 v[8:11], v[136:139], v[222:225], v[8:11]
	v_mfma_f32_16x16x32_bf16 v[60:63], v[132:135], v[202:205], v[60:63]
	v_mfma_f32_16x16x32_bf16 v[28:31], v[140:143], v[202:205], v[28:31]
	v_mfma_f32_16x16x32_bf16 v[52:55], v[132:135], v[210:213], v[52:55]
	v_mfma_f32_16x16x32_bf16 v[20:23], v[140:143], v[210:213], v[20:23]
	v_mfma_f32_16x16x32_bf16 v[48:51], v[132:135], v[218:221], v[48:51]
	v_mfma_f32_16x16x32_bf16 v[16:19], v[140:143], v[218:221], v[16:19]
	v_mfma_f32_16x16x32_bf16 v[44:47], v[132:135], v[226:229], v[44:47]
	v_mfma_f32_16x16x32_bf16 v[8:11], v[140:143], v[226:229], v[8:11]
	v_mfma_f32_16x16x32_bf16 v[56:59], v[168:171], v[198:201], v[56:59]
	v_mfma_f32_16x16x32_bf16 v[24:27], v[176:179], v[198:201], v[24:27]
	v_mfma_f32_16x16x32_bf16 v[40:43], v[168:171], v[206:209], v[40:43]
	v_mfma_f32_16x16x32_bf16 v[12:15], v[176:179], v[206:209], v[12:15]
	v_mfma_f32_16x16x32_bf16 v[36:39], v[168:171], v[214:217], v[36:39]
	v_mfma_f32_16x16x32_bf16 v[4:7], v[176:179], v[214:217], v[4:7]
	v_mfma_f32_16x16x32_bf16 v[32:35], v[168:171], v[222:225], v[32:35]
	v_mfma_f32_16x16x32_bf16 v[0:3], v[176:179], v[222:225], v[0:3]
	v_mfma_f32_16x16x32_bf16 v[56:59], v[172:175], v[202:205], v[56:59]
	v_mfma_f32_16x16x32_bf16 v[24:27], v[194:197], v[202:205], v[24:27]
	v_mfma_f32_16x16x32_bf16 v[40:43], v[172:175], v[210:213], v[40:43]
	v_mfma_f32_16x16x32_bf16 v[12:15], v[194:197], v[210:213], v[12:15]
	v_mfma_f32_16x16x32_bf16 v[36:39], v[172:175], v[218:221], v[36:39]
	v_mfma_f32_16x16x32_bf16 v[4:7], v[194:197], v[218:221], v[4:7]
	v_mfma_f32_16x16x32_bf16 v[32:35], v[172:175], v[226:229], v[32:35]
	v_mfma_f32_16x16x32_bf16 v[0:3], v[194:197], v[226:229], v[0:3]
	s_barrier
	s_add_i32 s78, s78, 2
	s_add_u32 s18, s18, 0x100
	s_addc_u32 s19, s19, 0
	s_add_u32 s76, s76, 0x100
	s_addc_u32 s77, s77, 0
	s_cmp_gt_u32 s78, 29
	s_cbranch_scc0 .LBB0_882
	s_setprio 0
	s_and_b64 vcc, exec, s[30:31]
	s_cbranch_vccz .LBB0_885
	s_barrier

; #define PG8_STAGE(bufoff, gbase, voff) do { _Pragma("unroll") for (int _i = 0; _i < 2; ++_i) \
;         __builtin_amdgcn_global_load_lds((const unsigned*)((const char*)(gbase) + (voff)[_i]), (PG8_LAS unsigned*)(lds + (bufoff) + ldsw + _i * 8192), 16, 0, 0); } while (0)
; #define PG8_LDA(dst, b, h) do { _Pragma("unroll") for (int m = 0; m < 4; ++m) _Pragma("unroll") for (int k = 0; k < 2; ++k) dst[m][k] = *(const PG8_LAS bf16x8*)(lds + PG8_SA(b, h) + aoff + m * 2048 + k * 1024); } while (0)
; #define PG8_LDB(dst, b, h) do { _Pragma("unroll") for (int n = 0; n < 2; ++n) _Pragma("unroll") for (int k = 0; k < 2; ++k) dst[n][k] = *(const PG8_LAS bf16x8*)(lds + PG8_SB(b, h) + boff + n * 2048 + k * 1024); } while (0)
; #define PG8_MMA(ai, bj, At, Bt) do { __builtin_amdgcn_s_setprio(1); _Pragma("unroll") for (int m = 0; m < 4; ++m) _Pragma("unroll") for (int n = 0; n < 2; ++n) _Pragma("unroll") for (int k = 0; k < 2; ++k) \
;         acc[ai][bj][m][n] = __builtin_amdgcn_mfma_f32_16x16x32_bf16(Bt[n][k], At[m][k], acc[ai][bj][m][n], 0, 0, 0); __builtin_amdgcn_s_setprio(0); } while (0)
; #define PG8_WAIT_V(n) asm volatile("s_waitcnt vmcnt(" #n ")" ::: "memory")
; #define PG8_WAIT_L(n) asm volatile("s_waitcnt lgkmcnt(" #n ")" ::: "memory")
; #define PG8_BAR __builtin_amdgcn_s_barrier()
; template <class Epi, class Sched, bool ALIGN_EPI = false, bool SP2 = false>
; __device__ __forceinline__ void gemm_phase(PG8_LAS unsigned char* lds, const Gemm g, const Sched& S, const Epi& E) {
;     ...
;         const char* nA = has_next ? (const char*)(nxt.seg ? g.A2 : g.A) + (size_t)nxt.pm * tstep : cA; const char* nB = has_next ? (const char*)(nxt.seg ? g.Bt2 : g.Bt) + (size_t)nxt.pn * tstep : cB;
;         for (int t = 0; t < nt; t += 2) {
;             const bool last = (t == nt - 2);
;             const char* a1 = cA + (size_t)(t + 1) * kstep;
;             const char* a2 = last ? nA : cA + (size_t)(t + 2) * kstep; const char* b2 = last ? nB : cB + (size_t)(t + 2) * kstep;
;     ...
;             PG8_LDB(B0, 0, 0); PG8_LDB(B1, 0, 1); PG8_SCHED; PG8_LDA(At, 0, 0); PG8_STAGE(PG8_SA(1, 1), a1 + hstep, voffA);
;             PG8_WAIT_V(8); PG8_WAIT_L(0); PG8_BAR; PG8_MMA(0, 0, At, B0); PG8_MMA(0, 1, At, B1); PG8_BAR; PG8_SCHED;
;             PG8_LDA(At, 0, 1); PG8_STAGE(PG8_SB(0, 0), b2, voffB); PG8_STAGE(PG8_SB(0, 1), b2 + hstep, voffB); PG8_STAGE(PG8_SA(0, 0), a2, voffA);
.LBB0_1059:
	s_add_u32 s24, s24, 0x158080
	s_addc_u32 s25, s25, 0
	s_add_u32 s58, s26, 0x100
	v_mov_b32_e32 v0, 0
	s_addc_u32 s59, s27, 0
	s_mov_b32 s60, -2
	s_cmp_lg_u64 s[12:13], 0
	s_cbranch_scc1 .Lsp3_lead
	s_setprio 1
.Lsp3_lead:
	ds_read_b128 v[154:157], v150
	ds_read_b128 v[160:163], v151
	ds_read_b128 v[164:167], v150 offset:2048
	ds_read_b128 v[168:171], v151 offset:2048
	ds_read_b128 v[172:175], v150 offset:16384
	ds_read_b128 v[176:179], v151 offset:16384
	ds_read_b128 v[180:183], v150 offset:18432
	ds_read_b128 v[184:187], v151 offset:18432
	s_add_u32 s26, s24, 0xffea8080
	s_addc_u32 s27, s25, -1
	s_cmpk_eq_i32 s60, 0x52
	s_cselect_b32 s29, s3, s27
	s_cselect_b32 s28, s2, s26
	s_cselect_b32 s27, s23, s59
	s_cselect_b32 s26, s22, s58
	v_lshl_add_u64 v[146:147], s[24:25], 0, v[136:137]
	s_add_i32 m0, s40, 0xc000
	ds_read_b128 v[188:191], v152
	ds_read_b128 v[192:195], v242
	ds_read_b128 v[196:199], v152 offset:2048
	ds_read_b128 v[200:203], v242 offset:2048
	ds_read_b128 v[204:207], v152 offset:4096
	ds_read_b128 v[208:211], v242 offset:4096
	ds_read_b128 v[212:215], v152 offset:6144
	ds_read_b128 v[216:219], v242 offset:6144
	global_load_lds_dwordx4 v[146:147], off
	v_lshl_add_u64 v[146:147], s[24:25], 0, v[138:139]
	s_add_i32 m0, s40, 0xe000
	s_nop 0
	global_load_lds_dwordx4 v[146:147], off
	s_waitcnt vmcnt(8)
	s_waitcnt lgkmcnt(0)
	s_barrier
	s_waitcnt lgkmcnt(0)
	v_mfma_f32_16x16x32_bf16 v[124:127], v[154:157], v[188:191], 0
	v_mfma_f32_16x16x32_bf16 v[120:123], v[164:167], v[188:191], 0
	v_mfma_f32_16x16x32_bf16 v[116:119], v[154:157], v[196:199], 0
	v_mfma_f32_16x16x32_bf16 v[108:111], v[164:167], v[196:199], 0
	v_mfma_f32_16x16x32_bf16 v[100:103], v[154:157], v[204:207], 0
	v_mfma_f32_16x16x32_bf16 v[92:95], v[164:167], v[204:207], 0
	v_mfma_f32_16x16x32_bf16 v[84:87], v[154:157], v[212:215], 0
	v_mfma_f32_16x16x32_bf16 v[76:79], v[164:167], v[212:215], 0
	v_mfma_f32_16x16x32_bf16 v[124:127], v[160:163], v[192:195], v[124:127]
	v_mfma_f32_16x16x32_bf16 v[120:123], v[168:171], v[192:195], v[120:123]
	v_mfma_f32_16x16x32_bf16 v[116:119], v[160:163], v[200:203], v[116:119]
	v_mfma_f32_16x16x32_bf16 v[108:111], v[168:171], v[200:203], v[108:111]
	v_mfma_f32_16x16x32_bf16 v[100:103], v[160:163], v[208:211], v[100:103]
	v_mfma_f32_16x16x32_bf16 v[92:95], v[168:171], v[208:211], v[92:95]
	v_mfma_f32_16x16x32_bf16 v[84:87], v[160:163], v[216:219], v[84:87]
	v_mfma_f32_16x16x32_bf16 v[76:79], v[168:171], v[216:219], v[76:79]
	v_mfma_f32_16x16x32_bf16 v[112:115], v[172:175], v[188:191], 0
	v_mfma_f32_16x16x32_bf16 v[104:107], v[180:183], v[188:191], 0
	v_mfma_f32_16x16x32_bf16 v[96:99], v[172:175], v[196:199], 0
	v_mfma_f32_16x16x32_bf16 v[88:91], v[180:183], v[196:199], 0
	v_mfma_f32_16x16x32_bf16 v[80:83], v[172:175], v[204:207], 0
	v_mfma_f32_16x16x32_bf16 v[72:75], v[180:183], v[204:207], 0
	v_mfma_f32_16x16x32_bf16 v[68:71], v[172:175], v[212:215], 0
	v_mfma_f32_16x16x32_bf16 v[64:67], v[180:183], v[212:215], 0
	v_mfma_f32_16x16x32_bf16 v[112:115], v[176:179], v[192:195], v[112:115]
	v_mfma_f32_16x16x32_bf16 v[104:107], v[184:187], v[192:195], v[104:107]
	v_mfma_f32_16x16x32_bf16 v[96:99], v[176:179], v[200:203], v[96:99]
	v_mfma_f32_16x16x32_bf16 v[88:91], v[184:187], v[200:203], v[88:91]
	v_mfma_f32_16x16x32_bf16 v[80:83], v[176:179], v[208:211], v[80:83]
	v_mfma_f32_16x16x32_bf16 v[72:75], v[184:187], v[208:211], v[72:75]
	v_mfma_f32_16x16x32_bf16 v[68:71], v[176:179], v[216:219], v[68:71]
	v_mfma_f32_16x16x32_bf16 v[64:67], v[184:187], v[216:219], v[64:67]
	s_barrier
	s_add_i32 s36, s48, s39
	v_lshl_add_u64 v[146:147], s[26:27], 0, v[130:131]
	s_mov_b32 m0, s36
	ds_read_b128 v[188:191], v152 offset:16384
	ds_read_b128 v[192:195], v242 offset:16384
	ds_read_b128 v[196:199], v152 offset:18432
	ds_read_b128 v[200:203], v242 offset:18432
	ds_read_b128 v[204:207], v152 offset:20480
	ds_read_b128 v[208:211], v242 offset:20480
	ds_read_b128 v[212:215], v152 offset:22528
	ds_read_b128 v[216:219], v242 offset:22528
	global_load_lds_dwordx4 v[146:147], off
	s_add_i32 m0, s36, 0x2000
	s_add_u32 s36, s26, 0x158000
	v_lshl_add_u64 v[220:221], s[26:27], 0, v[134:135]
	s_addc_u32 s37, s27, 0
	s_add_i32 s61, s49, s39
	global_load_lds_dwordx4 v[220:221], off
	v_lshl_add_u64 v[222:223], s[36:37], 0, v[130:131]
	s_mov_b32 m0, s61
	v_lshl_add_u64 v[224:225], s[28:29], 0, v[132:133]
	global_load_lds_dwordx4 v[222:223], off
	v_lshl_add_u64 v[222:223], s[36:37], 0, v[134:135]
	s_add_i32 m0, s61, 0x2000
	s_nop 0
	global_load_lds_dwordx4 v[222:223], off
	v_lshl_add_u64 v[222:223], s[28:29], 0, v[128:129]
	s_mov_b32 m0, s40
	s_nop 0
	global_load_lds_dwordx4 v[222:223], off
	s_mov_b32 m0, s41
	s_nop 0
	global_load_lds_dwordx4 v[224:225], off
	s_waitcnt vmcnt(8)
	s_waitcnt lgkmcnt(0)
	s_barrier
; #define PG8_STAGE(bufoff, gbase, voff) do { _Pragma("unroll") for (int _i = 0; _i < 2; ++_i) \
;         __builtin_amdgcn_global_load_lds((const unsigned*)((const char*)(gbase) + (voff)[_i]), (PG8_LAS unsigned*)(lds + (bufoff) + ldsw + _i * 8192), 16, 0, 0); } while (0)
; #define PG8_LDA(dst, b, h) do { _Pragma("unroll") for (int m = 0; m < 4; ++m) _Pragma("unroll") for (int k = 0; k < 2; ++k) dst[m][k] = *(const PG8_LAS bf16x8*)(lds + PG8_SA(b, h) + aoff + m * 2048 + k * 1024); } while (0)
; #define PG8_LDB(dst, b, h) do { _Pragma("unroll") for (int n = 0; n < 2; ++n) _Pragma("unroll") for (int k = 0; k < 2; ++k) dst[n][k] = *(const PG8_LAS bf16x8*)(lds + PG8_SB(b, h) + boff + n * 2048 + k * 1024); } while (0)
; #define PG8_MMA(ai, bj, At, Bt) do { __builtin_amdgcn_s_setprio(1); _Pragma("unroll") for (int m = 0; m < 4; ++m) _Pragma("unroll") for (int n = 0; n < 2; ++n) _Pragma("unroll") for (int k = 0; k < 2; ++k) \
;         acc[ai][bj][m][n] = __builtin_amdgcn_mfma_f32_16x16x32_bf16(Bt[n][k], At[m][k], acc[ai][bj][m][n], 0, 0, 0); __builtin_amdgcn_s_setprio(0); } while (0)
; #define PG8_WAIT_V(n) asm volatile("s_waitcnt vmcnt(" #n ")" ::: "memory")
; #define PG8_WAIT_L(n) asm volatile("s_waitcnt lgkmcnt(" #n ")" ::: "memory")
; #define PG8_BAR __builtin_amdgcn_s_barrier()
; #define PG8_SCHED __builtin_amdgcn_sched_barrier(0)
; template <class Epi, class Sched, bool ALIGN_EPI = false, bool SP2 = false>
; __device__ __forceinline__ void gemm_phase(PG8_LAS unsigned char* lds, const Gemm g, const Sched& S, const Epi& E) {
;     ...
;             PG8_WAIT_V(8); PG8_WAIT_L(0); PG8_BAR; PG8_MMA(1, 0, At, B0); PG8_MMA(1, 1, At, B1); PG8_BAR; PG8_SCHED;
;             PG8_LDB(B0, 1, 0); PG8_LDB(B1, 1, 1); PG8_SCHED; PG8_LDA(At, 1, 0); PG8_STAGE(PG8_SA(0, 1), a2 + hstep, voffA);
;             PG8_WAIT_V(8); PG8_WAIT_L(0); PG8_BAR; PG8_MMA(0, 0, At, B0); PG8_MMA(0, 1, At, B1); PG8_BAR; PG8_SCHED;
	s_waitcnt lgkmcnt(0)
	v_mfma_f32_16x16x32_bf16 v[60:63], v[154:157], v[188:191], 0
	v_mfma_f32_16x16x32_bf16 v[56:59], v[164:167], v[188:191], 0
	v_mfma_f32_16x16x32_bf16 v[52:55], v[154:157], v[196:199], 0
	v_mfma_f32_16x16x32_bf16 v[44:47], v[164:167], v[196:199], 0
	v_mfma_f32_16x16x32_bf16 v[36:39], v[154:157], v[204:207], 0
	v_mfma_f32_16x16x32_bf16 v[28:31], v[164:167], v[204:207], 0
	v_mfma_f32_16x16x32_bf16 v[20:23], v[154:157], v[212:215], 0
	v_mfma_f32_16x16x32_bf16 v[12:15], v[164:167], v[212:215], 0
	v_mfma_f32_16x16x32_bf16 v[60:63], v[160:163], v[192:195], v[60:63]
	v_mfma_f32_16x16x32_bf16 v[56:59], v[168:171], v[192:195], v[56:59]
	v_mfma_f32_16x16x32_bf16 v[52:55], v[160:163], v[200:203], v[52:55]
	v_mfma_f32_16x16x32_bf16 v[44:47], v[168:171], v[200:203], v[44:47]
	v_mfma_f32_16x16x32_bf16 v[36:39], v[160:163], v[208:211], v[36:39]
	v_mfma_f32_16x16x32_bf16 v[28:31], v[168:171], v[208:211], v[28:31]
	v_mfma_f32_16x16x32_bf16 v[20:23], v[160:163], v[216:219], v[20:23]
	v_mfma_f32_16x16x32_bf16 v[12:15], v[168:171], v[216:219], v[12:15]
	v_mfma_f32_16x16x32_bf16 v[48:51], v[172:175], v[188:191], 0
	v_mfma_f32_16x16x32_bf16 v[40:43], v[180:183], v[188:191], 0
	v_mfma_f32_16x16x32_bf16 v[32:35], v[172:175], v[196:199], 0
	v_mfma_f32_16x16x32_bf16 v[24:27], v[180:183], v[196:199], 0
	v_mfma_f32_16x16x32_bf16 v[16:19], v[172:175], v[204:207], 0
	v_mfma_f32_16x16x32_bf16 v[8:11], v[180:183], v[204:207], 0
	v_mfma_f32_16x16x32_bf16 v[4:7], v[172:175], v[212:215], 0
	v_mfma_f32_16x16x32_bf16 v[0:3], v[180:183], v[212:215], 0
	v_mfma_f32_16x16x32_bf16 v[48:51], v[176:179], v[192:195], v[48:51]
	v_mfma_f32_16x16x32_bf16 v[40:43], v[184:187], v[192:195], v[40:43]
	v_mfma_f32_16x16x32_bf16 v[32:35], v[176:179], v[200:203], v[32:35]
	v_mfma_f32_16x16x32_bf16 v[24:27], v[184:187], v[200:203], v[24:27]
	v_mfma_f32_16x16x32_bf16 v[16:19], v[176:179], v[208:211], v[16:19]
	v_mfma_f32_16x16x32_bf16 v[8:11], v[184:187], v[208:211], v[8:11]
	v_mfma_f32_16x16x32_bf16 v[4:7], v[176:179], v[216:219], v[4:7]
	v_mfma_f32_16x16x32_bf16 v[0:3], v[184:187], v[216:219], v[0:3]
	s_barrier
	s_add_i32 s36, 0, 0x18000
	v_add_u32_e32 v153, s36, v148
	s_add_i32 s37, 0, 0x1c000
	ds_read_b128 v[154:157], v150 offset:32768
	ds_read_b128 v[160:163], v151 offset:32768
	ds_read_b128 v[164:167], v150 offset:34816
	ds_read_b128 v[168:171], v151 offset:34816
	v_add_u32_e32 v153, s37, v148
	ds_read_b128 v[172:175], v150 offset:49152
	ds_read_b128 v[176:179], v151 offset:49152
	ds_read_b128 v[180:183], v150 offset:51200
	ds_read_b128 v[184:187], v151 offset:51200
	s_add_u32 s28, s28, 0x158000
	s_addc_u32 s29, s29, 0
	s_mov_b32 m0, s42
	v_lshl_add_u64 v[226:227], s[28:29], 0, v[128:129]
	ds_read_b128 v[188:191], v152 offset:32768
	ds_read_b128 v[192:195], v242 offset:32768
	ds_read_b128 v[196:199], v152 offset:34816
	ds_read_b128 v[200:203], v242 offset:34816
	ds_read_b128 v[204:207], v152 offset:36864
	ds_read_b128 v[208:211], v242 offset:36864
	ds_read_b128 v[212:215], v152 offset:38912
	ds_read_b128 v[216:219], v242 offset:38912
	global_load_lds_dwordx4 v[226:227], off
	v_lshl_add_u64 v[226:227], s[28:29], 0, v[132:133]
	s_mov_b32 m0, s43
	s_nop 0
	global_load_lds_dwordx4 v[226:227], off
	s_waitcnt vmcnt(8)
	s_waitcnt lgkmcnt(0)
	s_barrier
	s_waitcnt lgkmcnt(0)
	v_mfma_f32_16x16x32_bf16 v[124:127], v[154:157], v[188:191], v[124:127]
	v_mfma_f32_16x16x32_bf16 v[120:123], v[164:167], v[188:191], v[120:123]
	v_mfma_f32_16x16x32_bf16 v[116:119], v[154:157], v[196:199], v[116:119]
	v_mfma_f32_16x16x32_bf16 v[108:111], v[164:167], v[196:199], v[108:111]
	v_mfma_f32_16x16x32_bf16 v[100:103], v[154:157], v[204:207], v[100:103]
	v_mfma_f32_16x16x32_bf16 v[92:95], v[164:167], v[204:207], v[92:95]
	v_mfma_f32_16x16x32_bf16 v[84:87], v[154:157], v[212:215], v[84:87]
	v_mfma_f32_16x16x32_bf16 v[76:79], v[164:167], v[212:215], v[76:79]
	v_mfma_f32_16x16x32_bf16 v[124:127], v[160:163], v[192:195], v[124:127]
	v_mfma_f32_16x16x32_bf16 v[120:123], v[168:171], v[192:195], v[120:123]
	v_mfma_f32_16x16x32_bf16 v[116:119], v[160:163], v[200:203], v[116:119]
	v_mfma_f32_16x16x32_bf16 v[108:111], v[168:171], v[200:203], v[108:111]
	v_mfma_f32_16x16x32_bf16 v[100:103], v[160:163], v[208:211], v[100:103]
	v_mfma_f32_16x16x32_bf16 v[92:95], v[168:171], v[208:211], v[92:95]
	v_mfma_f32_16x16x32_bf16 v[84:87], v[160:163], v[216:219], v[84:87]
	v_mfma_f32_16x16x32_bf16 v[76:79], v[168:171], v[216:219], v[76:79]
	v_mfma_f32_16x16x32_bf16 v[112:115], v[172:175], v[188:191], v[112:115]
	v_mfma_f32_16x16x32_bf16 v[104:107], v[180:183], v[188:191], v[104:107]
	v_mfma_f32_16x16x32_bf16 v[96:99], v[172:175], v[196:199], v[96:99]
	v_mfma_f32_16x16x32_bf16 v[88:91], v[180:183], v[196:199], v[88:91]
	v_mfma_f32_16x16x32_bf16 v[80:83], v[172:175], v[204:207], v[80:83]
	v_mfma_f32_16x16x32_bf16 v[72:75], v[180:183], v[204:207], v[72:75]
	v_mfma_f32_16x16x32_bf16 v[68:71], v[172:175], v[212:215], v[68:71]
	v_mfma_f32_16x16x32_bf16 v[64:67], v[180:183], v[212:215], v[64:67]
	v_mfma_f32_16x16x32_bf16 v[112:115], v[176:179], v[192:195], v[112:115]
	v_mfma_f32_16x16x32_bf16 v[104:107], v[184:187], v[192:195], v[104:107]
	v_mfma_f32_16x16x32_bf16 v[96:99], v[176:179], v[200:203], v[96:99]
	v_mfma_f32_16x16x32_bf16 v[88:91], v[184:187], v[200:203], v[88:91]
	v_mfma_f32_16x16x32_bf16 v[80:83], v[176:179], v[208:211], v[80:83]
	v_mfma_f32_16x16x32_bf16 v[72:75], v[184:187], v[208:211], v[72:75]
	v_mfma_f32_16x16x32_bf16 v[68:71], v[176:179], v[216:219], v[68:71]
	v_mfma_f32_16x16x32_bf16 v[64:67], v[184:187], v[216:219], v[64:67]
	s_barrier
; #define PG8_STAGE(bufoff, gbase, voff) do { _Pragma("unroll") for (int _i = 0; _i < 2; ++_i) \
;         __builtin_amdgcn_global_load_lds((const unsigned*)((const char*)(gbase) + (voff)[_i]), (PG8_LAS unsigned*)(lds + (bufoff) + ldsw + _i * 8192), 16, 0, 0); } while (0)
; #define PG8_LDA(dst, b, h) do { _Pragma("unroll") for (int m = 0; m < 4; ++m) _Pragma("unroll") for (int k = 0; k < 2; ++k) dst[m][k] = *(const PG8_LAS bf16x8*)(lds + PG8_SA(b, h) + aoff + m * 2048 + k * 1024); } while (0)
; #define PG8_LDB(dst, b, h) do { _Pragma("unroll") for (int n = 0; n < 2; ++n) _Pragma("unroll") for (int k = 0; k < 2; ++k) dst[n][k] = *(const PG8_LAS bf16x8*)(lds + PG8_SB(b, h) + boff + n * 2048 + k * 1024); } while (0)
; #define PG8_MMA(ai, bj, At, Bt) do { __builtin_amdgcn_s_setprio(1); _Pragma("unroll") for (int m = 0; m < 4; ++m) _Pragma("unroll") for (int n = 0; n < 2; ++n) _Pragma("unroll") for (int k = 0; k < 2; ++k) \
;         acc[ai][bj][m][n] = __builtin_amdgcn_mfma_f32_16x16x32_bf16(Bt[n][k], At[m][k], acc[ai][bj][m][n], 0, 0, 0); __builtin_amdgcn_s_setprio(0); } while (0)
; #define PG8_WAIT_V(n) asm volatile("s_waitcnt vmcnt(" #n ")" ::: "memory")
; #define PG8_WAIT_L(n) asm volatile("s_waitcnt lgkmcnt(" #n ")" ::: "memory")
; #define PG8_BAR __builtin_amdgcn_s_barrier()
; #define PG8_SCHED __builtin_amdgcn_sched_barrier(0)
; template <class Epi, class Sched, bool ALIGN_EPI = false, bool SP2 = false>
; __device__ __forceinline__ void gemm_phase(PG8_LAS unsigned char* lds, const Gemm g, const Sched& S, const Epi& E) {
;     ...
;             PG8_LDB(B0, 0, 0); PG8_LDB(B1, 0, 1); PG8_SCHED; PG8_LDA(At, 0, 0); PG8_STAGE(PG8_SA(1, 1), a1 + hstep, voffA);
;             PG8_WAIT_V(8); PG8_WAIT_L(0); PG8_BAR; PG8_MMA(0, 0, At, B0); PG8_MMA(0, 1, At, B1); PG8_BAR; PG8_SCHED;
;     ...
;             PG8_LDA(At, 1, 1); PG8_STAGE(PG8_SB(1, 0), b3, voffB); PG8_STAGE(PG8_SB(1, 1), b3 + hstep, voffB); PG8_STAGE(PG8_SA(1, 0), a3, voffA);
;             PG8_WAIT_V(8); PG8_WAIT_L(0); PG8_BAR; PG8_MMA(1, 0, At, B0); PG8_MMA(1, 1, At, B1); PG8_BAR; PG8_SCHED;
	s_add_i32 s28, s36, s39
	v_lshl_add_u64 v[146:147], v[146:147], 0, s[10:11]
	s_mov_b32 m0, s28
	ds_read_b128 v[188:191], v152 offset:49152
	ds_read_b128 v[192:195], v242 offset:49152
	ds_read_b128 v[196:199], v152 offset:51200
	ds_read_b128 v[200:203], v242 offset:51200
	ds_read_b128 v[204:207], v152 offset:53248
	ds_read_b128 v[208:211], v242 offset:53248
	ds_read_b128 v[212:215], v152 offset:55296
	ds_read_b128 v[216:219], v242 offset:55296
	global_load_lds_dwordx4 v[146:147], off
	s_add_i32 m0, s28, 0x2000
	s_add_u32 s26, s26, 0x158080
	v_lshl_add_u64 v[146:147], v[220:221], 0, s[10:11]
	s_addc_u32 s27, s27, 0
	s_add_i32 s28, s37, s39
	global_load_lds_dwordx4 v[146:147], off
	v_lshl_add_u64 v[146:147], s[26:27], 0, v[130:131]
	s_mov_b32 m0, s28
	s_nop 0
	global_load_lds_dwordx4 v[146:147], off
	v_lshl_add_u64 v[146:147], s[26:27], 0, v[134:135]
	s_add_i32 m0, s28, 0x2000
	s_nop 0
	global_load_lds_dwordx4 v[146:147], off
	v_lshl_add_u64 v[146:147], v[222:223], 0, s[10:11]
	s_mov_b32 m0, s45
	s_nop 0
	global_load_lds_dwordx4 v[146:147], off
	v_lshl_add_u64 v[146:147], v[224:225], 0, s[10:11]
	s_mov_b32 m0, s46
	s_nop 0
	global_load_lds_dwordx4 v[146:147], off
	s_waitcnt vmcnt(8)
	s_waitcnt lgkmcnt(0)
	s_barrier
	s_waitcnt lgkmcnt(0)
	v_mfma_f32_16x16x32_bf16 v[60:63], v[154:157], v[188:191], v[60:63]
	v_mfma_f32_16x16x32_bf16 v[56:59], v[164:167], v[188:191], v[56:59]
	v_mfma_f32_16x16x32_bf16 v[52:55], v[154:157], v[196:199], v[52:55]
	v_mfma_f32_16x16x32_bf16 v[44:47], v[164:167], v[196:199], v[44:47]
	v_mfma_f32_16x16x32_bf16 v[36:39], v[154:157], v[204:207], v[36:39]
	v_mfma_f32_16x16x32_bf16 v[28:31], v[164:167], v[204:207], v[28:31]
	v_mfma_f32_16x16x32_bf16 v[20:23], v[154:157], v[212:215], v[20:23]
	v_mfma_f32_16x16x32_bf16 v[12:15], v[164:167], v[212:215], v[12:15]
	v_mfma_f32_16x16x32_bf16 v[60:63], v[160:163], v[192:195], v[60:63]
	v_mfma_f32_16x16x32_bf16 v[56:59], v[168:171], v[192:195], v[56:59]
	v_mfma_f32_16x16x32_bf16 v[52:55], v[160:163], v[200:203], v[52:55]
	v_mfma_f32_16x16x32_bf16 v[44:47], v[168:171], v[200:203], v[44:47]
	v_mfma_f32_16x16x32_bf16 v[36:39], v[160:163], v[208:211], v[36:39]
	v_mfma_f32_16x16x32_bf16 v[28:31], v[168:171], v[208:211], v[28:31]
	v_mfma_f32_16x16x32_bf16 v[20:23], v[160:163], v[216:219], v[20:23]
	v_mfma_f32_16x16x32_bf16 v[12:15], v[168:171], v[216:219], v[12:15]
	v_mfma_f32_16x16x32_bf16 v[48:51], v[172:175], v[188:191], v[48:51]
	v_mfma_f32_16x16x32_bf16 v[40:43], v[180:183], v[188:191], v[40:43]
	v_mfma_f32_16x16x32_bf16 v[32:35], v[172:175], v[196:199], v[32:35]
	v_mfma_f32_16x16x32_bf16 v[24:27], v[180:183], v[196:199], v[24:27]
	v_mfma_f32_16x16x32_bf16 v[16:19], v[172:175], v[204:207], v[16:19]
	v_mfma_f32_16x16x32_bf16 v[8:11], v[180:183], v[204:207], v[8:11]
	v_mfma_f32_16x16x32_bf16 v[4:7], v[172:175], v[212:215], v[4:7]
	v_mfma_f32_16x16x32_bf16 v[0:3], v[180:183], v[212:215], v[0:3]
	v_mfma_f32_16x16x32_bf16 v[48:51], v[176:179], v[192:195], v[48:51]
	v_mfma_f32_16x16x32_bf16 v[40:43], v[184:187], v[192:195], v[40:43]
	v_mfma_f32_16x16x32_bf16 v[32:35], v[176:179], v[200:203], v[32:35]
	v_mfma_f32_16x16x32_bf16 v[24:27], v[184:187], v[200:203], v[24:27]
	v_mfma_f32_16x16x32_bf16 v[16:19], v[176:179], v[208:211], v[16:19]
	v_mfma_f32_16x16x32_bf16 v[8:11], v[184:187], v[208:211], v[8:11]
	v_mfma_f32_16x16x32_bf16 v[4:7], v[176:179], v[216:219], v[4:7]
	v_mfma_f32_16x16x32_bf16 v[0:3], v[184:187], v[216:219], v[0:3]
	s_barrier
	s_add_i32 s60, s60, 2
	s_add_u32 s24, s24, 0x100
	s_addc_u32 s25, s25, 0
	s_add_u32 s58, s58, 0x100
	s_addc_u32 s59, s59, 0
.LBB0_1060:
	ds_read_b128 v[154:157], v150
	ds_read_b128 v[160:163], v151
	ds_read_b128 v[164:167], v150 offset:2048
	ds_read_b128 v[168:171], v151 offset:2048
	ds_read_b128 v[172:175], v150 offset:16384
	ds_read_b128 v[176:179], v151 offset:16384
	ds_read_b128 v[180:183], v150 offset:18432
	ds_read_b128 v[184:187], v151 offset:18432
	s_add_u32 s26, s24, 0xffea8080
	s_addc_u32 s27, s25, -1
	s_cmpk_eq_i32 s60, 0x52
	s_cselect_b32 s29, s3, s27
	s_cselect_b32 s28, s2, s26
	s_cselect_b32 s27, s23, s59
	s_cselect_b32 s26, s22, s58
	v_lshl_add_u64 v[146:147], s[24:25], 0, v[136:137]
	s_add_i32 m0, s40, 0xc000
	ds_read_b128 v[188:191], v152
	ds_read_b128 v[192:195], v242
	ds_read_b128 v[196:199], v152 offset:2048
	ds_read_b128 v[200:203], v242 offset:2048
	ds_read_b128 v[204:207], v152 offset:4096
	ds_read_b128 v[208:211], v242 offset:4096
	ds_read_b128 v[212:215], v152 offset:6144
	ds_read_b128 v[216:219], v242 offset:6144
	global_load_lds_dwordx4 v[146:147], off
	v_lshl_add_u64 v[146:147], s[24:25], 0, v[138:139]
	s_add_i32 m0, s40, 0xe000
	s_nop 0
	global_load_lds_dwordx4 v[146:147], off
	s_waitcnt vmcnt(8)
	s_waitcnt lgkmcnt(0)
	s_barrier
; #define PG8_STAGE(bufoff, gbase, voff) do { _Pragma("unroll") for (int _i = 0; _i < 2; ++_i) \
;         __builtin_amdgcn_global_load_lds((const unsigned*)((const char*)(gbase) + (voff)[_i]), (PG8_LAS unsigned*)(lds + (bufoff) + ldsw + _i * 8192), 16, 0, 0); } while (0)
; #define PG8_LDA(dst, b, h) do { _Pragma("unroll") for (int m = 0; m < 4; ++m) _Pragma("unroll") for (int k = 0; k < 2; ++k) dst[m][k] = *(const PG8_LAS bf16x8*)(lds + PG8_SA(b, h) + aoff + m * 2048 + k * 1024); } while (0)
; #define PG8_MMA(ai, bj, At, Bt) do { __builtin_amdgcn_s_setprio(1); _Pragma("unroll") for (int m = 0; m < 4; ++m) _Pragma("unroll") for (int n = 0; n < 2; ++n) _Pragma("unroll") for (int k = 0; k < 2; ++k) \
;         acc[ai][bj][m][n] = __builtin_amdgcn_mfma_f32_16x16x32_bf16(Bt[n][k], At[m][k], acc[ai][bj][m][n], 0, 0, 0); __builtin_amdgcn_s_setprio(0); } while (0)
; #define PG8_WAIT_V(n) asm volatile("s_waitcnt vmcnt(" #n ")" ::: "memory")
; #define PG8_WAIT_L(n) asm volatile("s_waitcnt lgkmcnt(" #n ")" ::: "memory")
; #define PG8_BAR __builtin_amdgcn_s_barrier()
; #define PG8_SCHED __builtin_amdgcn_sched_barrier(0)
; template <class Epi, class Sched, bool ALIGN_EPI = false, bool SP2 = false>
; __device__ __forceinline__ void gemm_phase(PG8_LAS unsigned char* lds, const Gemm g, const Sched& S, const Epi& E) {
;     ...
;             PG8_WAIT_V(8); PG8_WAIT_L(0); PG8_BAR; PG8_MMA(0, 0, At, B0); PG8_MMA(0, 1, At, B1); PG8_BAR; PG8_SCHED;
;             PG8_LDA(At, 0, 1); PG8_STAGE(PG8_SB(0, 0), b2, voffB); PG8_STAGE(PG8_SB(0, 1), b2 + hstep, voffB); PG8_STAGE(PG8_SA(0, 0), a2, voffA);
;             PG8_WAIT_V(8); PG8_WAIT_L(0); PG8_BAR; PG8_MMA(1, 0, At, B0); PG8_MMA(1, 1, At, B1); PG8_BAR; PG8_SCHED;
	s_waitcnt lgkmcnt(0)
	v_mfma_f32_16x16x32_bf16 v[124:127], v[154:157], v[188:191], v[124:127]
	v_mfma_f32_16x16x32_bf16 v[120:123], v[164:167], v[188:191], v[120:123]
	v_mfma_f32_16x16x32_bf16 v[116:119], v[154:157], v[196:199], v[116:119]
	v_mfma_f32_16x16x32_bf16 v[108:111], v[164:167], v[196:199], v[108:111]
	v_mfma_f32_16x16x32_bf16 v[100:103], v[154:157], v[204:207], v[100:103]
	v_mfma_f32_16x16x32_bf16 v[92:95], v[164:167], v[204:207], v[92:95]
	v_mfma_f32_16x16x32_bf16 v[84:87], v[154:157], v[212:215], v[84:87]
	v_mfma_f32_16x16x32_bf16 v[76:79], v[164:167], v[212:215], v[76:79]
	v_mfma_f32_16x16x32_bf16 v[124:127], v[160:163], v[192:195], v[124:127]
	v_mfma_f32_16x16x32_bf16 v[120:123], v[168:171], v[192:195], v[120:123]
	v_mfma_f32_16x16x32_bf16 v[116:119], v[160:163], v[200:203], v[116:119]
	v_mfma_f32_16x16x32_bf16 v[108:111], v[168:171], v[200:203], v[108:111]
	v_mfma_f32_16x16x32_bf16 v[100:103], v[160:163], v[208:211], v[100:103]
	v_mfma_f32_16x16x32_bf16 v[92:95], v[168:171], v[208:211], v[92:95]
	v_mfma_f32_16x16x32_bf16 v[84:87], v[160:163], v[216:219], v[84:87]
	v_mfma_f32_16x16x32_bf16 v[76:79], v[168:171], v[216:219], v[76:79]
	v_mfma_f32_16x16x32_bf16 v[112:115], v[172:175], v[188:191], v[112:115]
	v_mfma_f32_16x16x32_bf16 v[104:107], v[180:183], v[188:191], v[104:107]
	v_mfma_f32_16x16x32_bf16 v[96:99], v[172:175], v[196:199], v[96:99]
	v_mfma_f32_16x16x32_bf16 v[88:91], v[180:183], v[196:199], v[88:91]
	v_mfma_f32_16x16x32_bf16 v[80:83], v[172:175], v[204:207], v[80:83]
	v_mfma_f32_16x16x32_bf16 v[72:75], v[180:183], v[204:207], v[72:75]
	v_mfma_f32_16x16x32_bf16 v[68:71], v[172:175], v[212:215], v[68:71]
	v_mfma_f32_16x16x32_bf16 v[64:67], v[180:183], v[212:215], v[64:67]
	v_mfma_f32_16x16x32_bf16 v[112:115], v[176:179], v[192:195], v[112:115]
	v_mfma_f32_16x16x32_bf16 v[104:107], v[184:187], v[192:195], v[104:107]
	v_mfma_f32_16x16x32_bf16 v[96:99], v[176:179], v[200:203], v[96:99]
	v_mfma_f32_16x16x32_bf16 v[88:91], v[184:187], v[200:203], v[88:91]
	v_mfma_f32_16x16x32_bf16 v[80:83], v[176:179], v[208:211], v[80:83]
	v_mfma_f32_16x16x32_bf16 v[72:75], v[184:187], v[208:211], v[72:75]
	v_mfma_f32_16x16x32_bf16 v[68:71], v[176:179], v[216:219], v[68:71]
	v_mfma_f32_16x16x32_bf16 v[64:67], v[184:187], v[216:219], v[64:67]
	s_barrier
	s_add_i32 s36, s48, s39
	v_lshl_add_u64 v[146:147], s[26:27], 0, v[130:131]
	s_mov_b32 m0, s36
	ds_read_b128 v[188:191], v152 offset:16384
	ds_read_b128 v[192:195], v242 offset:16384
	ds_read_b128 v[196:199], v152 offset:18432
	ds_read_b128 v[200:203], v242 offset:18432
	ds_read_b128 v[204:207], v152 offset:20480
	ds_read_b128 v[208:211], v242 offset:20480
	ds_read_b128 v[212:215], v152 offset:22528
	ds_read_b128 v[216:219], v242 offset:22528
	global_load_lds_dwordx4 v[146:147], off
	s_add_i32 m0, s36, 0x2000
	s_add_u32 s36, s26, 0x158000
	v_lshl_add_u64 v[220:221], s[26:27], 0, v[134:135]
	s_addc_u32 s37, s27, 0
	s_add_i32 s61, s49, s39
	global_load_lds_dwordx4 v[220:221], off
	v_lshl_add_u64 v[222:223], s[36:37], 0, v[130:131]
	s_mov_b32 m0, s61
	v_lshl_add_u64 v[224:225], s[28:29], 0, v[132:133]
	global_load_lds_dwordx4 v[222:223], off
	v_lshl_add_u64 v[222:223], s[36:37], 0, v[134:135]
	s_add_i32 m0, s61, 0x2000
	s_nop 0
	global_load_lds_dwordx4 v[222:223], off
	v_lshl_add_u64 v[222:223], s[28:29], 0, v[128:129]
	s_mov_b32 m0, s40
	s_nop 0
	global_load_lds_dwordx4 v[222:223], off
	s_mov_b32 m0, s41
	s_nop 0
	global_load_lds_dwordx4 v[224:225], off
	s_waitcnt vmcnt(8)
	s_waitcnt lgkmcnt(0)
	s_barrier
	s_waitcnt lgkmcnt(0)
	v_mfma_f32_16x16x32_bf16 v[60:63], v[154:157], v[188:191], v[60:63]
	v_mfma_f32_16x16x32_bf16 v[56:59], v[164:167], v[188:191], v[56:59]
	v_mfma_f32_16x16x32_bf16 v[52:55], v[154:157], v[196:199], v[52:55]
	v_mfma_f32_16x16x32_bf16 v[44:47], v[164:167], v[196:199], v[44:47]
	v_mfma_f32_16x16x32_bf16 v[36:39], v[154:157], v[204:207], v[36:39]
	v_mfma_f32_16x16x32_bf16 v[28:31], v[164:167], v[204:207], v[28:31]
	v_mfma_f32_16x16x32_bf16 v[20:23], v[154:157], v[212:215], v[20:23]
	v_mfma_f32_16x16x32_bf16 v[12:15], v[164:167], v[212:215], v[12:15]
	v_mfma_f32_16x16x32_bf16 v[60:63], v[160:163], v[192:195], v[60:63]
	v_mfma_f32_16x16x32_bf16 v[56:59], v[168:171], v[192:195], v[56:59]
	v_mfma_f32_16x16x32_bf16 v[52:55], v[160:163], v[200:203], v[52:55]
	v_mfma_f32_16x16x32_bf16 v[44:47], v[168:171], v[200:203], v[44:47]
	v_mfma_f32_16x16x32_bf16 v[36:39], v[160:163], v[208:211], v[36:39]
	v_mfma_f32_16x16x32_bf16 v[28:31], v[168:171], v[208:211], v[28:31]
	v_mfma_f32_16x16x32_bf16 v[20:23], v[160:163], v[216:219], v[20:23]
	v_mfma_f32_16x16x32_bf16 v[12:15], v[168:171], v[216:219], v[12:15]
	v_mfma_f32_16x16x32_bf16 v[48:51], v[172:175], v[188:191], v[48:51]
	v_mfma_f32_16x16x32_bf16 v[40:43], v[180:183], v[188:191], v[40:43]
	v_mfma_f32_16x16x32_bf16 v[32:35], v[172:175], v[196:199], v[32:35]
	v_mfma_f32_16x16x32_bf16 v[24:27], v[180:183], v[196:199], v[24:27]
	v_mfma_f32_16x16x32_bf16 v[16:19], v[172:175], v[204:207], v[16:19]
	v_mfma_f32_16x16x32_bf16 v[8:11], v[180:183], v[204:207], v[8:11]
	v_mfma_f32_16x16x32_bf16 v[4:7], v[172:175], v[212:215], v[4:7]
	v_mfma_f32_16x16x32_bf16 v[0:3], v[180:183], v[212:215], v[0:3]
	v_mfma_f32_16x16x32_bf16 v[48:51], v[176:179], v[192:195], v[48:51]
	v_mfma_f32_16x16x32_bf16 v[40:43], v[184:187], v[192:195], v[40:43]
	v_mfma_f32_16x16x32_bf16 v[32:35], v[176:179], v[200:203], v[32:35]
	v_mfma_f32_16x16x32_bf16 v[24:27], v[184:187], v[200:203], v[24:27]
	v_mfma_f32_16x16x32_bf16 v[16:19], v[176:179], v[208:211], v[16:19]
	v_mfma_f32_16x16x32_bf16 v[8:11], v[184:187], v[208:211], v[8:11]
	v_mfma_f32_16x16x32_bf16 v[4:7], v[176:179], v[216:219], v[4:7]
	v_mfma_f32_16x16x32_bf16 v[0:3], v[184:187], v[216:219], v[0:3]
	s_barrier
; #define PG8_STAGE(bufoff, gbase, voff) do { _Pragma("unroll") for (int _i = 0; _i < 2; ++_i) \
;         __builtin_amdgcn_global_load_lds((const unsigned*)((const char*)(gbase) + (voff)[_i]), (PG8_LAS unsigned*)(lds + (bufoff) + ldsw + _i * 8192), 16, 0, 0); } while (0)
; #define PG8_LDA(dst, b, h) do { _Pragma("unroll") for (int m = 0; m < 4; ++m) _Pragma("unroll") for (int k = 0; k < 2; ++k) dst[m][k] = *(const PG8_LAS bf16x8*)(lds + PG8_SA(b, h) + aoff + m * 2048 + k * 1024); } while (0)
; #define PG8_LDB(dst, b, h) do { _Pragma("unroll") for (int n = 0; n < 2; ++n) _Pragma("unroll") for (int k = 0; k < 2; ++k) dst[n][k] = *(const PG8_LAS bf16x8*)(lds + PG8_SB(b, h) + boff + n * 2048 + k * 1024); } while (0)
; #define PG8_MMA(ai, bj, At, Bt) do { __builtin_amdgcn_s_setprio(1); _Pragma("unroll") for (int m = 0; m < 4; ++m) _Pragma("unroll") for (int n = 0; n < 2; ++n) _Pragma("unroll") for (int k = 0; k < 2; ++k) \
;         acc[ai][bj][m][n] = __builtin_amdgcn_mfma_f32_16x16x32_bf16(Bt[n][k], At[m][k], acc[ai][bj][m][n], 0, 0, 0); __builtin_amdgcn_s_setprio(0); } while (0)
; #define PG8_WAIT_V(n) asm volatile("s_waitcnt vmcnt(" #n ")" ::: "memory")
; #define PG8_WAIT_L(n) asm volatile("s_waitcnt lgkmcnt(" #n ")" ::: "memory")
; #define PG8_BAR __builtin_amdgcn_s_barrier()
; #define PG8_SCHED __builtin_amdgcn_sched_barrier(0)
; template <class Epi, class Sched, bool ALIGN_EPI = false, bool SP2 = false>
; __device__ __forceinline__ void gemm_phase(PG8_LAS unsigned char* lds, const Gemm g, const Sched& S, const Epi& E) {
;     ...
;             PG8_LDB(B0, 1, 0); PG8_LDB(B1, 1, 1); PG8_SCHED; PG8_LDA(At, 1, 0); PG8_STAGE(PG8_SA(0, 1), a2 + hstep, voffA);
;             PG8_WAIT_V(8); PG8_WAIT_L(0); PG8_BAR; PG8_MMA(0, 0, At, B0); PG8_MMA(0, 1, At, B1); PG8_BAR; PG8_SCHED;
	s_add_i32 s36, 0, 0x18000
	v_add_u32_e32 v153, s36, v148
	s_add_i32 s37, 0, 0x1c000
	ds_read_b128 v[154:157], v150 offset:32768
	ds_read_b128 v[160:163], v151 offset:32768
	ds_read_b128 v[164:167], v150 offset:34816
	ds_read_b128 v[168:171], v151 offset:34816
	v_add_u32_e32 v153, s37, v148
	ds_read_b128 v[172:175], v150 offset:49152
	ds_read_b128 v[176:179], v151 offset:49152
	ds_read_b128 v[180:183], v150 offset:51200
	ds_read_b128 v[184:187], v151 offset:51200
	s_add_u32 s28, s28, 0x158000
	s_addc_u32 s29, s29, 0
	s_mov_b32 m0, s42
	v_lshl_add_u64 v[226:227], s[28:29], 0, v[128:129]
	ds_read_b128 v[188:191], v152 offset:32768
	ds_read_b128 v[192:195], v242 offset:32768
	ds_read_b128 v[196:199], v152 offset:34816
	ds_read_b128 v[200:203], v242 offset:34816
	ds_read_b128 v[204:207], v152 offset:36864
	ds_read_b128 v[208:211], v242 offset:36864
	ds_read_b128 v[212:215], v152 offset:38912
	ds_read_b128 v[216:219], v242 offset:38912
	global_load_lds_dwordx4 v[226:227], off
	v_lshl_add_u64 v[226:227], s[28:29], 0, v[132:133]
	s_mov_b32 m0, s43
	s_nop 0
	global_load_lds_dwordx4 v[226:227], off
	s_waitcnt vmcnt(8)
	s_waitcnt lgkmcnt(0)
	s_barrier
	s_waitcnt lgkmcnt(0)
	v_mfma_f32_16x16x32_bf16 v[124:127], v[154:157], v[188:191], v[124:127]
	v_mfma_f32_16x16x32_bf16 v[120:123], v[164:167], v[188:191], v[120:123]
	v_mfma_f32_16x16x32_bf16 v[116:119], v[154:157], v[196:199], v[116:119]
	v_mfma_f32_16x16x32_bf16 v[108:111], v[164:167], v[196:199], v[108:111]
	v_mfma_f32_16x16x32_bf16 v[100:103], v[154:157], v[204:207], v[100:103]
	v_mfma_f32_16x16x32_bf16 v[92:95], v[164:167], v[204:207], v[92:95]
	v_mfma_f32_16x16x32_bf16 v[84:87], v[154:157], v[212:215], v[84:87]
	v_mfma_f32_16x16x32_bf16 v[76:79], v[164:167], v[212:215], v[76:79]
	v_mfma_f32_16x16x32_bf16 v[124:127], v[160:163], v[192:195], v[124:127]
	v_mfma_f32_16x16x32_bf16 v[120:123], v[168:171], v[192:195], v[120:123]
	v_mfma_f32_16x16x32_bf16 v[116:119], v[160:163], v[200:203], v[116:119]
	v_mfma_f32_16x16x32_bf16 v[108:111], v[168:171], v[200:203], v[108:111]
	v_mfma_f32_16x16x32_bf16 v[100:103], v[160:163], v[208:211], v[100:103]
	v_mfma_f32_16x16x32_bf16 v[92:95], v[168:171], v[208:211], v[92:95]
	v_mfma_f32_16x16x32_bf16 v[84:87], v[160:163], v[216:219], v[84:87]
	v_mfma_f32_16x16x32_bf16 v[76:79], v[168:171], v[216:219], v[76:79]
	v_mfma_f32_16x16x32_bf16 v[112:115], v[172:175], v[188:191], v[112:115]
	v_mfma_f32_16x16x32_bf16 v[104:107], v[180:183], v[188:191], v[104:107]
	v_mfma_f32_16x16x32_bf16 v[96:99], v[172:175], v[196:199], v[96:99]
	v_mfma_f32_16x16x32_bf16 v[88:91], v[180:183], v[196:199], v[88:91]
	v_mfma_f32_16x16x32_bf16 v[80:83], v[172:175], v[204:207], v[80:83]
	v_mfma_f32_16x16x32_bf16 v[72:75], v[180:183], v[204:207], v[72:75]
	v_mfma_f32_16x16x32_bf16 v[68:71], v[172:175], v[212:215], v[68:71]
	v_mfma_f32_16x16x32_bf16 v[64:67], v[180:183], v[212:215], v[64:67]
	v_mfma_f32_16x16x32_bf16 v[112:115], v[176:179], v[192:195], v[112:115]
	v_mfma_f32_16x16x32_bf16 v[104:107], v[184:187], v[192:195], v[104:107]
	v_mfma_f32_16x16x32_bf16 v[96:99], v[176:179], v[200:203], v[96:99]
	v_mfma_f32_16x16x32_bf16 v[88:91], v[184:187], v[200:203], v[88:91]
	v_mfma_f32_16x16x32_bf16 v[80:83], v[176:179], v[208:211], v[80:83]
	v_mfma_f32_16x16x32_bf16 v[72:75], v[184:187], v[208:211], v[72:75]
	v_mfma_f32_16x16x32_bf16 v[68:71], v[176:179], v[216:219], v[68:71]
	v_mfma_f32_16x16x32_bf16 v[64:67], v[184:187], v[216:219], v[64:67]
	s_barrier
; #define PG8_STAGE(bufoff, gbase, voff) do { _Pragma("unroll") for (int _i = 0; _i < 2; ++_i) \
;         __builtin_amdgcn_global_load_lds((const unsigned*)((const char*)(gbase) + (voff)[_i]), (PG8_LAS unsigned*)(lds + (bufoff) + ldsw + _i * 8192), 16, 0, 0); } while (0)
; #define PG8_LDA(dst, b, h) do { _Pragma("unroll") for (int m = 0; m < 4; ++m) _Pragma("unroll") for (int k = 0; k < 2; ++k) dst[m][k] = *(const PG8_LAS bf16x8*)(lds + PG8_SA(b, h) + aoff + m * 2048 + k * 1024); } while (0)
; #define PG8_MMA(ai, bj, At, Bt) do { __builtin_amdgcn_s_setprio(1); _Pragma("unroll") for (int m = 0; m < 4; ++m) _Pragma("unroll") for (int n = 0; n < 2; ++n) _Pragma("unroll") for (int k = 0; k < 2; ++k) \
;         acc[ai][bj][m][n] = __builtin_amdgcn_mfma_f32_16x16x32_bf16(Bt[n][k], At[m][k], acc[ai][bj][m][n], 0, 0, 0); __builtin_amdgcn_s_setprio(0); } while (0)
; #define PG8_WAIT_V(n) asm volatile("s_waitcnt vmcnt(" #n ")" ::: "memory")
; #define PG8_WAIT_L(n) asm volatile("s_waitcnt lgkmcnt(" #n ")" ::: "memory")
; #define PG8_BAR __builtin_amdgcn_s_barrier()
; #define PG8_SCHED __builtin_amdgcn_sched_barrier(0)
; template <class Epi, class Sched, bool ALIGN_EPI = false, bool SP2 = false>
; __device__ __forceinline__ void gemm_phase(PG8_LAS unsigned char* lds, const Gemm g, const Sched& S, const Epi& E) {
;     ...
;             PG8_LDA(At, 1, 1); PG8_STAGE(PG8_SB(1, 0), b3, voffB); PG8_STAGE(PG8_SB(1, 1), b3 + hstep, voffB); PG8_STAGE(PG8_SA(1, 0), a3, voffA);
;             PG8_WAIT_V(8); PG8_WAIT_L(0); PG8_BAR; PG8_MMA(1, 0, At, B0); PG8_MMA(1, 1, At, B1); PG8_BAR; PG8_SCHED;
;     ...
;         if constexpr (ALIGN_EPI) { if (wr == 0) PG8_BAR; }
	s_add_i32 s28, s36, s39
	v_lshl_add_u64 v[146:147], v[146:147], 0, s[10:11]
	s_mov_b32 m0, s28
	ds_read_b128 v[188:191], v152 offset:49152
	ds_read_b128 v[192:195], v242 offset:49152
	ds_read_b128 v[196:199], v152 offset:51200
	ds_read_b128 v[200:203], v242 offset:51200
	ds_read_b128 v[204:207], v152 offset:53248
	ds_read_b128 v[208:211], v242 offset:53248
	ds_read_b128 v[212:215], v152 offset:55296
	ds_read_b128 v[216:219], v242 offset:55296
	global_load_lds_dwordx4 v[146:147], off
	s_add_i32 m0, s28, 0x2000
	s_add_u32 s26, s26, 0x158080
	v_lshl_add_u64 v[146:147], v[220:221], 0, s[10:11]
	s_addc_u32 s27, s27, 0
	s_add_i32 s28, s37, s39
	global_load_lds_dwordx4 v[146:147], off
	v_lshl_add_u64 v[146:147], s[26:27], 0, v[130:131]
	s_mov_b32 m0, s28
	s_nop 0
	global_load_lds_dwordx4 v[146:147], off
	v_lshl_add_u64 v[146:147], s[26:27], 0, v[134:135]
	s_add_i32 m0, s28, 0x2000
	s_nop 0
	global_load_lds_dwordx4 v[146:147], off
	v_lshl_add_u64 v[146:147], v[222:223], 0, s[10:11]
	s_mov_b32 m0, s45
	s_nop 0
	global_load_lds_dwordx4 v[146:147], off
	v_lshl_add_u64 v[146:147], v[224:225], 0, s[10:11]
	s_mov_b32 m0, s46
	s_nop 0
	global_load_lds_dwordx4 v[146:147], off
	s_waitcnt vmcnt(8)
	s_waitcnt lgkmcnt(0)
	s_barrier
	s_waitcnt lgkmcnt(0)
	v_mfma_f32_16x16x32_bf16 v[60:63], v[154:157], v[188:191], v[60:63]
	v_mfma_f32_16x16x32_bf16 v[56:59], v[164:167], v[188:191], v[56:59]
	v_mfma_f32_16x16x32_bf16 v[52:55], v[154:157], v[196:199], v[52:55]
	v_mfma_f32_16x16x32_bf16 v[44:47], v[164:167], v[196:199], v[44:47]
	v_mfma_f32_16x16x32_bf16 v[36:39], v[154:157], v[204:207], v[36:39]
	v_mfma_f32_16x16x32_bf16 v[28:31], v[164:167], v[204:207], v[28:31]
	v_mfma_f32_16x16x32_bf16 v[20:23], v[154:157], v[212:215], v[20:23]
	v_mfma_f32_16x16x32_bf16 v[12:15], v[164:167], v[212:215], v[12:15]
	v_mfma_f32_16x16x32_bf16 v[60:63], v[160:163], v[192:195], v[60:63]
	v_mfma_f32_16x16x32_bf16 v[56:59], v[168:171], v[192:195], v[56:59]
	v_mfma_f32_16x16x32_bf16 v[52:55], v[160:163], v[200:203], v[52:55]
	v_mfma_f32_16x16x32_bf16 v[44:47], v[168:171], v[200:203], v[44:47]
	v_mfma_f32_16x16x32_bf16 v[36:39], v[160:163], v[208:211], v[36:39]
	v_mfma_f32_16x16x32_bf16 v[28:31], v[168:171], v[208:211], v[28:31]
	v_mfma_f32_16x16x32_bf16 v[20:23], v[160:163], v[216:219], v[20:23]
	v_mfma_f32_16x16x32_bf16 v[12:15], v[168:171], v[216:219], v[12:15]
	v_mfma_f32_16x16x32_bf16 v[48:51], v[172:175], v[188:191], v[48:51]
	v_mfma_f32_16x16x32_bf16 v[40:43], v[180:183], v[188:191], v[40:43]
	v_mfma_f32_16x16x32_bf16 v[32:35], v[172:175], v[196:199], v[32:35]
	v_mfma_f32_16x16x32_bf16 v[24:27], v[180:183], v[196:199], v[24:27]
	v_mfma_f32_16x16x32_bf16 v[16:19], v[172:175], v[204:207], v[16:19]
	v_mfma_f32_16x16x32_bf16 v[8:11], v[180:183], v[204:207], v[8:11]
	v_mfma_f32_16x16x32_bf16 v[4:7], v[172:175], v[212:215], v[4:7]
	v_mfma_f32_16x16x32_bf16 v[0:3], v[180:183], v[212:215], v[0:3]
	v_mfma_f32_16x16x32_bf16 v[48:51], v[176:179], v[192:195], v[48:51]
	v_mfma_f32_16x16x32_bf16 v[40:43], v[184:187], v[192:195], v[40:43]
	v_mfma_f32_16x16x32_bf16 v[32:35], v[176:179], v[200:203], v[32:35]
	v_mfma_f32_16x16x32_bf16 v[24:27], v[184:187], v[200:203], v[24:27]
	v_mfma_f32_16x16x32_bf16 v[16:19], v[176:179], v[208:211], v[16:19]
	v_mfma_f32_16x16x32_bf16 v[8:11], v[184:187], v[208:211], v[8:11]
	v_mfma_f32_16x16x32_bf16 v[4:7], v[176:179], v[216:219], v[4:7]
	v_mfma_f32_16x16x32_bf16 v[0:3], v[184:187], v[216:219], v[0:3]
	s_barrier
	s_add_i32 s60, s60, 2
	s_add_u32 s24, s24, 0x100
	s_addc_u32 s25, s25, 0
	s_add_u32 s58, s58, 0x100
	s_addc_u32 s59, s59, 0
	s_cmpk_gt_u32 s60, 0x53
	s_cbranch_scc0 .LBB0_1060
	s_setprio 0
	s_and_b64 vcc, exec, s[12:13]
	s_cbranch_vccz .LBB0_1063
	s_barrier
